# GEMM k-loops: s_setprio 1 for the MFMA compute segment, 0 for the LDS write segment
# speedup vs baseline: 1.0163x; 1.0103x over previous
.LBB0_1228:
	ds_read_b128 v[148:151], v130
	ds_read_b128 v[152:155], v130 offset:4608
	ds_read_b128 v[156:159], v131 offset:18432
	ds_read_b128 v[160:163], v131 offset:23040
	ds_read_b128 v[164:167], v131 offset:27648
	ds_read_b128 v[168:171], v131 offset:32256
	ds_read_b128 v[172:175], v130 offset:32
	ds_read_b128 v[176:179], v130 offset:4640
	ds_read_b128 v[180:183], v131 offset:18464
	ds_read_b128 v[184:187], v131 offset:23072
	ds_read_b128 v[188:191], v131 offset:27680
	ds_read_b128 v[192:195], v131 offset:32288
	s_waitcnt lgkmcnt(9)
	v_mfma_f32_32x32x16_bf16 v[112:127], v[148:151], v[156:159], v[112:127]
	s_waitcnt lgkmcnt(8)
	v_mfma_f32_32x32x16_bf16 v[96:111], v[148:151], v[160:163], v[96:111]
	s_waitcnt lgkmcnt(7)
	v_mfma_f32_32x32x16_bf16 v[80:95], v[148:151], v[164:167], v[80:95]
	s_waitcnt lgkmcnt(6)
	v_mfma_f32_32x32x16_bf16 v[64:79], v[148:151], v[168:171], v[64:79]
	v_lshl_add_u64 v[208:209], v[134:135], 0, s[0:1]
	s_mov_b32 s4, 0xa768000
	v_add_co_u32_e32 v148, vcc, s4, v208
	v_lshl_add_u64 v[212:213], v[136:137], 0, s[0:1]
	s_nop 0
	v_addc_co_u32_e32 v149, vcc, 0, v209, vcc
	s_mov_b32 s4, 0x6000000
	v_add_co_u32_e32 v196, vcc, s4, v212
	s_nop 1
	v_addc_co_u32_e32 v197, vcc, 0, v213, vcc
	global_load_dwordx4 v[148:151], v[148:149], off offset:384
	s_nop 0
	global_load_dwordx4 v[196:199], v[196:197], off offset:128
	v_mfma_f32_32x32x16_bf16 v[48:63], v[152:155], v[156:159], v[48:63]
	v_mfma_f32_32x32x16_bf16 v[32:47], v[152:155], v[160:163], v[32:47]
	v_mfma_f32_32x32x16_bf16 v[16:31], v[152:155], v[164:167], v[16:31]
	v_mfma_f32_32x32x16_bf16 v[0:15], v[152:155], v[168:171], v[0:15]
	s_mov_b32 s4, 0x6084000
	v_add_co_u32_e32 v152, vcc, s4, v212
	s_nop 1
	v_addc_co_u32_e32 v153, vcc, 0, v213, vcc
	global_load_dwordx4 v[152:155], v[152:153], off offset:128
	ds_read_b128 v[156:159], v130 offset:64
	ds_read_b128 v[160:163], v130 offset:4672
	ds_read_b128 v[164:167], v131 offset:18496
	ds_read_b128 v[168:171], v131 offset:23104
	ds_read_b128 v[200:203], v131 offset:27712
	ds_read_b128 v[204:207], v131 offset:32320
	s_waitcnt lgkmcnt(9)
	v_mfma_f32_32x32x16_bf16 v[112:127], v[172:175], v[180:183], v[112:127]
	s_waitcnt lgkmcnt(8)
	v_mfma_f32_32x32x16_bf16 v[96:111], v[172:175], v[184:187], v[96:111]
	s_waitcnt lgkmcnt(7)
	v_mfma_f32_32x32x16_bf16 v[80:95], v[172:175], v[188:191], v[80:95]
	s_waitcnt lgkmcnt(6)
	v_mfma_f32_32x32x16_bf16 v[64:79], v[172:175], v[192:195], v[64:79]
	s_mov_b32 s4, 0xa789000
	v_add_co_u32_e32 v172, vcc, s4, v208
	s_mov_b32 s4, 0x6021000
	s_nop 0
	v_addc_co_u32_e32 v173, vcc, 0, v209, vcc
	v_add_co_u32_e32 v216, vcc, s4, v212
	s_nop 1
	v_addc_co_u32_e32 v217, vcc, 0, v213, vcc
	global_load_dwordx4 v[172:175], v[172:173], off offset:384
	s_nop 0
	global_load_dwordx4 v[216:219], v[216:217], off offset:128
	v_mfma_f32_32x32x16_bf16 v[48:63], v[176:179], v[180:183], v[48:63]
	v_mfma_f32_32x32x16_bf16 v[32:47], v[176:179], v[184:187], v[32:47]
	v_mfma_f32_32x32x16_bf16 v[16:31], v[176:179], v[188:191], v[16:31]
	v_mfma_f32_32x32x16_bf16 v[0:15], v[176:179], v[192:195], v[0:15]
	s_mov_b32 s4, 0x60a5000
	v_add_co_u32_e32 v176, vcc, s4, v212
	s_nop 1
	v_addc_co_u32_e32 v177, vcc, 0, v213, vcc
	global_load_dwordx4 v[176:179], v[176:177], off offset:128
	ds_read_b128 v[180:183], v130 offset:96
	ds_read_b128 v[184:187], v130 offset:4704
	ds_read_b128 v[188:191], v131 offset:18528
	ds_read_b128 v[192:195], v131 offset:23136
	ds_read_b128 v[220:223], v131 offset:27744
	ds_read_b128 v[224:227], v131 offset:32352
	s_waitcnt lgkmcnt(9)
	v_mfma_f32_32x32x16_bf16 v[112:127], v[156:159], v[164:167], v[112:127]
	s_waitcnt lgkmcnt(8)
	v_mfma_f32_32x32x16_bf16 v[96:111], v[156:159], v[168:171], v[96:111]
	s_waitcnt lgkmcnt(7)
	v_mfma_f32_32x32x16_bf16 v[80:95], v[156:159], v[200:203], v[80:95]
	s_waitcnt lgkmcnt(6)
	v_mfma_f32_32x32x16_bf16 v[64:79], v[156:159], v[204:207], v[64:79]
	v_add_co_u32_e32 v156, vcc, s77, v208
	s_nop 1
	v_addc_co_u32_e32 v157, vcc, 0, v209, vcc
	v_add_co_u32_e32 v228, vcc, s78, v212
	s_nop 1
	v_addc_co_u32_e32 v229, vcc, 0, v213, vcc
	global_load_dwordx4 v[156:159], v[156:157], off offset:384
	s_nop 0
	global_load_dwordx4 v[228:231], v[228:229], off offset:128
	v_mfma_f32_32x32x16_bf16 v[48:63], v[160:163], v[164:167], v[48:63]
	v_mfma_f32_32x32x16_bf16 v[32:47], v[160:163], v[168:171], v[32:47]
	v_mfma_f32_32x32x16_bf16 v[16:31], v[160:163], v[200:203], v[16:31]
	v_mfma_f32_32x32x16_bf16 v[0:15], v[160:163], v[204:207], v[0:15]
	v_add_co_u32_e32 v160, vcc, s79, v212
	s_nop 1
	v_addc_co_u32_e32 v161, vcc, 0, v213, vcc
	global_load_dwordx4 v[160:163], v[160:161], off offset:128
	s_waitcnt lgkmcnt(3)
	v_mfma_f32_32x32x16_bf16 v[112:127], v[180:183], v[188:191], v[112:127]
	s_waitcnt lgkmcnt(2)
	v_mfma_f32_32x32x16_bf16 v[96:111], v[180:183], v[192:195], v[96:111]
	s_waitcnt lgkmcnt(1)
	v_mfma_f32_32x32x16_bf16 v[80:95], v[180:183], v[220:223], v[80:95]
	s_waitcnt lgkmcnt(0)
	v_mfma_f32_32x32x16_bf16 v[64:79], v[180:183], v[224:227], v[64:79]
	v_add_co_u32_e32 v164, vcc, s80, v208
	s_nop 1
	v_addc_co_u32_e32 v165, vcc, 0, v209, vcc
	v_add_co_u32_e32 v168, vcc, s81, v212
	s_nop 1
	v_addc_co_u32_e32 v169, vcc, 0, v213, vcc
	global_load_dwordx4 v[164:167], v[164:165], off offset:384
	s_nop 0
	global_load_dwordx4 v[168:171], v[168:169], off offset:128
	v_mfma_f32_32x32x16_bf16 v[48:63], v[184:187], v[188:191], v[48:63]
	v_mfma_f32_32x32x16_bf16 v[32:47], v[184:187], v[192:195], v[32:47]
	v_mfma_f32_32x32x16_bf16 v[16:31], v[184:187], v[220:223], v[16:31]
	v_mfma_f32_32x32x16_bf16 v[0:15], v[184:187], v[224:227], v[0:15]
	v_add_co_u32_e32 v180, vcc, s82, v212
	s_nop 1
	v_addc_co_u32_e32 v181, vcc, 0, v213, vcc
	global_load_dwordx4 v[180:183], v[180:181], off offset:128
	s_add_u32 s0, s0, 0x80
	s_addc_u32 s1, s1, 0
	s_cmpk_eq_i32 s0, 0xf80
	s_barrier
; DI int TID() { int t = threadIdx.x; asm volatile("" : "+v"(t)); return t; }
; template <int EPI>
; __device__ __forceinline__ void gemm_tile(const Params& p, int layer, const u16* __restrict__ A, const u16* __restrict__ Bt, int mt, int nt, char* lds) {
;   u16* As = (u16*)lds;
;   u16* Bs = As + 128 * GLD;
;   const int tid = TID(), wid = tid >> 6, lane = tid & 63, r = lane & 31, h = lane >> 5;
;   const int wr = wid >> 1, wc = wid & 1;
;   const int m0 = mt * 128, n0 = nt * 256;
;   const int lrow = tid >> 3, lch = (tid & 7) * 8;
;   const u16* ag = A + (size_t)(m0 + lrow) * LDX + lch;
;   const u16* bg = Bt + (size_t)(n0 + lrow) * LDX + lch;
;   const u16* a_r = As + (wr * 64 + r) * GLD + 8 * h;
;   const u16* b_r = Bs + (wc * 128 + r) * GLD + 8 * h;
;   f32x16 acc[2][4];
; #pragma unroll
;   for (int i = 0; i < 2; ++i)
; #pragma unroll
;     for (int j = 0; j < 4; ++j)
; #pragma unroll
;       for (int e = 0; e < 16; ++e) acc[i][j][e] = 0.f;
;   u32x4 sa[4], sb[8];
; #pragma unroll
;   for (int pp = 0; pp < 4; ++pp) sa[pp] = *(const u32x4*)(ag + (size_t)pp * 32 * LDX);
; #pragma unroll
;   for (int pp = 0; pp < 8; ++pp) sb[pp] = *(const u32x4*)(bg + (size_t)pp * 32 * LDX);
;   G_WRITE();
;   __syncthreads();
;   constexpr int NK = 2048 / 64;
;   for (int kt = 0; kt < NK - 1; ++kt) {
;     G_SLAB(true, kt + 1)
;     __syncthreads();
;     G_WRITE();
;     __syncthreads();
;   }
;   G_SLAB(false, 0)
	s_setprio 0
	s_waitcnt vmcnt(11)
	ds_write_b128 v132, v[148:151]
	s_waitcnt vmcnt(8)
	ds_write_b128 v132, v[172:175] offset:4608
	s_waitcnt vmcnt(5)
	ds_write_b128 v132, v[156:159] offset:9216
	s_waitcnt vmcnt(2)
	ds_write_b128 v132, v[164:167] offset:13824
	ds_write_b128 v132, v[196:199] offset:18432
	ds_write_b128 v132, v[216:219] offset:23040
	ds_write_b128 v132, v[228:231] offset:27648
	s_waitcnt vmcnt(1)
	ds_write_b128 v132, v[168:171] offset:32256
	ds_write_b128 v132, v[152:155] offset:36864
	ds_write_b128 v132, v[176:179] offset:41472
	ds_write_b128 v132, v[160:163] offset:46080
	s_waitcnt vmcnt(0)
	ds_write_b128 v132, v[180:183] offset:50688
	s_waitcnt lgkmcnt(0)
	s_setprio 1
	s_barrier
	s_cbranch_scc0 .LBB0_1228
	ds_read_b128 v[132:135], v130
	ds_read_b128 v[148:151], v130 offset:4608
	ds_read_b128 v[152:155], v131 offset:18432
	ds_read_b128 v[156:159], v131 offset:23040
	ds_read_b128 v[160:163], v131 offset:27648
	ds_read_b128 v[164:167], v131 offset:32256
	ds_read_b128 v[168:171], v130 offset:32
	ds_read_b128 v[172:175], v130 offset:4640
	ds_read_b128 v[176:179], v131 offset:18464
	ds_read_b128 v[180:183], v131 offset:23072
	ds_read_b128 v[184:187], v131 offset:27680
	ds_read_b128 v[188:191], v131 offset:32288
	s_waitcnt lgkmcnt(9)
	v_mfma_f32_32x32x16_bf16 v[112:127], v[132:135], v[152:155], v[112:127]
	s_waitcnt lgkmcnt(8)
	v_mfma_f32_32x32x16_bf16 v[96:111], v[132:135], v[156:159], v[96:111]
	s_waitcnt lgkmcnt(7)
	v_mfma_f32_32x32x16_bf16 v[80:95], v[132:135], v[160:163], v[80:95]
	s_waitcnt lgkmcnt(6)
	v_mfma_f32_32x32x16_bf16 v[64:79], v[132:135], v[164:167], v[64:79]
	v_mfma_f32_32x32x16_bf16 v[48:63], v[148:151], v[152:155], v[48:63]
	v_mfma_f32_32x32x16_bf16 v[32:47], v[148:151], v[156:159], v[32:47]
	v_mfma_f32_32x32x16_bf16 v[16:31], v[148:151], v[160:163], v[16:31]
	v_mfma_f32_32x32x16_bf16 v[0:15], v[148:151], v[164:167], v[0:15]
	ds_read_b128 v[132:135], v130 offset:64
	ds_read_b128 v[148:151], v130 offset:4672
	ds_read_b128 v[152:155], v131 offset:18496
	ds_read_b128 v[156:159], v131 offset:23104
	ds_read_b128 v[160:163], v131 offset:27712
	ds_read_b128 v[164:167], v131 offset:32320
	s_waitcnt lgkmcnt(9)
	v_mfma_f32_32x32x16_bf16 v[112:127], v[168:171], v[176:179], v[112:127]
	s_waitcnt lgkmcnt(8)
	v_mfma_f32_32x32x16_bf16 v[96:111], v[168:171], v[180:183], v[96:111]
	s_waitcnt lgkmcnt(7)
	v_mfma_f32_32x32x16_bf16 v[80:95], v[168:171], v[184:187], v[80:95]
	s_waitcnt lgkmcnt(6)
	v_mfma_f32_32x32x16_bf16 v[64:79], v[168:171], v[188:191], v[64:79]
	v_mfma_f32_32x32x16_bf16 v[48:63], v[172:175], v[176:179], v[48:63]
	v_mfma_f32_32x32x16_bf16 v[32:47], v[172:175], v[180:183], v[32:47]
	v_mfma_f32_32x32x16_bf16 v[16:31], v[172:175], v[184:187], v[16:31]
	v_mfma_f32_32x32x16_bf16 v[0:15], v[172:175], v[188:191], v[0:15]
	ds_read_b128 v[168:171], v130 offset:96
	ds_read_b128 v[172:175], v130 offset:4704
	ds_read_b128 v[176:179], v131 offset:18528
	ds_read_b128 v[180:183], v131 offset:23136
	ds_read_b128 v[184:187], v131 offset:27744
	ds_read_b128 v[188:191], v131 offset:32352
	s_waitcnt lgkmcnt(9)
	v_mfma_f32_32x32x16_bf16 v[112:127], v[132:135], v[152:155], v[112:127]
	s_waitcnt lgkmcnt(8)
	v_mfma_f32_32x32x16_bf16 v[96:111], v[132:135], v[156:159], v[96:111]
	s_waitcnt lgkmcnt(7)
	v_mfma_f32_32x32x16_bf16 v[80:95], v[132:135], v[160:163], v[80:95]
	s_waitcnt lgkmcnt(6)
	v_mfma_f32_32x32x16_bf16 v[64:79], v[132:135], v[164:167], v[64:79]
	v_mfma_f32_32x32x16_bf16 v[48:63], v[148:151], v[152:155], v[48:63]
	v_mfma_f32_32x32x16_bf16 v[32:47], v[148:151], v[156:159], v[32:47]
	v_mfma_f32_32x32x16_bf16 v[16:31], v[148:151], v[160:163], v[16:31]
	v_mfma_f32_32x32x16_bf16 v[0:15], v[148:151], v[164:167], v[0:15]
	s_waitcnt lgkmcnt(3)
	v_mfma_f32_32x32x16_bf16 v[112:127], v[168:171], v[176:179], v[112:127]
	s_waitcnt lgkmcnt(2)
	v_mfma_f32_32x32x16_bf16 v[96:111], v[168:171], v[180:183], v[96:111]
	s_waitcnt lgkmcnt(1)
	v_mfma_f32_32x32x16_bf16 v[80:95], v[168:171], v[184:187], v[80:95]
	s_waitcnt lgkmcnt(0)
	v_mfma_f32_32x32x16_bf16 v[64:79], v[168:171], v[188:191], v[64:79]
	v_mfma_f32_32x32x16_bf16 v[48:63], v[172:175], v[176:179], v[48:63]
	v_mfma_f32_32x32x16_bf16 v[32:47], v[172:175], v[180:183], v[32:47]
	v_mfma_f32_32x32x16_bf16 v[16:31], v[172:175], v[184:187], v[16:31]
	v_mfma_f32_32x32x16_bf16 v[0:15], v[172:175], v[188:191], v[0:15]
	s_and_b32 s35, s34, 0xffff
	s_cmp_lg_u32 s35, 10
	v_or_b32_e32 v137, s47, v145
	s_cselect_b64 s[18:19], -1, 0
	s_and_b32 s88, s34, 0xfffffe
	v_cmp_eq_u32_e64 s[0:1], 0, v144
	v_mov_b32_e32 v128, 0
	v_cmp_gt_i32_e64 s[10:11], s83, v137
	v_cmp_lt_i32_e64 s[14:15], s90, v137
	s_mov_b64 s[4:5], -1
	s_and_b64 vcc, exec, s[18:19]
	s_barrier
	s_cbranch_vccz .LBB0_1234
	s_cmp_lt_i32 s88, 14
	s_cbranch_scc1 .LBB0_1232
	s_cmp_eq_u32 s88, 14
	s_cselect_b64 s[4:5], -1, 0
	s_cbranch_execz .LBB0_1233
	s_branch .LBB0_1234

.LBB0_1630:
	ds_read_b128 v[144:147], v132
	ds_read_b128 v[148:151], v132 offset:4608
	ds_read_b128 v[152:155], v133 offset:18432
	ds_read_b128 v[156:159], v133 offset:23040
	ds_read_b128 v[160:163], v133 offset:27648
	ds_read_b128 v[164:167], v133 offset:32256
	ds_read_b128 v[168:171], v132 offset:32
	ds_read_b128 v[172:175], v132 offset:4640
	ds_read_b128 v[176:179], v133 offset:18464
	ds_read_b128 v[180:183], v133 offset:23072
	ds_read_b128 v[184:187], v133 offset:27680
	ds_read_b128 v[188:191], v133 offset:32288
	s_waitcnt lgkmcnt(9)
	v_mfma_f32_32x32x16_bf16 v[112:127], v[144:147], v[152:155], v[112:127]
	s_waitcnt lgkmcnt(8)
	v_mfma_f32_32x32x16_bf16 v[96:111], v[144:147], v[156:159], v[96:111]
	s_waitcnt lgkmcnt(7)
	v_mfma_f32_32x32x16_bf16 v[80:95], v[144:147], v[160:163], v[80:95]
	s_waitcnt lgkmcnt(6)
	v_mfma_f32_32x32x16_bf16 v[64:79], v[144:147], v[164:167], v[64:79]
	v_lshl_add_u64 v[208:209], v[136:137], 0, s[0:1]
	s_mov_b32 s7, 0x17eb8000
	v_add_co_u32_e32 v144, vcc, s7, v208
	v_lshl_add_u64 v[212:213], v[138:139], 0, s[0:1]
	s_nop 0
	v_addc_co_u32_e32 v145, vcc, 0, v209, vcc
	s_mov_b32 s7, 0x8520000
	v_add_co_u32_e32 v192, vcc, s7, v212
	s_nop 1
	v_addc_co_u32_e32 v193, vcc, 0, v213, vcc
	global_load_dwordx4 v[144:147], v[144:145], off offset:384
	s_nop 0
	global_load_dwordx4 v[192:195], v[192:193], off offset:128
	v_mfma_f32_32x32x16_bf16 v[48:63], v[148:151], v[152:155], v[48:63]
	v_mfma_f32_32x32x16_bf16 v[32:47], v[148:151], v[156:159], v[32:47]
	v_mfma_f32_32x32x16_bf16 v[16:31], v[148:151], v[160:163], v[16:31]
	v_mfma_f32_32x32x16_bf16 v[0:15], v[148:151], v[164:167], v[0:15]
	s_mov_b32 s7, 0x85a4000
	v_add_co_u32_e32 v148, vcc, s7, v212
	s_nop 1
	v_addc_co_u32_e32 v149, vcc, 0, v213, vcc
	global_load_dwordx4 v[148:151], v[148:149], off offset:128
	ds_read_b128 v[152:155], v132 offset:64
	ds_read_b128 v[156:159], v132 offset:4672
	ds_read_b128 v[160:163], v133 offset:18496
	ds_read_b128 v[164:167], v133 offset:23104
	ds_read_b128 v[196:199], v133 offset:27712
	ds_read_b128 v[200:203], v133 offset:32320
	s_waitcnt lgkmcnt(9)
	v_mfma_f32_32x32x16_bf16 v[112:127], v[168:171], v[176:179], v[112:127]
	s_waitcnt lgkmcnt(8)
	v_mfma_f32_32x32x16_bf16 v[96:111], v[168:171], v[180:183], v[96:111]
	s_waitcnt lgkmcnt(7)
	v_mfma_f32_32x32x16_bf16 v[80:95], v[168:171], v[184:187], v[80:95]
	s_waitcnt lgkmcnt(6)
	v_mfma_f32_32x32x16_bf16 v[64:79], v[168:171], v[188:191], v[64:79]
	s_mov_b32 s7, 0x17ed9000
	v_add_co_u32_e32 v168, vcc, s7, v208
	s_mov_b32 s7, 0x8541000
	s_nop 0
	v_addc_co_u32_e32 v169, vcc, 0, v209, vcc
	v_add_co_u32_e32 v204, vcc, s7, v212
	s_nop 1
	v_addc_co_u32_e32 v205, vcc, 0, v213, vcc
	global_load_dwordx4 v[168:171], v[168:169], off offset:384
	s_nop 0
	global_load_dwordx4 v[204:207], v[204:205], off offset:128
	v_mfma_f32_32x32x16_bf16 v[48:63], v[172:175], v[176:179], v[48:63]
	v_mfma_f32_32x32x16_bf16 v[32:47], v[172:175], v[180:183], v[32:47]
	v_mfma_f32_32x32x16_bf16 v[16:31], v[172:175], v[184:187], v[16:31]
	v_mfma_f32_32x32x16_bf16 v[0:15], v[172:175], v[188:191], v[0:15]
	s_mov_b32 s7, 0x85c5000
	v_add_co_u32_e32 v172, vcc, s7, v212
	s_nop 1
	v_addc_co_u32_e32 v173, vcc, 0, v213, vcc
	global_load_dwordx4 v[172:175], v[172:173], off offset:128
	ds_read_b128 v[176:179], v132 offset:96
	ds_read_b128 v[180:183], v132 offset:4704
	ds_read_b128 v[184:187], v133 offset:18528
	ds_read_b128 v[188:191], v133 offset:23136
	ds_read_b128 v[216:219], v133 offset:27744
	ds_read_b128 v[220:223], v133 offset:32352
	s_waitcnt lgkmcnt(9)
	v_mfma_f32_32x32x16_bf16 v[112:127], v[152:155], v[160:163], v[112:127]
	s_waitcnt lgkmcnt(8)
	v_mfma_f32_32x32x16_bf16 v[96:111], v[152:155], v[164:167], v[96:111]
	s_waitcnt lgkmcnt(7)
	v_mfma_f32_32x32x16_bf16 v[80:95], v[152:155], v[196:199], v[80:95]
	s_waitcnt lgkmcnt(6)
	v_mfma_f32_32x32x16_bf16 v[64:79], v[152:155], v[200:203], v[64:79]
	s_mov_b32 s7, 0x17efa000
	v_add_co_u32_e32 v152, vcc, s7, v208
	s_nop 1
	v_addc_co_u32_e32 v153, vcc, 0, v209, vcc
	v_add_co_u32_e32 v224, vcc, s77, v212
	s_nop 1
	v_addc_co_u32_e32 v225, vcc, 0, v213, vcc
	global_load_dwordx4 v[152:155], v[152:153], off offset:384
	s_nop 0
	global_load_dwordx4 v[224:227], v[224:225], off offset:128
	v_mfma_f32_32x32x16_bf16 v[48:63], v[156:159], v[160:163], v[48:63]
	v_mfma_f32_32x32x16_bf16 v[32:47], v[156:159], v[164:167], v[32:47]
	v_mfma_f32_32x32x16_bf16 v[16:31], v[156:159], v[196:199], v[16:31]
	v_mfma_f32_32x32x16_bf16 v[0:15], v[156:159], v[200:203], v[0:15]
	v_add_co_u32_e32 v156, vcc, s78, v212
	s_nop 1
	v_addc_co_u32_e32 v157, vcc, 0, v213, vcc
	global_load_dwordx4 v[156:159], v[156:157], off offset:128
	s_waitcnt lgkmcnt(3)
	v_mfma_f32_32x32x16_bf16 v[112:127], v[176:179], v[184:187], v[112:127]
	s_waitcnt lgkmcnt(2)
	v_mfma_f32_32x32x16_bf16 v[96:111], v[176:179], v[188:191], v[96:111]
	s_waitcnt lgkmcnt(1)
	v_mfma_f32_32x32x16_bf16 v[80:95], v[176:179], v[216:219], v[80:95]
	s_waitcnt lgkmcnt(0)
	v_mfma_f32_32x32x16_bf16 v[64:79], v[176:179], v[220:223], v[64:79]
	v_add_co_u32_e32 v160, vcc, s79, v208
	s_nop 1
	v_addc_co_u32_e32 v161, vcc, 0, v209, vcc
	v_add_co_u32_e32 v164, vcc, s80, v212
	s_nop 1
	v_addc_co_u32_e32 v165, vcc, 0, v213, vcc
	global_load_dwordx4 v[160:163], v[160:161], off offset:384
	s_nop 0
	global_load_dwordx4 v[164:167], v[164:165], off offset:128
	v_mfma_f32_32x32x16_bf16 v[48:63], v[180:183], v[184:187], v[48:63]
	v_mfma_f32_32x32x16_bf16 v[32:47], v[180:183], v[188:191], v[32:47]
	v_mfma_f32_32x32x16_bf16 v[16:31], v[180:183], v[216:219], v[16:31]
	v_mfma_f32_32x32x16_bf16 v[0:15], v[180:183], v[220:223], v[0:15]
	v_add_co_u32_e32 v176, vcc, s81, v212
	s_nop 1
	v_addc_co_u32_e32 v177, vcc, 0, v213, vcc
	global_load_dwordx4 v[176:179], v[176:177], off offset:128
	s_add_u32 s0, s0, 0x80
	s_addc_u32 s1, s1, 0
	s_cmpk_eq_i32 s0, 0xf80
	s_barrier
; DI int TID() { int t = threadIdx.x; asm volatile("" : "+v"(t)); return t; }
; template <int EPI>
; __device__ __forceinline__ void gemm_tile(const Params& p, int layer, const u16* __restrict__ A, const u16* __restrict__ Bt, int mt, int nt, char* lds) {
;   u16* As = (u16*)lds;
;   u16* Bs = As + 128 * GLD;
;   const int tid = TID(), wid = tid >> 6, lane = tid & 63, r = lane & 31, h = lane >> 5;
;   const int wr = wid >> 1, wc = wid & 1;
;   const int m0 = mt * 128, n0 = nt * 256;
;   const int lrow = tid >> 3, lch = (tid & 7) * 8;
;   const u16* ag = A + (size_t)(m0 + lrow) * LDX + lch;
;   const u16* bg = Bt + (size_t)(n0 + lrow) * LDX + lch;
;   const u16* a_r = As + (wr * 64 + r) * GLD + 8 * h;
;   const u16* b_r = Bs + (wc * 128 + r) * GLD + 8 * h;
;   f32x16 acc[2][4];
; #pragma unroll
;   for (int i = 0; i < 2; ++i)
; #pragma unroll
;     for (int j = 0; j < 4; ++j)
; #pragma unroll
;       for (int e = 0; e < 16; ++e) acc[i][j][e] = 0.f;
;   u32x4 sa[4], sb[8];
; #pragma unroll
;   for (int pp = 0; pp < 4; ++pp) sa[pp] = *(const u32x4*)(ag + (size_t)pp * 32 * LDX);
; #pragma unroll
;   for (int pp = 0; pp < 8; ++pp) sb[pp] = *(const u32x4*)(bg + (size_t)pp * 32 * LDX);
;   G_WRITE();
;   __syncthreads();
;   constexpr int NK = 2048 / 64;
;   for (int kt = 0; kt < NK - 1; ++kt) {
;     G_SLAB(true, kt + 1)
;     __syncthreads();
;     G_WRITE();
;     __syncthreads();
;   }
;   G_SLAB(false, 0)
	s_setprio 0
	s_waitcnt vmcnt(11)
	ds_write_b128 v134, v[144:147]
	s_waitcnt vmcnt(8)
	ds_write_b128 v134, v[168:171] offset:4608
	s_waitcnt vmcnt(5)
	ds_write_b128 v134, v[152:155] offset:9216
	s_waitcnt vmcnt(2)
	ds_write_b128 v134, v[160:163] offset:13824
	ds_write_b128 v134, v[192:195] offset:18432
	ds_write_b128 v134, v[204:207] offset:23040
	ds_write_b128 v134, v[224:227] offset:27648
	s_waitcnt vmcnt(1)
	ds_write_b128 v134, v[164:167] offset:32256
	ds_write_b128 v134, v[148:151] offset:36864
	ds_write_b128 v134, v[172:175] offset:41472
	ds_write_b128 v134, v[156:159] offset:46080
	s_waitcnt vmcnt(0)
	ds_write_b128 v134, v[176:179] offset:50688
	s_waitcnt lgkmcnt(0)
	s_setprio 1
	s_barrier
	s_cbranch_scc0 .LBB0_1630
	ds_read_b128 v[134:137], v132
	ds_read_b128 v[144:147], v132 offset:4608
	ds_read_b128 v[148:151], v133 offset:18432
	ds_read_b128 v[152:155], v133 offset:23040
	ds_read_b128 v[156:159], v133 offset:27648
	ds_read_b128 v[160:163], v133 offset:32256
	ds_read_b128 v[164:167], v132 offset:32
	ds_read_b128 v[168:171], v132 offset:4640
	ds_read_b128 v[172:175], v133 offset:18464
	ds_read_b128 v[176:179], v133 offset:23072
	ds_read_b128 v[180:183], v133 offset:27680
	ds_read_b128 v[184:187], v133 offset:32288
	s_waitcnt lgkmcnt(9)
	v_mfma_f32_32x32x16_bf16 v[112:127], v[134:137], v[148:151], v[112:127]
	s_waitcnt lgkmcnt(8)
	v_mfma_f32_32x32x16_bf16 v[96:111], v[134:137], v[152:155], v[96:111]
	s_waitcnt lgkmcnt(7)
	v_mfma_f32_32x32x16_bf16 v[80:95], v[134:137], v[156:159], v[80:95]
	s_waitcnt lgkmcnt(6)
	v_mfma_f32_32x32x16_bf16 v[64:79], v[134:137], v[160:163], v[64:79]
	v_mfma_f32_32x32x16_bf16 v[48:63], v[144:147], v[148:151], v[48:63]
	v_mfma_f32_32x32x16_bf16 v[32:47], v[144:147], v[152:155], v[32:47]
	v_mfma_f32_32x32x16_bf16 v[16:31], v[144:147], v[156:159], v[16:31]
	v_mfma_f32_32x32x16_bf16 v[0:15], v[144:147], v[160:163], v[0:15]
	ds_read_b128 v[134:137], v132 offset:64
	ds_read_b128 v[144:147], v132 offset:4672
	ds_read_b128 v[148:151], v133 offset:18496
	ds_read_b128 v[152:155], v133 offset:23104
	ds_read_b128 v[156:159], v133 offset:27712
	ds_read_b128 v[160:163], v133 offset:32320
	s_waitcnt lgkmcnt(9)
	v_mfma_f32_32x32x16_bf16 v[112:127], v[164:167], v[172:175], v[112:127]
	s_waitcnt lgkmcnt(8)
	v_mfma_f32_32x32x16_bf16 v[96:111], v[164:167], v[176:179], v[96:111]
	s_waitcnt lgkmcnt(7)
	v_mfma_f32_32x32x16_bf16 v[80:95], v[164:167], v[180:183], v[80:95]
	s_waitcnt lgkmcnt(6)
	v_mfma_f32_32x32x16_bf16 v[64:79], v[164:167], v[184:187], v[64:79]
	v_mfma_f32_32x32x16_bf16 v[48:63], v[168:171], v[172:175], v[48:63]
	v_mfma_f32_32x32x16_bf16 v[32:47], v[168:171], v[176:179], v[32:47]
	v_mfma_f32_32x32x16_bf16 v[16:31], v[168:171], v[180:183], v[16:31]
	v_mfma_f32_32x32x16_bf16 v[0:15], v[168:171], v[184:187], v[0:15]
	ds_read_b128 v[164:167], v132 offset:96
	ds_read_b128 v[168:171], v132 offset:4704
	ds_read_b128 v[172:175], v133 offset:18528
	ds_read_b128 v[176:179], v133 offset:23136
	ds_read_b128 v[180:183], v133 offset:27744
	ds_read_b128 v[184:187], v133 offset:32352
	s_waitcnt lgkmcnt(9)
	v_mfma_f32_32x32x16_bf16 v[112:127], v[134:137], v[148:151], v[112:127]
	s_waitcnt lgkmcnt(8)
	v_mfma_f32_32x32x16_bf16 v[96:111], v[134:137], v[152:155], v[96:111]
	s_waitcnt lgkmcnt(7)
	v_mfma_f32_32x32x16_bf16 v[80:95], v[134:137], v[156:159], v[80:95]
	s_waitcnt lgkmcnt(6)
	v_mfma_f32_32x32x16_bf16 v[64:79], v[134:137], v[160:163], v[64:79]
	v_mfma_f32_32x32x16_bf16 v[48:63], v[144:147], v[148:151], v[48:63]
	v_mfma_f32_32x32x16_bf16 v[32:47], v[144:147], v[152:155], v[32:47]
	v_mfma_f32_32x32x16_bf16 v[16:31], v[144:147], v[156:159], v[16:31]
	v_mfma_f32_32x32x16_bf16 v[0:15], v[144:147], v[160:163], v[0:15]
	s_waitcnt lgkmcnt(3)
	v_mfma_f32_32x32x16_bf16 v[112:127], v[164:167], v[172:175], v[112:127]
	s_waitcnt lgkmcnt(2)
	v_mfma_f32_32x32x16_bf16 v[96:111], v[164:167], v[176:179], v[96:111]
	s_waitcnt lgkmcnt(1)
	v_mfma_f32_32x32x16_bf16 v[80:95], v[164:167], v[180:183], v[80:95]
	s_waitcnt lgkmcnt(0)
	v_mfma_f32_32x32x16_bf16 v[64:79], v[164:167], v[184:187], v[64:79]
	v_mfma_f32_32x32x16_bf16 v[48:63], v[168:171], v[172:175], v[48:63]
	v_mfma_f32_32x32x16_bf16 v[32:47], v[168:171], v[176:179], v[32:47]
	v_mfma_f32_32x32x16_bf16 v[16:31], v[168:171], v[180:183], v[16:31]
	v_mfma_f32_32x32x16_bf16 v[0:15], v[168:171], v[184:187], v[0:15]
	v_or_b32_e32 v132, s6, v140
	s_cmp_lt_i32 s5, 2
	v_mov_b32_e32 v128, 0
	s_barrier
; DI int crow(int i, int h) { return (i & 3) + 8 * (i >> 2) + 4 * h; }
; DI const float* modp(const Params& p, int layer, int v) { return (const float*)(p.ws + OFF_MOD) + (size_t)(layer * 2 + v) * 12288; }
; template <int EPI>
; __device__ __forceinline__ void gemm_tile(const Params& p, int layer, const u16* __restrict__ A, const u16* __restrict__ Bt, int mt, int nt, char* lds) {
;     ...
;       } else if (EPI == 1) {
;         float* PRE = (float*)(p.ws + OFF_P);
;         const int v = m0 < NCTX ? 1 : 0;
;         const float g = modp(p, layer, v)[4096 + gc];
; #pragma unroll
;         for (int e = 0; e < 16; ++e) {
;           const int gr = grb + crow(e, h);
;           float xin;
;           if (layer == 0) xin = (gr < NCTX) ? p.ctx[(size_t)gr * DM + gc] : p.x[(size_t)(gr - NCTX) * DM + gc];
;           else xin = ((const float*)(p.ws + OFF_XRES))[(size_t)gr * LDF + gc];
;           PRE[(size_t)gr * LDF + gc] = ALPHA * xin + (DBG_NOATTN ? 0.f : g * acc[i][j][e]);
;         }
	s_cselect_b32 s0, 0xc000, 0
	s_add_u32 s70, s48, s0
	v_add_u32_e32 v138, v128, v132
	v_ashrrev_i32_e32 v139, 31, v138
	s_addc_u32 s71, s49, 0
	v_lshlrev_b64 v[140:141], 2, v[138:139]
	v_lshl_add_u64 v[134:135], s[70:71], 0, v[140:141]
	v_add_co_u32_e32 v134, vcc, 0xa724000, v134
	v_add_u32_e32 v128, s4, v142
	s_nop 0
	v_addc_co_u32_e32 v135, vcc, 0, v135, vcc
	global_load_dword v136, v[134:135], off
	v_lshl_or_b32 v134, v130, 2, v128
	v_lshl_add_u64 v[150:151], s[68:69], 0, v[140:141]
	v_cmp_gt_i32_e32 vcc, s83, v134
	v_cmp_lt_i32_e64 s[0:1], s88, v134
	v_add_u32_e32 v128, 0xffffff00, v134
	s_and_saveexec_b64 s[4:5], s[0:1]
	s_xor_b64 s[0:1], exec, s[4:5]
	v_lshlrev_b64 v[142:143], 13, v[128:129]
	v_lshl_add_u64 v[142:143], v[150:151], 0, v[142:143]
	v_mov_b32_e32 v135, v129
	s_or_saveexec_b64 s[0:1], s[0:1]
	v_lshl_add_u64 v[154:155], s[72:73], 0, v[140:141]
	s_xor_b64 exec, exec, s[0:1]
	v_ashrrev_i32_e32 v135, 31, v134
	v_lshlrev_b64 v[140:141], 13, v[134:135]
	v_lshl_add_u64 v[142:143], v[154:155], 0, v[140:141]
	s_or_b64 exec, exec, s[0:1]
	global_load_dword v137, v[142:143], off
	v_lshl_add_u64 v[144:145], v[138:139], 2, s[60:61]
	v_mov_b32_e32 v130, v112
	v_mul_lo_u32 v196, v135, s89
	v_mad_u64_u32 v[140:141], s[0:1], v134, s89, v[144:145]
	v_or_b32_e32 v138, 1, v134
	v_add_u32_e32 v141, v196, v141
	v_cmp_gt_i32_e64 s[0:1], s83, v138
	v_cmp_lt_i32_e64 s[4:5], s88, v138
	s_waitcnt vmcnt(0)
	v_pk_mul_f32 v[142:143], v[130:131], v[136:137]
	s_nop 0
	v_add_f32_e32 v112, v142, v143
	global_store_dword v[140:141], v112, off
	v_add_u32_e32 v140, 0xffffff01, v134
	s_and_saveexec_b64 s[6:7], s[4:5]
	s_xor_b64 s[4:5], exec, s[6:7]
	v_mov_b32_e32 v141, v129
	v_lshlrev_b64 v[142:143], 13, v[140:141]
	v_lshl_add_u64 v[142:143], v[150:151], 0, v[142:143]
	v_mov_b32_e32 v139, v129
	s_andn2_saveexec_b64 s[4:5], s[4:5]
	v_ashrrev_i32_e32 v139, 31, v138
	v_lshlrev_b64 v[142:143], 13, v[138:139]
	v_lshl_add_u64 v[142:143], v[154:155], 0, v[142:143]
	s_or_b64 exec, exec, s[4:5]
	global_load_dword v137, v[142:143], off
	v_mov_b32_e32 v130, v113
	v_mul_lo_u32 v141, v139, s89
	v_mad_u64_u32 v[142:143], s[4:5], v138, s89, v[144:145]
	v_or_b32_e32 v112, 2, v134
	v_add_u32_e32 v143, v141, v143
	v_cmp_gt_i32_e64 s[4:5], s83, v112
	v_cmp_lt_i32_e64 s[6:7], s88, v112
	s_waitcnt vmcnt(0)
	v_pk_mul_f32 v[146:147], v[130:131], v[136:137]
	s_nop 0
	v_add_f32_e32 v113, v146, v147
	global_store_dword v[142:143], v113, off
	v_add_u32_e32 v142, 0xffffff02, v134
	s_and_saveexec_b64 s[8:9], s[6:7]
	s_xor_b64 s[6:7], exec, s[8:9]
	v_mov_b32_e32 v143, v129
	v_lshlrev_b64 v[146:147], 13, v[142:143]
	v_lshl_add_u64 v[146:147], v[150:151], 0, v[146:147]
	v_mov_b32_e32 v113, v129
	s_andn2_saveexec_b64 s[6:7], s[6:7]
	v_ashrrev_i32_e32 v113, 31, v112
	v_lshlrev_b64 v[146:147], 13, v[112:113]
	v_lshl_add_u64 v[146:147], v[154:155], 0, v[146:147]
	s_or_b64 exec, exec, s[6:7]
	global_load_dword v137, v[146:147], off
	v_mov_b32_e32 v130, v114
	v_mul_lo_u32 v143, v113, s89
	v_mad_u64_u32 v[148:149], s[6:7], v112, s89, v[144:145]
	v_or_b32_e32 v146, 3, v134
	v_add_u32_e32 v149, v143, v149
	v_cmp_gt_i32_e64 s[6:7], s83, v146
	v_cmp_lt_i32_e64 s[8:9], s88, v146
	s_waitcnt vmcnt(0)
	v_pk_mul_f32 v[152:153], v[130:131], v[136:137]
	s_nop 0
	v_add_f32_e32 v114, v152, v153
	global_store_dword v[148:149], v114, off
	v_add_u32_e32 v148, 0xffffff03, v134
	s_and_saveexec_b64 s[10:11], s[8:9]
	s_xor_b64 s[8:9], exec, s[10:11]
	v_mov_b32_e32 v149, v129
	v_lshlrev_b64 v[152:153], 13, v[148:149]
	v_lshl_add_u64 v[152:153], v[150:151], 0, v[152:153]
	v_mov_b32_e32 v147, v129
	s_andn2_saveexec_b64 s[8:9], s[8:9]
	v_ashrrev_i32_e32 v147, 31, v146
	v_lshlrev_b64 v[152:153], 13, v[146:147]
	v_lshl_add_u64 v[152:153], v[154:155], 0, v[152:153]
	s_or_b64 exec, exec, s[8:9]
	global_load_dword v137, v[152:153], off
	v_mov_b32_e32 v130, v115
	v_mul_lo_u32 v149, v147, s89
	v_mad_u64_u32 v[152:153], s[8:9], v146, s89, v[144:145]
	v_or_b32_e32 v114, 8, v134
	v_add_u32_e32 v153, v149, v153
	v_cmp_gt_i32_e64 s[8:9], s83, v114
	v_cmp_lt_i32_e64 s[10:11], s88, v114
	s_waitcnt vmcnt(0)
	v_pk_mul_f32 v[156:157], v[130:131], v[136:137]
	s_nop 0
	v_add_f32_e32 v115, v156, v157
	global_store_dword v[152:153], v115, off
	v_add_u32_e32 v152, 0xffffff08, v134
	s_and_saveexec_b64 s[12:13], s[10:11]
	s_xor_b64 s[10:11], exec, s[12:13]
	v_mov_b32_e32 v153, v129
	v_lshlrev_b64 v[156:157], 13, v[152:153]
	v_lshl_add_u64 v[156:157], v[150:151], 0, v[156:157]
	v_mov_b32_e32 v115, v129
	s_andn2_saveexec_b64 s[10:11], s[10:11]
	v_ashrrev_i32_e32 v115, 31, v114
	v_lshlrev_b64 v[156:157], 13, v[114:115]
	v_lshl_add_u64 v[156:157], v[154:155], 0, v[156:157]
	s_or_b64 exec, exec, s[10:11]
	global_load_dword v137, v[156:157], off
	v_mov_b32_e32 v130, v116
	v_mul_lo_u32 v153, v115, s89
	v_mad_u64_u32 v[158:159], s[10:11], v114, s89, v[144:145]
	v_or_b32_e32 v156, 9, v134
	v_add_u32_e32 v159, v153, v159
	v_cmp_gt_i32_e64 s[10:11], s83, v156
	v_cmp_lt_i32_e64 s[12:13], s88, v156
	s_waitcnt vmcnt(0)
	v_pk_mul_f32 v[160:161], v[130:131], v[136:137]
	s_nop 0
	v_add_f32_e32 v116, v160, v161
	global_store_dword v[158:159], v116, off
	v_add_u32_e32 v158, 0xffffff09, v134
	s_and_saveexec_b64 s[14:15], s[12:13]
	s_xor_b64 s[12:13], exec, s[14:15]
	v_mov_b32_e32 v159, v129
	v_lshlrev_b64 v[160:161], 13, v[158:159]
	v_lshl_add_u64 v[160:161], v[150:151], 0, v[160:161]
	v_mov_b32_e32 v157, v129
	s_andn2_saveexec_b64 s[12:13], s[12:13]
	v_ashrrev_i32_e32 v157, 31, v156
	v_lshlrev_b64 v[160:161], 13, v[156:157]
	v_lshl_add_u64 v[160:161], v[154:155], 0, v[160:161]
	s_or_b64 exec, exec, s[12:13]
	global_load_dword v137, v[160:161], off
	v_mov_b32_e32 v130, v117
	v_mul_lo_u32 v159, v157, s89
	v_mad_u64_u32 v[160:161], s[12:13], v156, s89, v[144:145]
	v_or_b32_e32 v116, 10, v134
	v_add_u32_e32 v161, v159, v161
	v_cmp_gt_i32_e64 s[12:13], s83, v116
	v_cmp_lt_i32_e64 s[14:15], s88, v116
	s_waitcnt vmcnt(0)
; DI int crow(int i, int h) { return (i & 3) + 8 * (i >> 2) + 4 * h; }
; DI const float* modp(const Params& p, int layer, int v) { return (const float*)(p.ws + OFF_MOD) + (size_t)(layer * 2 + v) * 12288; }
; template <int EPI>
; __device__ __forceinline__ void gemm_tile(const Params& p, int layer, const u16* __restrict__ A, const u16* __restrict__ Bt, int mt, int nt, char* lds) {
;     ...
;       } else if (EPI == 1) {
;         float* PRE = (float*)(p.ws + OFF_P);
;         const int v = m0 < NCTX ? 1 : 0;
;         const float g = modp(p, layer, v)[4096 + gc];
; #pragma unroll
;         for (int e = 0; e < 16; ++e) {
;           const int gr = grb + crow(e, h);
;           float xin;
;           if (layer == 0) xin = (gr < NCTX) ? p.ctx[(size_t)gr * DM + gc] : p.x[(size_t)(gr - NCTX) * DM + gc];
;           else xin = ((const float*)(p.ws + OFF_XRES))[(size_t)gr * LDF + gc];
;           PRE[(size_t)gr * LDF + gc] = ALPHA * xin + (DBG_NOATTN ? 0.f : g * acc[i][j][e]);
;         }
	v_pk_mul_f32 v[162:163], v[130:131], v[136:137]
	s_nop 0
	v_add_f32_e32 v117, v162, v163
	global_store_dword v[160:161], v117, off
	v_add_u32_e32 v160, 0xffffff0a, v134
	s_and_saveexec_b64 s[16:17], s[14:15]
	s_xor_b64 s[14:15], exec, s[16:17]
	v_mov_b32_e32 v161, v129
	v_lshlrev_b64 v[162:163], 13, v[160:161]
	v_lshl_add_u64 v[162:163], v[150:151], 0, v[162:163]
	v_mov_b32_e32 v117, v129
	s_andn2_saveexec_b64 s[14:15], s[14:15]
	v_ashrrev_i32_e32 v117, 31, v116
	v_lshlrev_b64 v[162:163], 13, v[116:117]
	v_lshl_add_u64 v[162:163], v[154:155], 0, v[162:163]
	s_or_b64 exec, exec, s[14:15]
	global_load_dword v137, v[162:163], off
	v_mov_b32_e32 v130, v118
	v_mul_lo_u32 v161, v117, s89
	v_mad_u64_u32 v[164:165], s[14:15], v116, s89, v[144:145]
	v_or_b32_e32 v162, 11, v134
	v_add_u32_e32 v165, v161, v165
	v_cmp_gt_i32_e64 s[14:15], s83, v162
	v_cmp_lt_i32_e64 s[16:17], s88, v162
	s_waitcnt vmcnt(0)
	v_pk_mul_f32 v[166:167], v[130:131], v[136:137]
	s_nop 0
	v_add_f32_e32 v118, v166, v167
	global_store_dword v[164:165], v118, off
	v_add_u32_e32 v164, 0xffffff0b, v134
	s_and_saveexec_b64 s[18:19], s[16:17]
	s_xor_b64 s[16:17], exec, s[18:19]
	v_mov_b32_e32 v165, v129
	v_lshlrev_b64 v[166:167], 13, v[164:165]
	v_lshl_add_u64 v[166:167], v[150:151], 0, v[166:167]
	v_mov_b32_e32 v163, v129
	s_andn2_saveexec_b64 s[16:17], s[16:17]
	v_ashrrev_i32_e32 v163, 31, v162
	v_lshlrev_b64 v[166:167], 13, v[162:163]
	v_lshl_add_u64 v[166:167], v[154:155], 0, v[166:167]
	s_or_b64 exec, exec, s[16:17]
	global_load_dword v137, v[166:167], off
	v_mov_b32_e32 v130, v119
	v_mul_lo_u32 v165, v163, s89
	v_mad_u64_u32 v[166:167], s[16:17], v162, s89, v[144:145]
	v_or_b32_e32 v118, 16, v134
	v_add_u32_e32 v167, v165, v167
	v_cmp_gt_i32_e64 s[16:17], s83, v118
	v_cmp_lt_i32_e64 s[18:19], s88, v118
	s_waitcnt vmcnt(0)
	v_pk_mul_f32 v[168:169], v[130:131], v[136:137]
	s_nop 0
	v_add_f32_e32 v119, v168, v169
	global_store_dword v[166:167], v119, off
	v_add_u32_e32 v166, 0xffffff10, v134
	s_and_saveexec_b64 s[20:21], s[18:19]
	s_xor_b64 s[18:19], exec, s[20:21]
	v_mov_b32_e32 v167, v129
	v_lshlrev_b64 v[168:169], 13, v[166:167]
	v_lshl_add_u64 v[168:169], v[150:151], 0, v[168:169]
	v_mov_b32_e32 v119, v129
	s_andn2_saveexec_b64 s[18:19], s[18:19]
	v_ashrrev_i32_e32 v119, 31, v118
	v_lshlrev_b64 v[168:169], 13, v[118:119]
	v_lshl_add_u64 v[168:169], v[154:155], 0, v[168:169]
	s_or_b64 exec, exec, s[18:19]
	global_load_dword v137, v[168:169], off
	v_mov_b32_e32 v130, v120
	v_mul_lo_u32 v167, v119, s89
	v_mad_u64_u32 v[170:171], s[18:19], v118, s89, v[144:145]
	v_or_b32_e32 v168, 17, v134
	v_add_u32_e32 v171, v167, v171
	v_cmp_gt_i32_e64 s[18:19], s83, v168
	v_cmp_lt_i32_e64 s[20:21], s88, v168
	s_waitcnt vmcnt(0)
	v_pk_mul_f32 v[172:173], v[130:131], v[136:137]
	s_nop 0
	v_add_f32_e32 v120, v172, v173
	global_store_dword v[170:171], v120, off
	v_add_u32_e32 v170, 0xffffff11, v134
	s_and_saveexec_b64 s[22:23], s[20:21]
	s_xor_b64 s[20:21], exec, s[22:23]
	v_mov_b32_e32 v171, v129
	v_lshlrev_b64 v[172:173], 13, v[170:171]
	v_lshl_add_u64 v[172:173], v[150:151], 0, v[172:173]
	v_mov_b32_e32 v169, v129
	s_andn2_saveexec_b64 s[20:21], s[20:21]
	v_ashrrev_i32_e32 v169, 31, v168
	v_lshlrev_b64 v[172:173], 13, v[168:169]
	v_lshl_add_u64 v[172:173], v[154:155], 0, v[172:173]
	s_or_b64 exec, exec, s[20:21]
	global_load_dword v137, v[172:173], off
	v_mov_b32_e32 v130, v121
	v_mul_lo_u32 v171, v169, s89
	v_mad_u64_u32 v[172:173], s[20:21], v168, s89, v[144:145]
	v_or_b32_e32 v120, 18, v134
	v_add_u32_e32 v173, v171, v173
	v_cmp_gt_i32_e64 s[20:21], s83, v120
	v_cmp_lt_i32_e64 s[22:23], s88, v120
	s_waitcnt vmcnt(0)
	v_pk_mul_f32 v[174:175], v[130:131], v[136:137]
	s_nop 0
	v_add_f32_e32 v121, v174, v175
	global_store_dword v[172:173], v121, off
	v_add_u32_e32 v172, 0xffffff12, v134
	s_and_saveexec_b64 s[24:25], s[22:23]
	s_xor_b64 s[22:23], exec, s[24:25]
	v_mov_b32_e32 v173, v129
	v_lshlrev_b64 v[174:175], 13, v[172:173]
	v_lshl_add_u64 v[174:175], v[150:151], 0, v[174:175]
	v_mov_b32_e32 v121, v129
	s_andn2_saveexec_b64 s[22:23], s[22:23]
	v_ashrrev_i32_e32 v121, 31, v120
	v_lshlrev_b64 v[174:175], 13, v[120:121]
	v_lshl_add_u64 v[174:175], v[154:155], 0, v[174:175]
	s_or_b64 exec, exec, s[22:23]
	global_load_dword v137, v[174:175], off
	v_mov_b32_e32 v130, v122
	v_mul_lo_u32 v173, v121, s89
	v_mad_u64_u32 v[176:177], s[22:23], v120, s89, v[144:145]
	v_or_b32_e32 v174, 19, v134
	v_add_u32_e32 v177, v173, v177
	v_cmp_gt_i32_e64 s[22:23], s83, v174
	v_cmp_lt_i32_e64 s[24:25], s88, v174
	s_waitcnt vmcnt(0)
	v_pk_mul_f32 v[178:179], v[130:131], v[136:137]
	s_nop 0
	v_add_f32_e32 v122, v178, v179
	global_store_dword v[176:177], v122, off
	v_add_u32_e32 v176, 0xffffff13, v134
	s_and_saveexec_b64 s[26:27], s[24:25]
	s_xor_b64 s[24:25], exec, s[26:27]
	v_mov_b32_e32 v177, v129
	v_lshlrev_b64 v[178:179], 13, v[176:177]
	v_lshl_add_u64 v[178:179], v[150:151], 0, v[178:179]
	v_mov_b32_e32 v175, v129
	s_andn2_saveexec_b64 s[24:25], s[24:25]
	v_ashrrev_i32_e32 v175, 31, v174
	v_lshlrev_b64 v[178:179], 13, v[174:175]
	v_lshl_add_u64 v[178:179], v[154:155], 0, v[178:179]
	s_or_b64 exec, exec, s[24:25]
	global_load_dword v137, v[178:179], off
	v_mov_b32_e32 v130, v123
	v_mul_lo_u32 v177, v175, s89
	v_mad_u64_u32 v[178:179], s[24:25], v174, s89, v[144:145]
	v_or_b32_e32 v122, 24, v134
	v_add_u32_e32 v179, v177, v179
	v_cmp_gt_i32_e64 s[24:25], s83, v122
	v_cmp_lt_i32_e64 s[26:27], s88, v122
	s_waitcnt vmcnt(0)
; DI int crow(int i, int h) { return (i & 3) + 8 * (i >> 2) + 4 * h; }
; DI const float* modp(const Params& p, int layer, int v) { return (const float*)(p.ws + OFF_MOD) + (size_t)(layer * 2 + v) * 12288; }
; template <int EPI>
; __device__ __forceinline__ void gemm_tile(const Params& p, int layer, const u16* __restrict__ A, const u16* __restrict__ Bt, int mt, int nt, char* lds) {
;     ...
;       } else if (EPI == 1) {
;         float* PRE = (float*)(p.ws + OFF_P);
;         const int v = m0 < NCTX ? 1 : 0;
;         const float g = modp(p, layer, v)[4096 + gc];
; #pragma unroll
;         for (int e = 0; e < 16; ++e) {
;           const int gr = grb + crow(e, h);
;           float xin;
;           if (layer == 0) xin = (gr < NCTX) ? p.ctx[(size_t)gr * DM + gc] : p.x[(size_t)(gr - NCTX) * DM + gc];
;           else xin = ((const float*)(p.ws + OFF_XRES))[(size_t)gr * LDF + gc];
;           PRE[(size_t)gr * LDF + gc] = ALPHA * xin + (DBG_NOATTN ? 0.f : g * acc[i][j][e]);
;         }
	v_pk_mul_f32 v[180:181], v[130:131], v[136:137]
	s_nop 0
	v_add_f32_e32 v123, v180, v181
	global_store_dword v[178:179], v123, off
	v_add_u32_e32 v178, 0xffffff18, v134
	s_and_saveexec_b64 s[28:29], s[26:27]
	s_xor_b64 s[26:27], exec, s[28:29]
	v_mov_b32_e32 v179, v129
	v_lshlrev_b64 v[180:181], 13, v[178:179]
	v_lshl_add_u64 v[180:181], v[150:151], 0, v[180:181]
	v_mov_b32_e32 v123, v129
	s_andn2_saveexec_b64 s[26:27], s[26:27]
	v_ashrrev_i32_e32 v123, 31, v122
	v_lshlrev_b64 v[180:181], 13, v[122:123]
	v_lshl_add_u64 v[180:181], v[154:155], 0, v[180:181]
	s_or_b64 exec, exec, s[26:27]
	global_load_dword v137, v[180:181], off
	v_mov_b32_e32 v130, v124
	v_mul_lo_u32 v179, v123, s89
	v_mad_u64_u32 v[182:183], s[26:27], v122, s89, v[144:145]
	v_or_b32_e32 v180, 25, v134
	v_add_u32_e32 v183, v179, v183
	v_cmp_gt_i32_e64 s[26:27], s83, v180
	v_cmp_lt_i32_e64 s[28:29], s88, v180
	s_waitcnt vmcnt(0)
	v_pk_mul_f32 v[184:185], v[130:131], v[136:137]
	s_nop 0
	v_add_f32_e32 v124, v184, v185
	global_store_dword v[182:183], v124, off
	v_add_u32_e32 v182, 0xffffff19, v134
	s_and_saveexec_b64 s[30:31], s[28:29]
	s_xor_b64 s[28:29], exec, s[30:31]
	v_mov_b32_e32 v183, v129
	v_lshlrev_b64 v[184:185], 13, v[182:183]
	v_lshl_add_u64 v[184:185], v[150:151], 0, v[184:185]
	v_mov_b32_e32 v181, v129
	s_andn2_saveexec_b64 s[28:29], s[28:29]
	v_ashrrev_i32_e32 v181, 31, v180
	v_lshlrev_b64 v[184:185], 13, v[180:181]
	v_lshl_add_u64 v[184:185], v[154:155], 0, v[184:185]
	s_or_b64 exec, exec, s[28:29]
	global_load_dword v137, v[184:185], off
	v_mov_b32_e32 v130, v125
	v_mul_lo_u32 v183, v181, s89
	v_mad_u64_u32 v[124:125], s[28:29], v180, s89, v[144:145]
	v_or_b32_e32 v184, 26, v134
	v_add_u32_e32 v125, v183, v125
	v_cmp_gt_i32_e64 s[28:29], s83, v184
	v_cmp_lt_i32_e64 s[30:31], s88, v184
	s_waitcnt vmcnt(0)
	v_pk_mul_f32 v[186:187], v[130:131], v[136:137]
	s_nop 0
	v_add_f32_e32 v130, v186, v187
	v_add_u32_e32 v186, 0xffffff1a, v134
	global_store_dword v[124:125], v130, off
	s_and_saveexec_b64 s[36:37], s[30:31]
	s_xor_b64 s[30:31], exec, s[36:37]
	v_mov_b32_e32 v187, v129
	v_lshlrev_b64 v[124:125], 13, v[186:187]
	v_lshl_add_u64 v[124:125], v[150:151], 0, v[124:125]
	v_mov_b32_e32 v185, v129
	s_andn2_saveexec_b64 s[30:31], s[30:31]
	v_ashrrev_i32_e32 v185, 31, v184
	v_lshlrev_b64 v[124:125], 13, v[184:185]
	v_lshl_add_u64 v[124:125], v[154:155], 0, v[124:125]
	s_or_b64 exec, exec, s[30:31]
	global_load_dword v137, v[124:125], off
	v_mov_b32_e32 v130, v126
	v_or_b32_e32 v188, 27, v134
	v_cmp_lt_i32_e64 s[36:37], s88, v188
	v_add_u32_e32 v190, 0xffffff1b, v134
	s_waitcnt vmcnt(0)
	v_pk_mul_f32 v[124:125], v[130:131], v[136:137]
	s_nop 0
	v_add_f32_e32 v126, v124, v125
	v_mul_lo_u32 v130, v185, s89
	v_mad_u64_u32 v[124:125], s[30:31], v184, s89, v[144:145]
	v_add_u32_e32 v125, v130, v125
	v_cmp_gt_i32_e64 s[30:31], s83, v188
	global_store_dword v[124:125], v126, off
	s_and_saveexec_b64 s[90:91], s[36:37]
	s_xor_b64 s[36:37], exec, s[90:91]
	v_mov_b32_e32 v191, v129
	v_lshlrev_b64 v[124:125], 13, v[190:191]
	v_lshl_add_u64 v[124:125], v[150:151], 0, v[124:125]
	v_mov_b32_e32 v189, v129
	s_andn2_saveexec_b64 s[36:37], s[36:37]
	v_ashrrev_i32_e32 v189, 31, v188
	v_lshlrev_b64 v[124:125], 13, v[188:189]
	v_lshl_add_u64 v[124:125], v[154:155], 0, v[124:125]
	v_mov_b32_e32 v191, v129
	s_or_b64 exec, exec, s[36:37]
	global_load_dword v126, v[124:125], off
	v_mad_u64_u32 v[144:145], s[36:37], v188, s89, v[144:145]
	v_mul_lo_u32 v187, v189, s89
	v_mov_b32_e32 v150, 0
	v_add_u32_e32 v145, v187, v145
	v_ashrrev_i32_e32 v133, 31, v132
	v_cndmask_b32_e32 v125, 0, v135, vcc
	v_cndmask_b32_e32 v124, v128, v134, vcc
	v_lshlrev_b64 v[124:125], 13, v[124:125]
	v_or_b32_e32 v135, 32, v132
	s_waitcnt vmcnt(0)
	v_mul_f32_e32 v126, 0x3fb504f3, v126
	v_fmac_f32_e32 v126, v127, v136
	global_store_dword v[144:145], v126, off
	s_nop 0
	v_ashrrev_i32_e32 v151, 31, v150
	v_lshl_add_u64 v[126:127], v[150:151], 0, v[132:133]
	v_lshlrev_b64 v[126:127], 2, v[126:127]
	v_lshl_add_u64 v[136:137], s[70:71], 0, v[126:127]
	v_lshl_add_u64 v[144:145], s[68:69], 0, v[126:127]
	v_lshl_add_u64 v[126:127], s[72:73], 0, v[126:127]
	v_lshl_add_u64 v[192:193], v[144:145], 0, s[62:63]
	v_lshl_add_u64 v[194:195], v[126:127], 0, s[62:63]
	v_cndmask_b32_e32 v127, v193, v195, vcc
	v_cndmask_b32_e32 v126, v192, v194, vcc
	v_add_co_u32_e64 v136, s[36:37], s82, v136
	v_lshl_add_u64 v[126:127], v[126:127], 0, v[124:125]
	s_nop 0
	v_addc_co_u32_e64 v137, s[36:37], 0, v137, s[36:37]
	global_load_dword v128, v[126:127], off
	global_load_dword v198, v[136:137], off offset:128
	v_mad_u64_u32 v[136:137], s[36:37], v134, s89, 0
	v_add_u32_e32 v144, v150, v135
	v_add_u32_e32 v137, v137, v196
	v_ashrrev_i32_e32 v145, 31, v144
	v_cndmask_b32_e64 v127, 0, v139, s[0:1]
	v_cndmask_b32_e64 v126, v140, v138, s[0:1]
	v_lshl_add_u64 v[136:137], s[60:61], 0, v[136:137]
	v_lshlrev_b64 v[196:197], 2, v[144:145]
	v_lshlrev_b64 v[126:127], 13, v[126:127]
	v_lshl_add_u64 v[144:145], v[136:137], 0, v[196:197]
	v_cndmask_b32_e64 v151, v193, v195, s[0:1]
	v_cndmask_b32_e64 v150, v192, v194, s[0:1]
	v_lshl_add_u64 v[150:151], v[150:151], 0, v[126:127]
	v_cndmask_b32_e64 v139, 0, v113, s[4:5]
	s_waitcnt vmcnt(1)
	v_mul_f32_e32 v128, 0x3fb504f3, v128
	s_waitcnt vmcnt(0)
	v_fmac_f32_e32 v128, v96, v198
	global_store_dword v[144:145], v128, off
	global_load_dword v96, v[150:151], off
	v_mad_u64_u32 v[144:145], s[36:37], v138, s89, 0
	v_add_u32_e32 v145, v145, v141
	v_cndmask_b32_e64 v138, v142, v112, s[4:5]
	v_lshl_add_u64 v[140:141], s[60:61], 0, v[144:145]
	v_lshlrev_b64 v[138:139], 13, v[138:139]
	v_lshl_add_u64 v[144:145], v[140:141], 0, v[196:197]
	v_cndmask_b32_e64 v151, v193, v195, s[4:5]
	v_cndmask_b32_e64 v150, v192, v194, s[4:5]
	v_lshl_add_u64 v[150:151], v[150:151], 0, v[138:139]
	v_mad_u64_u32 v[112:113], s[36:37], v112, s89, 0
	v_add_u32_e32 v113, v113, v143
	v_lshl_add_u64 v[112:113], s[60:61], 0, v[112:113]
	v_lshl_add_u64 v[142:143], v[112:113], 0, v[196:197]
	s_waitcnt vmcnt(0)
; DI int crow(int i, int h) { return (i & 3) + 8 * (i >> 2) + 4 * h; }
; DI const float* modp(const Params& p, int layer, int v) { return (const float*)(p.ws + OFF_MOD) + (size_t)(layer * 2 + v) * 12288; }
; template <int EPI>
; __device__ __forceinline__ void gemm_tile(const Params& p, int layer, const u16* __restrict__ A, const u16* __restrict__ Bt, int mt, int nt, char* lds) {
;     ...
;       } else if (EPI == 1) {
;         float* PRE = (float*)(p.ws + OFF_P);
;         const int v = m0 < NCTX ? 1 : 0;
;         const float g = modp(p, layer, v)[4096 + gc];
; #pragma unroll
;         for (int e = 0; e < 16; ++e) {
;           const int gr = grb + crow(e, h);
;           float xin;
;           if (layer == 0) xin = (gr < NCTX) ? p.ctx[(size_t)gr * DM + gc] : p.x[(size_t)(gr - NCTX) * DM + gc];
;           else xin = ((const float*)(p.ws + OFF_XRES))[(size_t)gr * LDF + gc];
;           PRE[(size_t)gr * LDF + gc] = ALPHA * xin + (DBG_NOATTN ? 0.f : g * acc[i][j][e]);
;         }
	v_mul_f32_e32 v96, 0x3fb504f3, v96
	v_fmac_f32_e32 v96, v97, v198
	global_store_dword v[144:145], v96, off
	global_load_dword v128, v[150:151], off
	v_cndmask_b32_e64 v97, 0, v147, s[6:7]
	v_cndmask_b32_e64 v96, v148, v146, s[6:7]
	v_lshlrev_b64 v[96:97], 13, v[96:97]
	v_cndmask_b32_e64 v145, v193, v195, s[6:7]
	v_cndmask_b32_e64 v144, v192, v194, s[6:7]
	v_lshl_add_u64 v[144:145], v[144:145], 0, v[96:97]
	v_cndmask_b32_e64 v148, v192, v194, s[8:9]
	s_waitcnt vmcnt(0)
	v_mul_f32_e32 v128, 0x3fb504f3, v128
	v_fmac_f32_e32 v128, v98, v198
	global_store_dword v[142:143], v128, off
	global_load_dword v98, v[144:145], off
	v_mad_u64_u32 v[144:145], s[36:37], v146, s89, 0
	v_add_u32_e32 v145, v145, v149
	v_cndmask_b32_e64 v143, 0, v115, s[8:9]
	v_cndmask_b32_e64 v142, v152, v114, s[8:9]
	v_lshl_add_u64 v[144:145], s[60:61], 0, v[144:145]
	v_lshlrev_b64 v[142:143], 13, v[142:143]
	v_lshl_add_u64 v[146:147], v[144:145], 0, v[196:197]
	v_cndmask_b32_e64 v149, v193, v195, s[8:9]
	v_lshl_add_u64 v[148:149], v[148:149], 0, v[142:143]
	v_mad_u64_u32 v[114:115], s[36:37], v114, s89, 0
	v_add_u32_e32 v115, v115, v153
	v_lshl_add_u64 v[114:115], s[60:61], 0, v[114:115]
	v_cndmask_b32_e64 v153, v193, v195, s[12:13]
	v_cndmask_b32_e64 v152, v192, v194, s[12:13]
	s_waitcnt vmcnt(0)
	v_mul_f32_e32 v98, 0x3fb504f3, v98
	v_fmac_f32_e32 v98, v99, v198
	global_store_dword v[146:147], v98, off
	global_load_dword v128, v[148:149], off
	v_cndmask_b32_e64 v99, 0, v157, s[10:11]
	v_cndmask_b32_e64 v98, v158, v156, s[10:11]
	v_lshlrev_b64 v[98:99], 13, v[98:99]
	v_lshl_add_u64 v[146:147], v[114:115], 0, v[196:197]
	v_cndmask_b32_e64 v149, v193, v195, s[10:11]
	v_cndmask_b32_e64 v148, v192, v194, s[10:11]
	v_lshl_add_u64 v[148:149], v[148:149], 0, v[98:99]
	v_cndmask_b32_e64 v157, v193, v195, s[16:17]
	s_waitcnt vmcnt(0)
	v_mul_f32_e32 v128, 0x3fb504f3, v128
	v_fmac_f32_e32 v128, v100, v198
	global_store_dword v[146:147], v128, off
	global_load_dword v100, v[148:149], off
	v_mad_u64_u32 v[148:149], s[36:37], v156, s89, 0
	v_add_u32_e32 v149, v149, v159
	v_cndmask_b32_e64 v147, 0, v117, s[12:13]
	v_cndmask_b32_e64 v146, v160, v116, s[12:13]
	v_lshl_add_u64 v[148:149], s[60:61], 0, v[148:149]
	v_lshlrev_b64 v[146:147], 13, v[146:147]
	v_lshl_add_u64 v[150:151], v[148:149], 0, v[196:197]
	v_lshl_add_u64 v[152:153], v[152:153], 0, v[146:147]
	v_mad_u64_u32 v[116:117], s[36:37], v116, s89, 0
	v_add_u32_e32 v117, v117, v161
	v_lshl_add_u64 v[116:117], s[60:61], 0, v[116:117]
	v_cndmask_b32_e64 v156, v192, v194, s[16:17]
	v_cndmask_b32_e64 v161, v193, v195, s[20:21]
	v_cndmask_b32_e64 v160, v192, v194, s[20:21]
	s_waitcnt vmcnt(0)
	v_mul_f32_e32 v100, 0x3fb504f3, v100
	v_fmac_f32_e32 v100, v101, v198
	global_store_dword v[150:151], v100, off
	global_load_dword v128, v[152:153], off
	v_cndmask_b32_e64 v101, 0, v163, s[14:15]
	v_cndmask_b32_e64 v100, v164, v162, s[14:15]
	v_lshlrev_b64 v[100:101], 13, v[100:101]
	v_lshl_add_u64 v[150:151], v[116:117], 0, v[196:197]
	v_cndmask_b32_e64 v153, v193, v195, s[14:15]
	v_cndmask_b32_e64 v152, v192, v194, s[14:15]
	v_lshl_add_u64 v[152:153], v[152:153], 0, v[100:101]
	v_cndmask_b32_e64 v164, v192, v194, s[24:25]
	s_waitcnt vmcnt(0)
	v_mul_f32_e32 v128, 0x3fb504f3, v128
	v_fmac_f32_e32 v128, v102, v198
	global_store_dword v[150:151], v128, off
	global_load_dword v102, v[152:153], off
	v_mad_u64_u32 v[152:153], s[36:37], v162, s89, 0
	v_add_u32_e32 v153, v153, v165
	v_cndmask_b32_e64 v151, 0, v119, s[16:17]
	v_cndmask_b32_e64 v150, v166, v118, s[16:17]
	v_lshl_add_u64 v[152:153], s[60:61], 0, v[152:153]
	v_lshlrev_b64 v[150:151], 13, v[150:151]
	v_lshl_add_u64 v[154:155], v[152:153], 0, v[196:197]
	v_lshl_add_u64 v[156:157], v[156:157], 0, v[150:151]
	v_mad_u64_u32 v[118:119], s[36:37], v118, s89, 0
	v_add_u32_e32 v119, v119, v167
	v_lshl_add_u64 v[118:119], s[60:61], 0, v[118:119]
	v_cndmask_b32_e64 v165, v193, v195, s[24:25]
	s_waitcnt vmcnt(0)
	v_mul_f32_e32 v102, 0x3fb504f3, v102
	v_fmac_f32_e32 v102, v103, v198
	global_store_dword v[154:155], v102, off
	global_load_dword v128, v[156:157], off
	v_cndmask_b32_e64 v103, 0, v169, s[18:19]
	v_cndmask_b32_e64 v102, v170, v168, s[18:19]
	v_lshlrev_b64 v[102:103], 13, v[102:103]
	v_lshl_add_u64 v[154:155], v[118:119], 0, v[196:197]
	v_cndmask_b32_e64 v157, v193, v195, s[18:19]
	v_cndmask_b32_e64 v156, v192, v194, s[18:19]
	v_lshl_add_u64 v[156:157], v[156:157], 0, v[102:103]
	v_cndmask_b32_e64 v169, v193, v195, s[28:29]
	v_cndmask_b32_e64 v170, v192, v194, s[30:31]
	s_waitcnt vmcnt(0)
	v_mul_f32_e32 v128, 0x3fb504f3, v128
	v_fmac_f32_e32 v128, v104, v198
	global_store_dword v[154:155], v128, off
	global_load_dword v104, v[156:157], off
	v_mad_u64_u32 v[156:157], s[36:37], v168, s89, 0
	v_add_u32_e32 v157, v157, v171
	v_cndmask_b32_e64 v155, 0, v121, s[20:21]
	v_cndmask_b32_e64 v154, v172, v120, s[20:21]
	v_lshl_add_u64 v[156:157], s[60:61], 0, v[156:157]
	v_lshlrev_b64 v[154:155], 13, v[154:155]
	v_lshl_add_u64 v[158:159], v[156:157], 0, v[196:197]
	v_lshl_add_u64 v[160:161], v[160:161], 0, v[154:155]
	v_mad_u64_u32 v[120:121], s[36:37], v120, s89, 0
	v_add_u32_e32 v121, v121, v173
	v_lshl_add_u64 v[120:121], s[60:61], 0, v[120:121]
	v_cndmask_b32_e64 v168, v192, v194, s[28:29]
	v_cndmask_b32_e64 v171, v193, v195, s[30:31]
	s_waitcnt vmcnt(0)
	v_mul_f32_e32 v104, 0x3fb504f3, v104
	v_fmac_f32_e32 v104, v105, v198
	global_store_dword v[158:159], v104, off
	global_load_dword v128, v[160:161], off
	v_cndmask_b32_e64 v105, 0, v175, s[22:23]
	v_cndmask_b32_e64 v104, v176, v174, s[22:23]
	v_lshlrev_b64 v[104:105], 13, v[104:105]
	v_lshl_add_u64 v[158:159], v[120:121], 0, v[196:197]
	v_cndmask_b32_e64 v161, v193, v195, s[22:23]
	v_cndmask_b32_e64 v160, v192, v194, s[22:23]
	v_lshl_add_u64 v[160:161], v[160:161], 0, v[104:105]
	s_waitcnt vmcnt(0)
; DI int crow(int i, int h) { return (i & 3) + 8 * (i >> 2) + 4 * h; }
; DI const float* modp(const Params& p, int layer, int v) { return (const float*)(p.ws + OFF_MOD) + (size_t)(layer * 2 + v) * 12288; }
; template <int EPI>
; __device__ __forceinline__ void gemm_tile(const Params& p, int layer, const u16* __restrict__ A, const u16* __restrict__ Bt, int mt, int nt, char* lds) {
;     ...
;       } else if (EPI == 1) {
;         float* PRE = (float*)(p.ws + OFF_P);
;         const int v = m0 < NCTX ? 1 : 0;
;         const float g = modp(p, layer, v)[4096 + gc];
; #pragma unroll
;         for (int e = 0; e < 16; ++e) {
;           const int gr = grb + crow(e, h);
;           float xin;
;           if (layer == 0) xin = (gr < NCTX) ? p.ctx[(size_t)gr * DM + gc] : p.x[(size_t)(gr - NCTX) * DM + gc];
;           else xin = ((const float*)(p.ws + OFF_XRES))[(size_t)gr * LDF + gc];
;           PRE[(size_t)gr * LDF + gc] = ALPHA * xin + (DBG_NOATTN ? 0.f : g * acc[i][j][e]);
;         }
	v_mul_f32_e32 v128, 0x3fb504f3, v128
	v_fmac_f32_e32 v128, v106, v198
	global_store_dword v[158:159], v128, off
	global_load_dword v106, v[160:161], off
	v_mad_u64_u32 v[160:161], s[36:37], v174, s89, 0
	v_add_u32_e32 v161, v161, v177
	v_cndmask_b32_e64 v159, 0, v123, s[24:25]
	v_cndmask_b32_e64 v158, v178, v122, s[24:25]
	v_lshl_add_u64 v[160:161], s[60:61], 0, v[160:161]
	v_lshlrev_b64 v[158:159], 13, v[158:159]
	v_lshl_add_u64 v[162:163], v[160:161], 0, v[196:197]
	v_lshl_add_u64 v[164:165], v[164:165], 0, v[158:159]
	v_mad_u64_u32 v[122:123], s[36:37], v122, s89, 0
	v_add_u32_e32 v123, v123, v179
	v_lshl_add_u64 v[122:123], s[60:61], 0, v[122:123]
	s_waitcnt vmcnt(0)
	v_mul_f32_e32 v106, 0x3fb504f3, v106
	v_fmac_f32_e32 v106, v107, v198
	global_store_dword v[162:163], v106, off
	global_load_dword v128, v[164:165], off
	v_cndmask_b32_e64 v107, 0, v181, s[26:27]
	v_cndmask_b32_e64 v106, v182, v180, s[26:27]
	v_lshlrev_b64 v[106:107], 13, v[106:107]
	v_lshl_add_u64 v[162:163], v[122:123], 0, v[196:197]
	v_cndmask_b32_e64 v165, v193, v195, s[26:27]
	v_cndmask_b32_e64 v164, v192, v194, s[26:27]
	v_lshl_add_u64 v[164:165], v[164:165], 0, v[106:107]
	s_waitcnt vmcnt(0)
	v_mul_f32_e32 v128, 0x3fb504f3, v128
	v_fmac_f32_e32 v128, v108, v198
	global_store_dword v[162:163], v128, off
	global_load_dword v108, v[164:165], off
	v_mad_u64_u32 v[164:165], s[36:37], v180, s89, 0
	v_add_u32_e32 v165, v165, v183
	v_cndmask_b32_e64 v163, 0, v185, s[28:29]
	v_cndmask_b32_e64 v162, v186, v184, s[28:29]
	v_lshl_add_u64 v[164:165], s[60:61], 0, v[164:165]
	v_lshlrev_b64 v[162:163], 13, v[162:163]
	v_lshl_add_u64 v[166:167], v[164:165], 0, v[196:197]
	v_lshl_add_u64 v[168:169], v[168:169], 0, v[162:163]
	s_waitcnt vmcnt(0)
	v_mul_f32_e32 v108, 0x3fb504f3, v108
	v_fmac_f32_e32 v108, v109, v198
	global_store_dword v[166:167], v108, off
	global_load_dword v128, v[168:169], off
	v_mad_u64_u32 v[166:167], s[36:37], v184, s89, 0
	v_add_u32_e32 v167, v167, v130
	v_cndmask_b32_e64 v109, v191, v189, s[30:31]
	v_cndmask_b32_e64 v108, v190, v188, s[30:31]
	v_lshl_add_u64 v[166:167], s[60:61], 0, v[166:167]
	v_lshlrev_b64 v[108:109], 13, v[108:109]
	v_lshl_add_u64 v[168:169], v[166:167], 0, v[196:197]
	v_lshl_add_u64 v[170:171], v[170:171], 0, v[108:109]
	s_waitcnt vmcnt(0)
	v_mul_f32_e32 v128, 0x3fb504f3, v128
	v_fmac_f32_e32 v128, v110, v198
	global_store_dword v[168:169], v128, off
	global_load_dword v128, v[170:171], off
	v_mov_b64_e32 v[168:169], s[60:61]
	v_mad_u64_u32 v[168:169], s[36:37], v188, s89, v[168:169]
	v_add_u32_e32 v169, v187, v169
	v_mov_b32_e32 v110, 0
	v_lshl_add_u64 v[170:171], v[168:169], 0, v[196:197]
	s_waitcnt vmcnt(0)
	v_mul_f32_e32 v128, 0x3fb504f3, v128
	v_fmac_f32_e32 v128, v111, v198
	global_store_dword v[170:171], v128, off
	s_nop 0
	v_ashrrev_i32_e32 v111, 31, v110
	v_lshl_add_u64 v[170:171], v[110:111], 0, v[132:133]
	v_lshlrev_b64 v[170:171], 2, v[170:171]
	v_lshl_add_u64 v[172:173], s[70:71], 0, v[170:171]
	v_lshl_add_u64 v[174:175], s[68:69], 0, v[170:171]
	v_lshl_add_u64 v[170:171], s[72:73], 0, v[170:171]
	v_lshl_add_u64 v[174:175], v[174:175], 0, s[64:65]
	v_lshl_add_u64 v[176:177], v[170:171], 0, s[64:65]
	v_cndmask_b32_e32 v171, v175, v177, vcc
	v_cndmask_b32_e32 v170, v174, v176, vcc
	v_add_co_u32_e64 v172, s[36:37], s82, v172
	v_lshl_add_u64 v[170:171], v[170:171], 0, v[124:125]
	s_nop 0
	v_addc_co_u32_e64 v173, s[36:37], 0, v173, s[36:37]
	global_load_dword v128, v[170:171], off
	global_load_dword v130, v[172:173], off offset:256
	v_or_b32_e32 v170, 64, v132
	v_add_u32_e32 v110, v110, v170
	v_ashrrev_i32_e32 v111, 31, v110
	v_lshlrev_b64 v[110:111], 2, v[110:111]
	v_lshl_add_u64 v[172:173], v[136:137], 0, v[110:111]
	v_cndmask_b32_e64 v179, v175, v177, s[0:1]
	v_cndmask_b32_e64 v178, v174, v176, s[0:1]
	v_lshl_add_u64 v[178:179], v[178:179], 0, v[126:127]
	v_or_b32_e32 v171, 0x60, v132
	s_waitcnt vmcnt(1)
	v_mul_f32_e32 v128, 0x3fb504f3, v128
	s_waitcnt vmcnt(0)
	v_fmac_f32_e32 v128, v80, v130
	global_store_dword v[172:173], v128, off
	global_load_dword v80, v[178:179], off
	v_lshl_add_u64 v[172:173], v[140:141], 0, v[110:111]
	v_cndmask_b32_e64 v179, v175, v177, s[4:5]
	v_cndmask_b32_e64 v178, v174, v176, s[4:5]
	v_lshl_add_u64 v[178:179], v[178:179], 0, v[138:139]
	s_waitcnt vmcnt(0)
	v_mul_f32_e32 v80, 0x3fb504f3, v80
	v_fmac_f32_e32 v80, v81, v130
	global_store_dword v[172:173], v80, off
	global_load_dword v128, v[178:179], off
	v_lshl_add_u64 v[80:81], v[112:113], 0, v[110:111]
	v_cndmask_b32_e64 v173, v175, v177, s[6:7]
	v_cndmask_b32_e64 v172, v174, v176, s[6:7]
	v_lshl_add_u64 v[172:173], v[172:173], 0, v[96:97]
	s_waitcnt vmcnt(0)
	v_mul_f32_e32 v128, 0x3fb504f3, v128
	v_fmac_f32_e32 v128, v82, v130
	global_store_dword v[80:81], v128, off
	global_load_dword v82, v[172:173], off
	v_lshl_add_u64 v[80:81], v[144:145], 0, v[110:111]
	v_cndmask_b32_e64 v173, v175, v177, s[8:9]
	v_cndmask_b32_e64 v172, v174, v176, s[8:9]
	v_lshl_add_u64 v[172:173], v[172:173], 0, v[142:143]
	s_waitcnt vmcnt(0)
	v_mul_f32_e32 v82, 0x3fb504f3, v82
	v_fmac_f32_e32 v82, v83, v130
	global_store_dword v[80:81], v82, off
	global_load_dword v128, v[172:173], off
	v_lshl_add_u64 v[80:81], v[114:115], 0, v[110:111]
	v_cndmask_b32_e64 v83, v175, v177, s[10:11]
	v_cndmask_b32_e64 v82, v174, v176, s[10:11]
	v_lshl_add_u64 v[82:83], v[82:83], 0, v[98:99]
	s_waitcnt vmcnt(0)
	v_mul_f32_e32 v128, 0x3fb504f3, v128
	v_fmac_f32_e32 v128, v84, v130
	global_store_dword v[80:81], v128, off
	global_load_dword v84, v[82:83], off
	v_lshl_add_u64 v[80:81], v[148:149], 0, v[110:111]
	v_cndmask_b32_e64 v83, v175, v177, s[12:13]
	v_cndmask_b32_e64 v82, v174, v176, s[12:13]
	v_lshl_add_u64 v[82:83], v[82:83], 0, v[146:147]
	v_add_u32_e32 v128, 0xffffff20, v134
	s_waitcnt vmcnt(0)
; DI int crow(int i, int h) { return (i & 3) + 8 * (i >> 2) + 4 * h; }
; DI const float* modp(const Params& p, int layer, int v) { return (const float*)(p.ws + OFF_MOD) + (size_t)(layer * 2 + v) * 12288; }
; template <int EPI>
; __device__ __forceinline__ void gemm_tile(const Params& p, int layer, const u16* __restrict__ A, const u16* __restrict__ Bt, int mt, int nt, char* lds) {
;     ...
;       } else if (EPI == 1) {
;         float* PRE = (float*)(p.ws + OFF_P);
;         const int v = m0 < NCTX ? 1 : 0;
;         const float g = modp(p, layer, v)[4096 + gc];
; #pragma unroll
;         for (int e = 0; e < 16; ++e) {
;           const int gr = grb + crow(e, h);
;           float xin;
;           if (layer == 0) xin = (gr < NCTX) ? p.ctx[(size_t)gr * DM + gc] : p.x[(size_t)(gr - NCTX) * DM + gc];
;           else xin = ((const float*)(p.ws + OFF_XRES))[(size_t)gr * LDF + gc];
;           PRE[(size_t)gr * LDF + gc] = ALPHA * xin + (DBG_NOATTN ? 0.f : g * acc[i][j][e]);
;         }
	v_mul_f32_e32 v84, 0x3fb504f3, v84
	v_fmac_f32_e32 v84, v85, v130
	global_store_dword v[80:81], v84, off
	global_load_dword v84, v[82:83], off
	v_lshl_add_u64 v[80:81], v[116:117], 0, v[110:111]
	v_cndmask_b32_e64 v83, v175, v177, s[14:15]
	v_cndmask_b32_e64 v82, v174, v176, s[14:15]
	v_lshl_add_u64 v[82:83], v[82:83], 0, v[100:101]
	s_waitcnt vmcnt(0)
	v_mul_f32_e32 v84, 0x3fb504f3, v84
	v_fmac_f32_e32 v84, v86, v130
	global_store_dword v[80:81], v84, off
	global_load_dword v84, v[82:83], off
	v_lshl_add_u64 v[80:81], v[152:153], 0, v[110:111]
	v_cndmask_b32_e64 v83, v175, v177, s[16:17]
	v_cndmask_b32_e64 v82, v174, v176, s[16:17]
	v_lshl_add_u64 v[82:83], v[82:83], 0, v[150:151]
	s_waitcnt vmcnt(0)
	v_mul_f32_e32 v84, 0x3fb504f3, v84
	v_fmac_f32_e32 v84, v87, v130
	global_store_dword v[80:81], v84, off
	global_load_dword v84, v[82:83], off
	v_lshl_add_u64 v[80:81], v[118:119], 0, v[110:111]
	v_cndmask_b32_e64 v83, v175, v177, s[18:19]
	v_cndmask_b32_e64 v82, v174, v176, s[18:19]
	v_lshl_add_u64 v[82:83], v[82:83], 0, v[102:103]
	s_waitcnt vmcnt(0)
	v_mul_f32_e32 v84, 0x3fb504f3, v84
	v_fmac_f32_e32 v84, v88, v130
	global_store_dword v[80:81], v84, off
	global_load_dword v84, v[82:83], off
	v_lshl_add_u64 v[80:81], v[156:157], 0, v[110:111]
	v_cndmask_b32_e64 v83, v175, v177, s[20:21]
	v_cndmask_b32_e64 v82, v174, v176, s[20:21]
	v_lshl_add_u64 v[82:83], v[82:83], 0, v[154:155]
	s_waitcnt vmcnt(0)
	v_mul_f32_e32 v84, 0x3fb504f3, v84
	v_fmac_f32_e32 v84, v89, v130
	global_store_dword v[80:81], v84, off
	global_load_dword v84, v[82:83], off
	v_lshl_add_u64 v[80:81], v[120:121], 0, v[110:111]
	v_cndmask_b32_e64 v83, v175, v177, s[22:23]
	v_cndmask_b32_e64 v82, v174, v176, s[22:23]
	v_lshl_add_u64 v[82:83], v[82:83], 0, v[104:105]
	s_waitcnt vmcnt(0)
	v_mul_f32_e32 v84, 0x3fb504f3, v84
	v_fmac_f32_e32 v84, v90, v130
	global_store_dword v[80:81], v84, off
	global_load_dword v84, v[82:83], off
	v_lshl_add_u64 v[80:81], v[160:161], 0, v[110:111]
	v_cndmask_b32_e64 v83, v175, v177, s[24:25]
	v_cndmask_b32_e64 v82, v174, v176, s[24:25]
	v_lshl_add_u64 v[82:83], v[82:83], 0, v[158:159]
	s_waitcnt vmcnt(0)
	v_mul_f32_e32 v84, 0x3fb504f3, v84
	v_fmac_f32_e32 v84, v91, v130
	global_store_dword v[80:81], v84, off
	global_load_dword v84, v[82:83], off
	v_lshl_add_u64 v[80:81], v[122:123], 0, v[110:111]
	v_cndmask_b32_e64 v83, v175, v177, s[26:27]
	v_cndmask_b32_e64 v82, v174, v176, s[26:27]
	v_lshl_add_u64 v[82:83], v[82:83], 0, v[106:107]
	s_waitcnt vmcnt(0)
	v_mul_f32_e32 v84, 0x3fb504f3, v84
	v_fmac_f32_e32 v84, v92, v130
	global_store_dword v[80:81], v84, off
	global_load_dword v84, v[82:83], off
	v_lshl_add_u64 v[80:81], v[164:165], 0, v[110:111]
	v_cndmask_b32_e64 v83, v175, v177, s[28:29]
	v_cndmask_b32_e64 v82, v174, v176, s[28:29]
	v_lshl_add_u64 v[82:83], v[82:83], 0, v[162:163]
	s_waitcnt vmcnt(0)
	v_mul_f32_e32 v84, 0x3fb504f3, v84
	v_fmac_f32_e32 v84, v93, v130
	global_store_dword v[80:81], v84, off
	global_load_dword v84, v[82:83], off
	v_lshl_add_u64 v[80:81], v[166:167], 0, v[110:111]
	v_cndmask_b32_e64 v83, v175, v177, s[30:31]
	v_cndmask_b32_e64 v82, v174, v176, s[30:31]
	v_lshl_add_u64 v[82:83], v[82:83], 0, v[108:109]
	s_waitcnt vmcnt(0)
	v_mul_f32_e32 v84, 0x3fb504f3, v84
	v_fmac_f32_e32 v84, v94, v130
	global_store_dword v[80:81], v84, off
	global_load_dword v81, v[82:83], off
	v_mov_b32_e32 v80, 0
	v_lshl_add_u64 v[82:83], v[168:169], 0, v[110:111]
	s_waitcnt vmcnt(0)
	v_mul_f32_e32 v81, 0x3fb504f3, v81
	v_fmac_f32_e32 v81, v95, v130
	global_store_dword v[82:83], v81, off
	s_nop 0
	v_ashrrev_i32_e32 v81, 31, v80
	v_lshl_add_u64 v[82:83], v[80:81], 0, v[132:133]
	v_lshlrev_b64 v[82:83], 2, v[82:83]
	v_lshl_add_u64 v[84:85], s[70:71], 0, v[82:83]
	v_lshl_add_u64 v[86:87], s[68:69], 0, v[82:83]
	v_lshl_add_u64 v[82:83], s[72:73], 0, v[82:83]
	v_lshl_add_u64 v[86:87], v[86:87], 0, s[66:67]
	v_lshl_add_u64 v[82:83], v[82:83], 0, s[66:67]
	v_cndmask_b32_e32 v89, v87, v83, vcc
	v_cndmask_b32_e32 v88, v86, v82, vcc
	v_add_co_u32_e64 v84, s[36:37], s82, v84
	v_lshl_add_u64 v[88:89], v[88:89], 0, v[124:125]
	s_nop 0
	v_addc_co_u32_e64 v85, s[36:37], 0, v85, s[36:37]
	global_load_dword v90, v[88:89], off
	global_load_dword v91, v[84:85], off offset:384
	v_add_u32_e32 v80, v80, v171
	v_ashrrev_i32_e32 v81, 31, v80
	v_lshlrev_b64 v[80:81], 2, v[80:81]
	v_lshl_add_u64 v[84:85], v[136:137], 0, v[80:81]
	v_cndmask_b32_e64 v89, v87, v83, s[0:1]
	v_cndmask_b32_e64 v88, v86, v82, s[0:1]
	v_lshl_add_u64 v[88:89], v[88:89], 0, v[126:127]
	s_waitcnt vmcnt(1)
	v_mul_f32_e32 v90, 0x3fb504f3, v90
	s_waitcnt vmcnt(0)
	v_fmac_f32_e32 v90, v64, v91
	global_store_dword v[84:85], v90, off
	global_load_dword v64, v[88:89], off
	v_lshl_add_u64 v[84:85], v[140:141], 0, v[80:81]
	v_cndmask_b32_e64 v89, v87, v83, s[4:5]
	v_cndmask_b32_e64 v88, v86, v82, s[4:5]
	v_lshl_add_u64 v[88:89], v[88:89], 0, v[138:139]
	s_waitcnt vmcnt(0)
	v_mul_f32_e32 v64, 0x3fb504f3, v64
	v_fmac_f32_e32 v64, v65, v91
	global_store_dword v[84:85], v64, off
	global_load_dword v88, v[88:89], off
	v_lshl_add_u64 v[64:65], v[112:113], 0, v[80:81]
	v_cndmask_b32_e64 v85, v87, v83, s[6:7]
	v_cndmask_b32_e64 v84, v86, v82, s[6:7]
	v_lshl_add_u64 v[84:85], v[84:85], 0, v[96:97]
	s_waitcnt vmcnt(0)
	v_mul_f32_e32 v88, 0x3fb504f3, v88
	v_fmac_f32_e32 v88, v66, v91
	global_store_dword v[64:65], v88, off
	global_load_dword v66, v[84:85], off
	v_lshl_add_u64 v[64:65], v[144:145], 0, v[80:81]
	v_cndmask_b32_e64 v85, v87, v83, s[8:9]
	v_cndmask_b32_e64 v84, v86, v82, s[8:9]
	v_lshl_add_u64 v[84:85], v[84:85], 0, v[142:143]
	s_waitcnt vmcnt(0)
; DI int crow(int i, int h) { return (i & 3) + 8 * (i >> 2) + 4 * h; }
; DI const float* modp(const Params& p, int layer, int v) { return (const float*)(p.ws + OFF_MOD) + (size_t)(layer * 2 + v) * 12288; }
; template <int EPI>
; __device__ __forceinline__ void gemm_tile(const Params& p, int layer, const u16* __restrict__ A, const u16* __restrict__ Bt, int mt, int nt, char* lds) {
;     ...
;       } else if (EPI == 1) {
;         float* PRE = (float*)(p.ws + OFF_P);
;         const int v = m0 < NCTX ? 1 : 0;
;         const float g = modp(p, layer, v)[4096 + gc];
; #pragma unroll
;         for (int e = 0; e < 16; ++e) {
;           const int gr = grb + crow(e, h);
;           float xin;
;           if (layer == 0) xin = (gr < NCTX) ? p.ctx[(size_t)gr * DM + gc] : p.x[(size_t)(gr - NCTX) * DM + gc];
;           else xin = ((const float*)(p.ws + OFF_XRES))[(size_t)gr * LDF + gc];
;           PRE[(size_t)gr * LDF + gc] = ALPHA * xin + (DBG_NOATTN ? 0.f : g * acc[i][j][e]);
;         }
	v_mul_f32_e32 v66, 0x3fb504f3, v66
	v_fmac_f32_e32 v66, v67, v91
	global_store_dword v[64:65], v66, off
	global_load_dword v84, v[84:85], off
	v_lshl_add_u64 v[64:65], v[114:115], 0, v[80:81]
	v_cndmask_b32_e64 v67, v87, v83, s[10:11]
	v_cndmask_b32_e64 v66, v86, v82, s[10:11]
	v_lshl_add_u64 v[66:67], v[66:67], 0, v[98:99]
	s_waitcnt vmcnt(0)
	v_mul_f32_e32 v84, 0x3fb504f3, v84
	v_fmac_f32_e32 v84, v68, v91
	global_store_dword v[64:65], v84, off
	global_load_dword v68, v[66:67], off
	v_lshl_add_u64 v[64:65], v[148:149], 0, v[80:81]
	v_cndmask_b32_e64 v67, v87, v83, s[12:13]
	v_cndmask_b32_e64 v66, v86, v82, s[12:13]
	v_lshl_add_u64 v[66:67], v[66:67], 0, v[146:147]
	s_waitcnt vmcnt(0)
	v_mul_f32_e32 v68, 0x3fb504f3, v68
	v_fmac_f32_e32 v68, v69, v91
	global_store_dword v[64:65], v68, off
	global_load_dword v68, v[66:67], off
	v_lshl_add_u64 v[64:65], v[116:117], 0, v[80:81]
	v_cndmask_b32_e64 v67, v87, v83, s[14:15]
	v_cndmask_b32_e64 v66, v86, v82, s[14:15]
	v_lshl_add_u64 v[66:67], v[66:67], 0, v[100:101]
	s_waitcnt vmcnt(0)
	v_mul_f32_e32 v68, 0x3fb504f3, v68
	v_fmac_f32_e32 v68, v70, v91
	global_store_dword v[64:65], v68, off
	global_load_dword v68, v[66:67], off
	v_lshl_add_u64 v[64:65], v[152:153], 0, v[80:81]
	v_cndmask_b32_e64 v67, v87, v83, s[16:17]
	v_cndmask_b32_e64 v66, v86, v82, s[16:17]
	v_lshl_add_u64 v[66:67], v[66:67], 0, v[150:151]
	s_waitcnt vmcnt(0)
	v_mul_f32_e32 v68, 0x3fb504f3, v68
	v_fmac_f32_e32 v68, v71, v91
	global_store_dword v[64:65], v68, off
	global_load_dword v68, v[66:67], off
	v_lshl_add_u64 v[64:65], v[118:119], 0, v[80:81]
	v_cndmask_b32_e64 v67, v87, v83, s[18:19]
	v_cndmask_b32_e64 v66, v86, v82, s[18:19]
	v_lshl_add_u64 v[66:67], v[66:67], 0, v[102:103]
	s_waitcnt vmcnt(0)
	v_mul_f32_e32 v68, 0x3fb504f3, v68
	v_fmac_f32_e32 v68, v72, v91
	global_store_dword v[64:65], v68, off
	global_load_dword v68, v[66:67], off
	v_lshl_add_u64 v[64:65], v[156:157], 0, v[80:81]
	v_cndmask_b32_e64 v67, v87, v83, s[20:21]
	v_cndmask_b32_e64 v66, v86, v82, s[20:21]
	v_lshl_add_u64 v[66:67], v[66:67], 0, v[154:155]
	s_waitcnt vmcnt(0)
	v_mul_f32_e32 v68, 0x3fb504f3, v68
	v_fmac_f32_e32 v68, v73, v91
	global_store_dword v[64:65], v68, off
	global_load_dword v68, v[66:67], off
	v_lshl_add_u64 v[64:65], v[120:121], 0, v[80:81]
	v_cndmask_b32_e64 v67, v87, v83, s[22:23]
	v_cndmask_b32_e64 v66, v86, v82, s[22:23]
	v_lshl_add_u64 v[66:67], v[66:67], 0, v[104:105]
	s_waitcnt vmcnt(0)
	v_mul_f32_e32 v68, 0x3fb504f3, v68
	v_fmac_f32_e32 v68, v74, v91
	global_store_dword v[64:65], v68, off
	global_load_dword v68, v[66:67], off
	v_lshl_add_u64 v[64:65], v[160:161], 0, v[80:81]
	v_cndmask_b32_e64 v67, v87, v83, s[24:25]
	v_cndmask_b32_e64 v66, v86, v82, s[24:25]
	v_lshl_add_u64 v[66:67], v[66:67], 0, v[158:159]
	s_waitcnt vmcnt(0)
	v_mul_f32_e32 v68, 0x3fb504f3, v68
	v_fmac_f32_e32 v68, v75, v91
	global_store_dword v[64:65], v68, off
	global_load_dword v68, v[66:67], off
	v_lshl_add_u64 v[64:65], v[122:123], 0, v[80:81]
	v_cndmask_b32_e64 v67, v87, v83, s[26:27]
	v_cndmask_b32_e64 v66, v86, v82, s[26:27]
	v_lshl_add_u64 v[66:67], v[66:67], 0, v[106:107]
	s_waitcnt vmcnt(0)
	v_mul_f32_e32 v68, 0x3fb504f3, v68
	v_fmac_f32_e32 v68, v76, v91
	global_store_dword v[64:65], v68, off
	global_load_dword v68, v[66:67], off
	v_lshl_add_u64 v[64:65], v[164:165], 0, v[80:81]
	v_cndmask_b32_e64 v67, v87, v83, s[28:29]
	v_cndmask_b32_e64 v66, v86, v82, s[28:29]
	v_lshl_add_u64 v[66:67], v[66:67], 0, v[162:163]
	s_waitcnt vmcnt(0)
	v_mul_f32_e32 v68, 0x3fb504f3, v68
	v_fmac_f32_e32 v68, v77, v91
	global_store_dword v[64:65], v68, off
	global_load_dword v68, v[66:67], off
	v_lshl_add_u64 v[64:65], v[166:167], 0, v[80:81]
	v_cndmask_b32_e64 v67, v87, v83, s[30:31]
	v_cndmask_b32_e64 v66, v86, v82, s[30:31]
	v_lshl_add_u64 v[66:67], v[66:67], 0, v[108:109]
	s_waitcnt vmcnt(0)
	v_mul_f32_e32 v68, 0x3fb504f3, v68
	v_fmac_f32_e32 v68, v78, v91
	global_store_dword v[64:65], v68, off
	global_load_dword v66, v[66:67], off
	v_mov_b32_e32 v67, 0
	v_lshl_add_u64 v[64:65], v[168:169], 0, v[80:81]
	s_waitcnt vmcnt(0)
	v_mul_f32_e32 v66, 0x3fb504f3, v66
	v_fmac_f32_e32 v66, v79, v91
	global_store_dword v[64:65], v66, off
	s_nop 0
	v_add_u32_e32 v68, v67, v132
	v_ashrrev_i32_e32 v69, 31, v68
	v_lshlrev_b64 v[70:71], 2, v[68:69]
	v_lshl_add_u64 v[64:65], s[70:71], 0, v[70:71]
	v_add_co_u32_e32 v64, vcc, 0xa724000, v64
	v_lshl_add_u64 v[80:81], s[68:69], 0, v[70:71]
	s_nop 0
	v_addc_co_u32_e32 v65, vcc, 0, v65, vcc
	global_load_dword v66, v[64:65], off
	v_or_b32_e32 v64, 32, v134
	v_cmp_gt_i32_e32 vcc, s83, v64
	v_cmp_lt_i32_e64 s[0:1], s88, v64
	s_and_saveexec_b64 s[4:5], s[0:1]
	s_xor_b64 s[0:1], exec, s[4:5]
	v_lshlrev_b64 v[72:73], 13, v[128:129]
	v_lshl_add_u64 v[72:73], v[80:81], 0, v[72:73]
	v_mov_b32_e32 v65, v129
	s_or_saveexec_b64 s[0:1], s[0:1]
	v_lshl_add_u64 v[82:83], s[72:73], 0, v[70:71]
	s_xor_b64 exec, exec, s[0:1]
	v_ashrrev_i32_e32 v65, 31, v64
	v_lshlrev_b64 v[70:71], 13, v[64:65]
	v_lshl_add_u64 v[72:73], v[82:83], 0, v[70:71]
	s_or_b64 exec, exec, s[0:1]
	global_load_dword v67, v[72:73], off
	v_lshl_add_u64 v[74:75], v[68:69], 2, s[60:61]
	v_mov_b32_e32 v130, v48
	v_mul_lo_u32 v126, v65, s89
	v_mad_u64_u32 v[70:71], s[0:1], v64, s89, v[74:75]
	v_or_b32_e32 v68, 33, v134
	v_add_u32_e32 v71, v126, v71
	v_cmp_gt_i32_e64 s[0:1], s83, v68
	v_cmp_lt_i32_e64 s[4:5], s88, v68
	s_waitcnt vmcnt(0)
; DI int crow(int i, int h) { return (i & 3) + 8 * (i >> 2) + 4 * h; }
; DI const float* modp(const Params& p, int layer, int v) { return (const float*)(p.ws + OFF_MOD) + (size_t)(layer * 2 + v) * 12288; }
; template <int EPI>
; __device__ __forceinline__ void gemm_tile(const Params& p, int layer, const u16* __restrict__ A, const u16* __restrict__ Bt, int mt, int nt, char* lds) {
;     ...
;       } else if (EPI == 1) {
;         float* PRE = (float*)(p.ws + OFF_P);
;         const int v = m0 < NCTX ? 1 : 0;
;         const float g = modp(p, layer, v)[4096 + gc];
; #pragma unroll
;         for (int e = 0; e < 16; ++e) {
;           const int gr = grb + crow(e, h);
;           float xin;
;           if (layer == 0) xin = (gr < NCTX) ? p.ctx[(size_t)gr * DM + gc] : p.x[(size_t)(gr - NCTX) * DM + gc];
;           else xin = ((const float*)(p.ws + OFF_XRES))[(size_t)gr * LDF + gc];
;           PRE[(size_t)gr * LDF + gc] = ALPHA * xin + (DBG_NOATTN ? 0.f : g * acc[i][j][e]);
;         }
	v_pk_mul_f32 v[72:73], v[130:131], v[66:67]
	s_nop 0
	v_add_f32_e32 v48, v72, v73
	global_store_dword v[70:71], v48, off
	v_add_u32_e32 v70, 0xffffff21, v134
	s_and_saveexec_b64 s[6:7], s[4:5]
	s_xor_b64 s[4:5], exec, s[6:7]
	v_mov_b32_e32 v71, v129
	v_lshlrev_b64 v[72:73], 13, v[70:71]
	v_lshl_add_u64 v[72:73], v[80:81], 0, v[72:73]
	v_mov_b32_e32 v69, v129
	s_andn2_saveexec_b64 s[4:5], s[4:5]
	v_ashrrev_i32_e32 v69, 31, v68
	v_lshlrev_b64 v[72:73], 13, v[68:69]
	v_lshl_add_u64 v[72:73], v[82:83], 0, v[72:73]
	s_or_b64 exec, exec, s[4:5]
	global_load_dword v67, v[72:73], off
	v_mov_b32_e32 v130, v49
	v_mul_lo_u32 v71, v69, s89
	v_mad_u64_u32 v[72:73], s[4:5], v68, s89, v[74:75]
	v_or_b32_e32 v48, 34, v134
	v_add_u32_e32 v73, v71, v73
	v_cmp_gt_i32_e64 s[4:5], s83, v48
	v_cmp_lt_i32_e64 s[6:7], s88, v48
	s_waitcnt vmcnt(0)
	v_pk_mul_f32 v[76:77], v[130:131], v[66:67]
	s_nop 0
	v_add_f32_e32 v49, v76, v77
	global_store_dword v[72:73], v49, off
	v_add_u32_e32 v72, 0xffffff22, v134
	s_and_saveexec_b64 s[8:9], s[6:7]
	s_xor_b64 s[6:7], exec, s[8:9]
	v_mov_b32_e32 v73, v129
	v_lshlrev_b64 v[76:77], 13, v[72:73]
	v_lshl_add_u64 v[76:77], v[80:81], 0, v[76:77]
	v_mov_b32_e32 v49, v129
	s_andn2_saveexec_b64 s[6:7], s[6:7]
	v_ashrrev_i32_e32 v49, 31, v48
	v_lshlrev_b64 v[76:77], 13, v[48:49]
	v_lshl_add_u64 v[76:77], v[82:83], 0, v[76:77]
	s_or_b64 exec, exec, s[6:7]
	global_load_dword v67, v[76:77], off
	v_mov_b32_e32 v130, v50
	v_mul_lo_u32 v73, v49, s89
	v_mad_u64_u32 v[78:79], s[6:7], v48, s89, v[74:75]
	v_or_b32_e32 v76, 35, v134
	v_add_u32_e32 v79, v73, v79
	v_cmp_gt_i32_e64 s[6:7], s83, v76
	v_cmp_lt_i32_e64 s[8:9], s88, v76
	s_waitcnt vmcnt(0)
	v_pk_mul_f32 v[84:85], v[130:131], v[66:67]
	s_nop 0
	v_add_f32_e32 v50, v84, v85
	global_store_dword v[78:79], v50, off
	v_add_u32_e32 v78, 0xffffff23, v134
	s_and_saveexec_b64 s[10:11], s[8:9]
	s_xor_b64 s[8:9], exec, s[10:11]
	v_mov_b32_e32 v79, v129
	v_lshlrev_b64 v[84:85], 13, v[78:79]
	v_lshl_add_u64 v[84:85], v[80:81], 0, v[84:85]
	v_mov_b32_e32 v77, v129
	s_andn2_saveexec_b64 s[8:9], s[8:9]
	v_ashrrev_i32_e32 v77, 31, v76
	v_lshlrev_b64 v[84:85], 13, v[76:77]
	v_lshl_add_u64 v[84:85], v[82:83], 0, v[84:85]
	s_or_b64 exec, exec, s[8:9]
	global_load_dword v67, v[84:85], off
	v_mov_b32_e32 v130, v51
	v_mul_lo_u32 v79, v77, s89
	v_mad_u64_u32 v[84:85], s[8:9], v76, s89, v[74:75]
	v_or_b32_e32 v50, 40, v134
	v_add_u32_e32 v85, v79, v85
	v_cmp_gt_i32_e64 s[8:9], s83, v50
	v_cmp_lt_i32_e64 s[10:11], s88, v50
	s_waitcnt vmcnt(0)
	v_pk_mul_f32 v[86:87], v[130:131], v[66:67]
	s_nop 0
	v_add_f32_e32 v51, v86, v87
	global_store_dword v[84:85], v51, off
	v_add_u32_e32 v84, 0xffffff28, v134
	s_and_saveexec_b64 s[12:13], s[10:11]
	s_xor_b64 s[10:11], exec, s[12:13]
	v_mov_b32_e32 v85, v129
	v_lshlrev_b64 v[86:87], 13, v[84:85]
	v_lshl_add_u64 v[86:87], v[80:81], 0, v[86:87]
	v_mov_b32_e32 v51, v129
	s_andn2_saveexec_b64 s[10:11], s[10:11]
	v_ashrrev_i32_e32 v51, 31, v50
	v_lshlrev_b64 v[86:87], 13, v[50:51]
	v_lshl_add_u64 v[86:87], v[82:83], 0, v[86:87]
	s_or_b64 exec, exec, s[10:11]
	global_load_dword v67, v[86:87], off
	v_mov_b32_e32 v130, v52
	v_mul_lo_u32 v85, v51, s89
	v_mad_u64_u32 v[88:89], s[10:11], v50, s89, v[74:75]
	v_or_b32_e32 v86, 41, v134
	v_add_u32_e32 v89, v85, v89
	v_cmp_gt_i32_e64 s[10:11], s83, v86
	v_cmp_lt_i32_e64 s[12:13], s88, v86
	s_waitcnt vmcnt(0)
	v_pk_mul_f32 v[90:91], v[130:131], v[66:67]
	s_nop 0
	v_add_f32_e32 v52, v90, v91
	global_store_dword v[88:89], v52, off
	v_add_u32_e32 v88, 0xffffff29, v134
	s_and_saveexec_b64 s[14:15], s[12:13]
	s_xor_b64 s[12:13], exec, s[14:15]
	v_mov_b32_e32 v89, v129
	v_lshlrev_b64 v[90:91], 13, v[88:89]
	v_lshl_add_u64 v[90:91], v[80:81], 0, v[90:91]
	v_mov_b32_e32 v87, v129
	s_andn2_saveexec_b64 s[12:13], s[12:13]
	v_ashrrev_i32_e32 v87, 31, v86
	v_lshlrev_b64 v[90:91], 13, v[86:87]
	v_lshl_add_u64 v[90:91], v[82:83], 0, v[90:91]
	s_or_b64 exec, exec, s[12:13]
	global_load_dword v67, v[90:91], off
	v_mov_b32_e32 v130, v53
	v_mul_lo_u32 v89, v87, s89
	v_mad_u64_u32 v[90:91], s[12:13], v86, s89, v[74:75]
	v_or_b32_e32 v52, 42, v134
	v_add_u32_e32 v91, v89, v91
	v_cmp_gt_i32_e64 s[12:13], s83, v52
	v_cmp_lt_i32_e64 s[14:15], s88, v52
	s_waitcnt vmcnt(0)
	v_pk_mul_f32 v[92:93], v[130:131], v[66:67]
	s_nop 0
	v_add_f32_e32 v53, v92, v93
	global_store_dword v[90:91], v53, off
	v_add_u32_e32 v90, 0xffffff2a, v134
	s_and_saveexec_b64 s[16:17], s[14:15]
	s_xor_b64 s[14:15], exec, s[16:17]
	v_mov_b32_e32 v91, v129
	v_lshlrev_b64 v[92:93], 13, v[90:91]
	v_lshl_add_u64 v[92:93], v[80:81], 0, v[92:93]
	v_mov_b32_e32 v53, v129
	s_andn2_saveexec_b64 s[14:15], s[14:15]
	v_ashrrev_i32_e32 v53, 31, v52
	v_lshlrev_b64 v[92:93], 13, v[52:53]
	v_lshl_add_u64 v[92:93], v[82:83], 0, v[92:93]
	s_or_b64 exec, exec, s[14:15]
	global_load_dword v67, v[92:93], off
	v_mov_b32_e32 v130, v54
	v_mul_lo_u32 v91, v53, s89
	v_mad_u64_u32 v[94:95], s[14:15], v52, s89, v[74:75]
	v_or_b32_e32 v92, 43, v134
	v_add_u32_e32 v95, v91, v95
	v_cmp_gt_i32_e64 s[14:15], s83, v92
	v_cmp_lt_i32_e64 s[16:17], s88, v92
	s_waitcnt vmcnt(0)
	v_pk_mul_f32 v[96:97], v[130:131], v[66:67]
	s_nop 0
	v_add_f32_e32 v54, v96, v97
	global_store_dword v[94:95], v54, off
	v_add_u32_e32 v94, 0xffffff2b, v134
	s_and_saveexec_b64 s[18:19], s[16:17]
	s_xor_b64 s[16:17], exec, s[18:19]
	v_mov_b32_e32 v95, v129
	v_lshlrev_b64 v[96:97], 13, v[94:95]
	v_lshl_add_u64 v[96:97], v[80:81], 0, v[96:97]
	v_mov_b32_e32 v93, v129
	s_andn2_saveexec_b64 s[16:17], s[16:17]
	v_ashrrev_i32_e32 v93, 31, v92
	v_lshlrev_b64 v[96:97], 13, v[92:93]
	v_lshl_add_u64 v[96:97], v[82:83], 0, v[96:97]
	s_or_b64 exec, exec, s[16:17]
	global_load_dword v67, v[96:97], off
	v_mov_b32_e32 v130, v55
	v_mul_lo_u32 v95, v93, s89
	v_mad_u64_u32 v[96:97], s[16:17], v92, s89, v[74:75]
	v_or_b32_e32 v54, 48, v134
	v_add_u32_e32 v97, v95, v97
	v_cmp_gt_i32_e64 s[16:17], s83, v54
	v_cmp_lt_i32_e64 s[18:19], s88, v54
	s_waitcnt vmcnt(0)
; DI int crow(int i, int h) { return (i & 3) + 8 * (i >> 2) + 4 * h; }
; DI const float* modp(const Params& p, int layer, int v) { return (const float*)(p.ws + OFF_MOD) + (size_t)(layer * 2 + v) * 12288; }
; template <int EPI>
; __device__ __forceinline__ void gemm_tile(const Params& p, int layer, const u16* __restrict__ A, const u16* __restrict__ Bt, int mt, int nt, char* lds) {
;     ...
;       } else if (EPI == 1) {
;         float* PRE = (float*)(p.ws + OFF_P);
;         const int v = m0 < NCTX ? 1 : 0;
;         const float g = modp(p, layer, v)[4096 + gc];
; #pragma unroll
;         for (int e = 0; e < 16; ++e) {
;           const int gr = grb + crow(e, h);
;           float xin;
;           if (layer == 0) xin = (gr < NCTX) ? p.ctx[(size_t)gr * DM + gc] : p.x[(size_t)(gr - NCTX) * DM + gc];
;           else xin = ((const float*)(p.ws + OFF_XRES))[(size_t)gr * LDF + gc];
;           PRE[(size_t)gr * LDF + gc] = ALPHA * xin + (DBG_NOATTN ? 0.f : g * acc[i][j][e]);
;         }
	v_pk_mul_f32 v[98:99], v[130:131], v[66:67]
	s_nop 0
	v_add_f32_e32 v55, v98, v99
	global_store_dword v[96:97], v55, off
	v_add_u32_e32 v96, 0xffffff30, v134
	s_and_saveexec_b64 s[20:21], s[18:19]
	s_xor_b64 s[18:19], exec, s[20:21]
	v_mov_b32_e32 v97, v129
	v_lshlrev_b64 v[98:99], 13, v[96:97]
	v_lshl_add_u64 v[98:99], v[80:81], 0, v[98:99]
	v_mov_b32_e32 v55, v129
	s_andn2_saveexec_b64 s[18:19], s[18:19]
	v_ashrrev_i32_e32 v55, 31, v54
	v_lshlrev_b64 v[98:99], 13, v[54:55]
	v_lshl_add_u64 v[98:99], v[82:83], 0, v[98:99]
	s_or_b64 exec, exec, s[18:19]
	global_load_dword v67, v[98:99], off
	v_mov_b32_e32 v130, v56
	v_mul_lo_u32 v97, v55, s89
	v_mad_u64_u32 v[100:101], s[18:19], v54, s89, v[74:75]
	v_or_b32_e32 v98, 49, v134
	v_add_u32_e32 v101, v97, v101
	v_cmp_gt_i32_e64 s[18:19], s83, v98
	v_cmp_lt_i32_e64 s[20:21], s88, v98
	s_waitcnt vmcnt(0)
	v_pk_mul_f32 v[102:103], v[130:131], v[66:67]
	s_nop 0
	v_add_f32_e32 v56, v102, v103
	global_store_dword v[100:101], v56, off
	v_add_u32_e32 v100, 0xffffff31, v134
	s_and_saveexec_b64 s[22:23], s[20:21]
	s_xor_b64 s[20:21], exec, s[22:23]
	v_mov_b32_e32 v101, v129
	v_lshlrev_b64 v[102:103], 13, v[100:101]
	v_lshl_add_u64 v[102:103], v[80:81], 0, v[102:103]
	v_mov_b32_e32 v99, v129
	s_andn2_saveexec_b64 s[20:21], s[20:21]
	v_ashrrev_i32_e32 v99, 31, v98
	v_lshlrev_b64 v[102:103], 13, v[98:99]
	v_lshl_add_u64 v[102:103], v[82:83], 0, v[102:103]
	s_or_b64 exec, exec, s[20:21]
	global_load_dword v67, v[102:103], off
	v_mov_b32_e32 v130, v57
	v_mul_lo_u32 v101, v99, s89
	v_mad_u64_u32 v[102:103], s[20:21], v98, s89, v[74:75]
	v_or_b32_e32 v56, 50, v134
	v_add_u32_e32 v103, v101, v103
	v_cmp_gt_i32_e64 s[20:21], s83, v56
	v_cmp_lt_i32_e64 s[22:23], s88, v56
	s_waitcnt vmcnt(0)
	v_pk_mul_f32 v[104:105], v[130:131], v[66:67]
	s_nop 0
	v_add_f32_e32 v57, v104, v105
	global_store_dword v[102:103], v57, off
	v_add_u32_e32 v102, 0xffffff32, v134
	s_and_saveexec_b64 s[24:25], s[22:23]
	s_xor_b64 s[22:23], exec, s[24:25]
	v_mov_b32_e32 v103, v129
	v_lshlrev_b64 v[104:105], 13, v[102:103]
	v_lshl_add_u64 v[104:105], v[80:81], 0, v[104:105]
	v_mov_b32_e32 v57, v129
	s_andn2_saveexec_b64 s[22:23], s[22:23]
	v_ashrrev_i32_e32 v57, 31, v56
	v_lshlrev_b64 v[104:105], 13, v[56:57]
	v_lshl_add_u64 v[104:105], v[82:83], 0, v[104:105]
	s_or_b64 exec, exec, s[22:23]
	global_load_dword v67, v[104:105], off
	v_mov_b32_e32 v130, v58
	v_mul_lo_u32 v103, v57, s89
	v_mad_u64_u32 v[106:107], s[22:23], v56, s89, v[74:75]
	v_or_b32_e32 v104, 51, v134
	v_add_u32_e32 v107, v103, v107
	v_cmp_gt_i32_e64 s[22:23], s83, v104
	v_cmp_lt_i32_e64 s[24:25], s88, v104
	s_waitcnt vmcnt(0)
	v_pk_mul_f32 v[108:109], v[130:131], v[66:67]
	s_nop 0
	v_add_f32_e32 v58, v108, v109
	global_store_dword v[106:107], v58, off
	v_add_u32_e32 v106, 0xffffff33, v134
	s_and_saveexec_b64 s[26:27], s[24:25]
	s_xor_b64 s[24:25], exec, s[26:27]
	v_mov_b32_e32 v107, v129
	v_lshlrev_b64 v[108:109], 13, v[106:107]
	v_lshl_add_u64 v[108:109], v[80:81], 0, v[108:109]
	v_mov_b32_e32 v105, v129
	s_andn2_saveexec_b64 s[24:25], s[24:25]
	v_ashrrev_i32_e32 v105, 31, v104
	v_lshlrev_b64 v[108:109], 13, v[104:105]
	v_lshl_add_u64 v[108:109], v[82:83], 0, v[108:109]
	s_or_b64 exec, exec, s[24:25]
	global_load_dword v67, v[108:109], off
	v_mov_b32_e32 v130, v59
	v_mul_lo_u32 v107, v105, s89
	v_mad_u64_u32 v[108:109], s[24:25], v104, s89, v[74:75]
	v_or_b32_e32 v58, 56, v134
	v_add_u32_e32 v109, v107, v109
	v_cmp_gt_i32_e64 s[24:25], s83, v58
	v_cmp_lt_i32_e64 s[26:27], s88, v58
	s_waitcnt vmcnt(0)
	v_pk_mul_f32 v[110:111], v[130:131], v[66:67]
	s_nop 0
	v_add_f32_e32 v59, v110, v111
	global_store_dword v[108:109], v59, off
	v_add_u32_e32 v108, 0xffffff38, v134
	s_and_saveexec_b64 s[28:29], s[26:27]
	s_xor_b64 s[26:27], exec, s[28:29]
	v_mov_b32_e32 v109, v129
	v_lshlrev_b64 v[110:111], 13, v[108:109]
	v_lshl_add_u64 v[110:111], v[80:81], 0, v[110:111]
	v_mov_b32_e32 v59, v129
	s_andn2_saveexec_b64 s[26:27], s[26:27]
	v_ashrrev_i32_e32 v59, 31, v58
	v_lshlrev_b64 v[110:111], 13, v[58:59]
	v_lshl_add_u64 v[110:111], v[82:83], 0, v[110:111]
	s_or_b64 exec, exec, s[26:27]
	global_load_dword v67, v[110:111], off
	v_mov_b32_e32 v130, v60
	v_mul_lo_u32 v109, v59, s89
	v_mad_u64_u32 v[112:113], s[26:27], v58, s89, v[74:75]
	v_or_b32_e32 v110, 57, v134
	v_add_u32_e32 v113, v109, v113
	v_cmp_gt_i32_e64 s[26:27], s83, v110
	v_cmp_lt_i32_e64 s[28:29], s88, v110
	s_waitcnt vmcnt(0)
	v_pk_mul_f32 v[114:115], v[130:131], v[66:67]
	s_nop 0
	v_add_f32_e32 v60, v114, v115
	global_store_dword v[112:113], v60, off
	v_add_u32_e32 v112, 0xffffff39, v134
	s_and_saveexec_b64 s[30:31], s[28:29]
	s_xor_b64 s[28:29], exec, s[30:31]
	v_mov_b32_e32 v113, v129
	v_lshlrev_b64 v[114:115], 13, v[112:113]
	v_lshl_add_u64 v[114:115], v[80:81], 0, v[114:115]
	v_mov_b32_e32 v111, v129
	s_andn2_saveexec_b64 s[28:29], s[28:29]
	v_ashrrev_i32_e32 v111, 31, v110
	v_lshlrev_b64 v[114:115], 13, v[110:111]
	v_lshl_add_u64 v[114:115], v[82:83], 0, v[114:115]
	s_or_b64 exec, exec, s[28:29]
	global_load_dword v67, v[114:115], off
	v_mov_b32_e32 v130, v61
	v_mul_lo_u32 v113, v111, s89
	v_mad_u64_u32 v[60:61], s[28:29], v110, s89, v[74:75]
	v_or_b32_e32 v114, 58, v134
	v_add_u32_e32 v61, v113, v61
	v_cmp_gt_i32_e64 s[28:29], s83, v114
	v_cmp_lt_i32_e64 s[30:31], s88, v114
	s_waitcnt vmcnt(0)
	v_pk_mul_f32 v[116:117], v[130:131], v[66:67]
	s_nop 0
	v_add_f32_e32 v67, v116, v117
	v_add_u32_e32 v116, 0xffffff3a, v134
	global_store_dword v[60:61], v67, off
	s_and_saveexec_b64 s[36:37], s[30:31]
	s_xor_b64 s[30:31], exec, s[36:37]
	v_mov_b32_e32 v117, v129
	v_lshlrev_b64 v[60:61], 13, v[116:117]
	v_lshl_add_u64 v[60:61], v[80:81], 0, v[60:61]
	v_mov_b32_e32 v115, v129
	s_andn2_saveexec_b64 s[30:31], s[30:31]
	v_ashrrev_i32_e32 v115, 31, v114
	v_lshlrev_b64 v[60:61], 13, v[114:115]
	v_lshl_add_u64 v[60:61], v[82:83], 0, v[60:61]
	s_or_b64 exec, exec, s[30:31]
	global_load_dword v67, v[60:61], off
	v_mov_b32_e32 v130, v62
	v_mul_lo_u32 v117, v115, s89
	v_or_b32_e32 v118, 59, v134
	v_cmp_lt_i32_e64 s[36:37], s88, v118
	v_add_u32_e32 v120, 0xffffff3b, v134
	s_waitcnt vmcnt(0)
	v_pk_mul_f32 v[60:61], v[130:131], v[66:67]
	s_nop 0
	v_add_f32_e32 v62, v60, v61
	v_mad_u64_u32 v[60:61], s[30:31], v114, s89, v[74:75]
	v_add_u32_e32 v61, v117, v61
	v_cmp_gt_i32_e64 s[30:31], s83, v118
	global_store_dword v[60:61], v62, off
	s_and_saveexec_b64 s[90:91], s[36:37]
	s_xor_b64 s[36:37], exec, s[90:91]
	v_mov_b32_e32 v121, v129
	v_lshlrev_b64 v[60:61], 13, v[120:121]
	v_lshl_add_u64 v[60:61], v[80:81], 0, v[60:61]
	v_mov_b32_e32 v119, v129
	s_andn2_saveexec_b64 s[36:37], s[36:37]
	s_cbranch_execz .LBB0_1626
	v_ashrrev_i32_e32 v119, 31, v118
	v_lshlrev_b64 v[60:61], 13, v[118:119]
	v_lshl_add_u64 v[60:61], v[82:83], 0, v[60:61]
	v_mov_b32_e32 v121, v129
	s_branch .LBB0_1626

; template <int EPI>
; __device__ __forceinline__ void gemm_tile(const Params& p, int layer, const u16* __restrict__ A, const u16* __restrict__ Bt, int mt, int nt, char* lds) {
;     ...
;   for (int kt = 0; kt < NK - 1; ++kt) {
;     G_SLAB(true, kt + 1)
;     __syncthreads();
;     G_WRITE();
;     __syncthreads();
;   }
.LBB0_1871:
	ds_read_b128 v[146:149], v130
	ds_read_b128 v[150:153], v130 offset:4608
	ds_read_b128 v[154:157], v131 offset:18432
	ds_read_b128 v[158:161], v131 offset:23040
	ds_read_b128 v[162:165], v131 offset:27648
	ds_read_b128 v[166:169], v131 offset:32256
	ds_read_b128 v[170:173], v130 offset:32
	ds_read_b128 v[174:177], v130 offset:4640
	ds_read_b128 v[178:181], v131 offset:18464
	ds_read_b128 v[182:185], v131 offset:23072
	ds_read_b128 v[186:189], v131 offset:27680
	ds_read_b128 v[190:193], v131 offset:32288
	s_waitcnt lgkmcnt(9)
	v_mfma_f32_32x32x16_bf16 v[112:127], v[146:149], v[154:157], v[112:127]
	s_waitcnt lgkmcnt(8)
	v_mfma_f32_32x32x16_bf16 v[96:111], v[146:149], v[158:161], v[96:111]
	s_waitcnt lgkmcnt(7)
	v_mfma_f32_32x32x16_bf16 v[80:95], v[146:149], v[162:165], v[80:95]
	s_waitcnt lgkmcnt(6)
	v_mfma_f32_32x32x16_bf16 v[64:79], v[146:149], v[166:169], v[64:79]
	v_lshl_add_u64 v[212:213], v[134:135], 0, s[18:19]
	v_add_co_u32_e32 v146, vcc, s28, v212
	v_lshl_add_u64 v[228:229], v[136:137], 0, s[18:19]
	s_nop 0
	v_addc_co_u32_e32 v147, vcc, 0, v213, vcc
	v_add_co_u32_e32 v194, vcc, s29, v228
	s_nop 1
	v_addc_co_u32_e32 v195, vcc, 0, v229, vcc
	global_load_dwordx4 v[146:149], v[146:147], off offset:384
	s_nop 0
	global_load_dwordx4 v[194:197], v[194:195], off offset:128
	v_mfma_f32_32x32x16_bf16 v[48:63], v[150:153], v[154:157], v[48:63]
	v_mfma_f32_32x32x16_bf16 v[32:47], v[150:153], v[158:161], v[32:47]
	v_mfma_f32_32x32x16_bf16 v[16:31], v[150:153], v[162:165], v[16:31]
	v_mfma_f32_32x32x16_bf16 v[0:15], v[150:153], v[166:169], v[0:15]
	v_add_co_u32_e32 v150, vcc, s30, v228
	s_nop 1
	v_addc_co_u32_e32 v151, vcc, 0, v229, vcc
	global_load_dwordx4 v[150:153], v[150:151], off offset:128
	ds_read_b128 v[154:157], v130 offset:64
	ds_read_b128 v[158:161], v130 offset:4672
	ds_read_b128 v[162:165], v131 offset:18496
	ds_read_b128 v[166:169], v131 offset:23104
	ds_read_b128 v[198:201], v131 offset:27712
	ds_read_b128 v[202:205], v131 offset:32320
	s_waitcnt lgkmcnt(9)
	v_mfma_f32_32x32x16_bf16 v[112:127], v[170:173], v[178:181], v[112:127]
	s_waitcnt lgkmcnt(8)
	v_mfma_f32_32x32x16_bf16 v[96:111], v[170:173], v[182:185], v[96:111]
	s_waitcnt lgkmcnt(7)
	v_mfma_f32_32x32x16_bf16 v[80:95], v[170:173], v[186:189], v[80:95]
	s_waitcnt lgkmcnt(6)
	v_mfma_f32_32x32x16_bf16 v[64:79], v[170:173], v[190:193], v[64:79]
	v_add_co_u32_e32 v170, vcc, s31, v212
	s_nop 1
	v_addc_co_u32_e32 v171, vcc, 0, v213, vcc
	v_add_co_u32_e32 v206, vcc, s36, v228
	s_nop 1
	v_addc_co_u32_e32 v207, vcc, 0, v229, vcc
	global_load_dwordx4 v[170:173], v[170:171], off offset:384
	s_nop 0
	global_load_dwordx4 v[206:209], v[206:207], off offset:128
	v_mfma_f32_32x32x16_bf16 v[48:63], v[174:177], v[178:181], v[48:63]
	v_mfma_f32_32x32x16_bf16 v[32:47], v[174:177], v[182:185], v[32:47]
	v_mfma_f32_32x32x16_bf16 v[16:31], v[174:177], v[186:189], v[16:31]
	v_mfma_f32_32x32x16_bf16 v[0:15], v[174:177], v[190:193], v[0:15]
	v_add_co_u32_e32 v174, vcc, s37, v228
	s_nop 1
	v_addc_co_u32_e32 v175, vcc, 0, v229, vcc
	global_load_dwordx4 v[174:177], v[174:175], off offset:128
	ds_read_b128 v[178:181], v130 offset:96
	ds_read_b128 v[182:185], v130 offset:4704
	ds_read_b128 v[186:189], v131 offset:18528
	ds_read_b128 v[190:193], v131 offset:23136
	ds_read_b128 v[216:219], v131 offset:27744
	ds_read_b128 v[220:223], v131 offset:32352
	s_waitcnt lgkmcnt(9)
	v_mfma_f32_32x32x16_bf16 v[112:127], v[154:157], v[162:165], v[112:127]
	s_waitcnt lgkmcnt(8)
	v_mfma_f32_32x32x16_bf16 v[96:111], v[154:157], v[166:169], v[96:111]
	s_waitcnt lgkmcnt(7)
	v_mfma_f32_32x32x16_bf16 v[80:95], v[154:157], v[198:201], v[80:95]
	s_waitcnt lgkmcnt(6)
	v_mfma_f32_32x32x16_bf16 v[64:79], v[154:157], v[202:205], v[64:79]
	v_add_co_u32_e32 v154, vcc, s48, v212
	s_nop 1
	v_addc_co_u32_e32 v155, vcc, 0, v213, vcc
	v_add_co_u32_e32 v224, vcc, s49, v228
	s_nop 1
	v_addc_co_u32_e32 v225, vcc, 0, v229, vcc
	global_load_dwordx4 v[154:157], v[154:155], off offset:384
	s_nop 0
	global_load_dwordx4 v[224:227], v[224:225], off offset:128
	v_mfma_f32_32x32x16_bf16 v[48:63], v[158:161], v[162:165], v[48:63]
	v_mfma_f32_32x32x16_bf16 v[32:47], v[158:161], v[166:169], v[32:47]
	v_mfma_f32_32x32x16_bf16 v[16:31], v[158:161], v[198:201], v[16:31]
	v_mfma_f32_32x32x16_bf16 v[0:15], v[158:161], v[202:205], v[0:15]
	v_add_co_u32_e32 v158, vcc, s50, v228
	s_nop 1
	v_addc_co_u32_e32 v159, vcc, 0, v229, vcc
	global_load_dwordx4 v[158:161], v[158:159], off offset:128
	s_waitcnt lgkmcnt(3)
	v_mfma_f32_32x32x16_bf16 v[112:127], v[178:181], v[186:189], v[112:127]
	s_waitcnt lgkmcnt(2)
	v_mfma_f32_32x32x16_bf16 v[96:111], v[178:181], v[190:193], v[96:111]
	s_waitcnt lgkmcnt(1)
	v_mfma_f32_32x32x16_bf16 v[80:95], v[178:181], v[216:219], v[80:95]
	s_waitcnt lgkmcnt(0)
	v_mfma_f32_32x32x16_bf16 v[64:79], v[178:181], v[220:223], v[64:79]
	v_add_co_u32_e32 v162, vcc, s51, v212
	s_nop 1
	v_addc_co_u32_e32 v163, vcc, 0, v213, vcc
	v_add_co_u32_e32 v166, vcc, s52, v228
	s_nop 1
	v_addc_co_u32_e32 v167, vcc, 0, v229, vcc
	global_load_dwordx4 v[162:165], v[162:163], off offset:384
	s_nop 0
	global_load_dwordx4 v[166:169], v[166:167], off offset:128
	v_mfma_f32_32x32x16_bf16 v[48:63], v[182:185], v[186:189], v[48:63]
	v_mfma_f32_32x32x16_bf16 v[32:47], v[182:185], v[190:193], v[32:47]
	v_mfma_f32_32x32x16_bf16 v[16:31], v[182:185], v[216:219], v[16:31]
	v_mfma_f32_32x32x16_bf16 v[0:15], v[182:185], v[220:223], v[0:15]
	v_add_co_u32_e32 v178, vcc, s53, v228
	s_nop 1
	v_addc_co_u32_e32 v179, vcc, 0, v229, vcc
	global_load_dwordx4 v[178:181], v[178:179], off offset:128
	s_add_u32 s18, s18, 0x80
	s_addc_u32 s19, s19, 0
	s_cmpk_eq_i32 s18, 0xf80
	s_barrier
; template <int EPI>
; __device__ __forceinline__ void gemm_tile(const Params& p, int layer, const u16* __restrict__ A, const u16* __restrict__ Bt, int mt, int nt, char* lds) {
;     ...
;   for (int kt = 0; kt < NK - 1; ++kt) {
;     G_SLAB(true, kt + 1)
;     __syncthreads();
;     G_WRITE();
;     __syncthreads();
;   }
;   G_SLAB(false, 0)
;   __syncthreads();
	s_setprio 0
	s_waitcnt vmcnt(11)
	ds_write_b128 v132, v[146:149]
	s_waitcnt vmcnt(8)
	ds_write_b128 v132, v[170:173] offset:4608
	s_waitcnt vmcnt(5)
	ds_write_b128 v132, v[154:157] offset:9216
	s_waitcnt vmcnt(2)
	ds_write_b128 v132, v[162:165] offset:13824
	ds_write_b128 v132, v[194:197] offset:18432
	ds_write_b128 v132, v[206:209] offset:23040
	ds_write_b128 v132, v[224:227] offset:27648
	s_waitcnt vmcnt(1)
	ds_write_b128 v132, v[166:169] offset:32256
	ds_write_b128 v132, v[150:153] offset:36864
	ds_write_b128 v132, v[174:177] offset:41472
	ds_write_b128 v132, v[158:161] offset:46080
	s_waitcnt vmcnt(0)
	ds_write_b128 v132, v[178:181] offset:50688
	s_waitcnt lgkmcnt(0)
	s_setprio 1
	s_barrier
	s_cbranch_scc0 .LBB0_1871
	ds_read_b128 v[132:135], v130
	ds_read_b128 v[146:149], v130 offset:4608
	ds_read_b128 v[150:153], v131 offset:18432
	ds_read_b128 v[154:157], v131 offset:23040
	ds_read_b128 v[158:161], v131 offset:27648
	ds_read_b128 v[162:165], v131 offset:32256
	ds_read_b128 v[166:169], v130 offset:32
	ds_read_b128 v[170:173], v130 offset:4640
	ds_read_b128 v[174:177], v131 offset:18464
	ds_read_b128 v[178:181], v131 offset:23072
	ds_read_b128 v[182:185], v131 offset:27680
	ds_read_b128 v[186:189], v131 offset:32288
	s_waitcnt lgkmcnt(7)
	v_mfma_f32_32x32x16_bf16 v[80:95], v[132:135], v[158:161], v[80:95]
	s_waitcnt lgkmcnt(6)
	v_mfma_f32_32x32x16_bf16 v[64:79], v[132:135], v[162:165], v[64:79]
	v_mfma_f32_32x32x16_bf16 v[112:127], v[132:135], v[150:153], v[112:127]
	v_mfma_f32_32x32x16_bf16 v[96:111], v[132:135], v[154:157], v[96:111]
	v_mfma_f32_32x32x16_bf16 v[48:63], v[146:149], v[150:153], v[48:63]
	v_mfma_f32_32x32x16_bf16 v[32:47], v[146:149], v[154:157], v[32:47]
	v_mfma_f32_32x32x16_bf16 v[16:31], v[146:149], v[158:161], v[16:31]
	v_mfma_f32_32x32x16_bf16 v[0:15], v[146:149], v[162:165], v[0:15]
	ds_read_b128 v[132:135], v130 offset:64
	ds_read_b128 v[146:149], v130 offset:4672
	ds_read_b128 v[150:153], v131 offset:18496
	ds_read_b128 v[154:157], v131 offset:23104
	ds_read_b128 v[158:161], v131 offset:27712
	ds_read_b128 v[162:165], v131 offset:32320
	s_waitcnt lgkmcnt(7)
	v_mfma_f32_32x32x16_bf16 v[80:95], v[166:169], v[182:185], v[80:95]
	s_waitcnt lgkmcnt(6)
	v_mfma_f32_32x32x16_bf16 v[64:79], v[166:169], v[186:189], v[64:79]
	v_mfma_f32_32x32x16_bf16 v[112:127], v[166:169], v[174:177], v[112:127]
	v_mfma_f32_32x32x16_bf16 v[96:111], v[166:169], v[178:181], v[96:111]
	v_mfma_f32_32x32x16_bf16 v[48:63], v[170:173], v[174:177], v[48:63]
	v_mfma_f32_32x32x16_bf16 v[32:47], v[170:173], v[178:181], v[32:47]
	v_mfma_f32_32x32x16_bf16 v[16:31], v[170:173], v[182:185], v[16:31]
	v_mfma_f32_32x32x16_bf16 v[0:15], v[170:173], v[186:189], v[0:15]
	ds_read_b128 v[166:169], v130 offset:96
	ds_read_b128 v[170:173], v130 offset:4704
	ds_read_b128 v[174:177], v131 offset:18528
	ds_read_b128 v[178:181], v131 offset:23136
	ds_read_b128 v[182:185], v131 offset:27744
	ds_read_b128 v[186:189], v131 offset:32352
	s_waitcnt lgkmcnt(7)
	v_mfma_f32_32x32x16_bf16 v[80:95], v[132:135], v[158:161], v[80:95]
	s_waitcnt lgkmcnt(6)
	v_mfma_f32_32x32x16_bf16 v[64:79], v[132:135], v[162:165], v[64:79]
	v_mfma_f32_32x32x16_bf16 v[112:127], v[132:135], v[150:153], v[112:127]
	v_mfma_f32_32x32x16_bf16 v[96:111], v[132:135], v[154:157], v[96:111]
	v_mfma_f32_32x32x16_bf16 v[48:63], v[146:149], v[150:153], v[48:63]
	v_mfma_f32_32x32x16_bf16 v[32:47], v[146:149], v[154:157], v[32:47]
	v_mfma_f32_32x32x16_bf16 v[16:31], v[146:149], v[158:161], v[16:31]
	v_mfma_f32_32x32x16_bf16 v[0:15], v[146:149], v[162:165], v[0:15]
	s_waitcnt lgkmcnt(1)
	v_mfma_f32_32x32x16_bf16 v[80:95], v[166:169], v[182:185], v[80:95]
	s_waitcnt lgkmcnt(0)
	v_mfma_f32_32x32x16_bf16 v[64:79], v[166:169], v[186:189], v[64:79]
	v_mfma_f32_32x32x16_bf16 v[112:127], v[166:169], v[174:177], v[112:127]
	v_mfma_f32_32x32x16_bf16 v[96:111], v[166:169], v[178:181], v[96:111]
	v_mfma_f32_32x32x16_bf16 v[48:63], v[170:173], v[174:177], v[48:63]
	v_mfma_f32_32x32x16_bf16 v[32:47], v[170:173], v[178:181], v[32:47]
	v_mfma_f32_32x32x16_bf16 v[16:31], v[170:173], v[182:185], v[16:31]
	v_mfma_f32_32x32x16_bf16 v[0:15], v[170:173], v[186:189], v[0:15]
	v_lshl_or_b32 v128, v139, 2, v143
	v_lshlrev_b32_e32 v130, 1, v144
	v_lshlrev_b32_e32 v131, 1, v138
	v_mul_lo_u32 v128, v128, s60
	v_mov_b32_e32 v132, v129
	s_nop 1
	v_cvt_pk_bf16_f32 v112, v112, s0
	v_add3_u32 v128, v130, v131, v128
	s_barrier
; DI u16 f2bf(float a) { return (u16)(pk2(a, 0.f) & 0xffffu); }
; DI int crow(int i, int h) { return (i & 3) + 8 * (i >> 2) + 4 * h; }
; template <int EPI>
; __device__ __forceinline__ void gemm_tile(const Params& p, int layer, const u16* __restrict__ A, const u16* __restrict__ Bt, int mt, int nt, char* lds) {
;     ...
;       } else {
;         u16* Qs = (u16*)lds;
; #pragma unroll
;         for (int e = 0; e < 16; ++e) {
;           const int lr = wr * 64 + i * 32 + crow(e, h);
;           Qs[lr * QLD + wc * 128 + j * 32 + r] = f2bf(acc[i][j][e]);
;         }
;       }
	ds_write_b16 v128, v112
	v_cvt_pk_bf16_f32 v112, v113, s0
	ds_write_b16 v128, v112 offset:528
	v_cvt_pk_bf16_f32 v112, v114, s0
	ds_write_b16 v128, v112 offset:1056
	v_cvt_pk_bf16_f32 v112, v115, s0
	ds_write_b16 v128, v112 offset:1584
	v_cvt_pk_bf16_f32 v112, v116, s0
	ds_write_b16 v128, v112 offset:4224
	v_cvt_pk_bf16_f32 v112, v117, s0
	ds_write_b16 v128, v112 offset:4752
	v_cvt_pk_bf16_f32 v112, v118, s0
	ds_write_b16 v128, v112 offset:5280
	v_cvt_pk_bf16_f32 v112, v119, s0
	ds_write_b16 v128, v112 offset:5808
	v_cvt_pk_bf16_f32 v112, v120, s0
	ds_write_b16 v128, v112 offset:8448
	v_cvt_pk_bf16_f32 v112, v121, s0
	ds_write_b16 v128, v112 offset:8976
	v_cvt_pk_bf16_f32 v112, v122, s0
	ds_write_b16 v128, v112 offset:9504
	v_cvt_pk_bf16_f32 v112, v123, s0
	ds_write_b16 v128, v112 offset:10032
	v_cvt_pk_bf16_f32 v112, v124, s0
	ds_write_b16 v128, v112 offset:12672
	v_cvt_pk_bf16_f32 v112, v125, s0
	ds_write_b16 v128, v112 offset:13200
	v_cvt_pk_bf16_f32 v112, v126, s0
	ds_write_b16 v128, v112 offset:13728
	v_cvt_pk_bf16_f32 v112, v127, s0
	ds_write_b16 v128, v112 offset:14256
	v_mov_b32_e32 v112, v129
	v_cvt_pk_bf16_f32 v96, v96, s0
	ds_write_b16 v128, v96 offset:64
	v_cvt_pk_bf16_f32 v96, v97, s0
	ds_write_b16 v128, v96 offset:592
	v_cvt_pk_bf16_f32 v96, v98, s0
	ds_write_b16 v128, v96 offset:1120
	v_cvt_pk_bf16_f32 v96, v99, s0
	ds_write_b16 v128, v96 offset:1648
	v_cvt_pk_bf16_f32 v96, v100, s0
	ds_write_b16 v128, v96 offset:4288
	v_cvt_pk_bf16_f32 v96, v101, s0
	ds_write_b16 v128, v96 offset:4816
	v_cvt_pk_bf16_f32 v96, v102, s0
	ds_write_b16 v128, v96 offset:5344
	v_cvt_pk_bf16_f32 v96, v103, s0
	ds_write_b16 v128, v96 offset:5872
	v_cvt_pk_bf16_f32 v96, v104, s0
	ds_write_b16 v128, v96 offset:8512
	v_cvt_pk_bf16_f32 v96, v105, s0
	ds_write_b16 v128, v96 offset:9040
	v_cvt_pk_bf16_f32 v96, v106, s0
	ds_write_b16 v128, v96 offset:9568
	v_cvt_pk_bf16_f32 v96, v107, s0
	ds_write_b16 v128, v96 offset:10096
	v_cvt_pk_bf16_f32 v96, v108, s0
	ds_write_b16 v128, v96 offset:12736
	v_cvt_pk_bf16_f32 v96, v109, s0
	ds_write_b16 v128, v96 offset:13264
	v_cvt_pk_bf16_f32 v96, v110, s0
	ds_write_b16 v128, v96 offset:13792
	v_cvt_pk_bf16_f32 v96, v111, s0
	ds_write_b16 v128, v96 offset:14320
	v_mov_b32_e32 v96, v129
	v_cvt_pk_bf16_f32 v80, v80, s0
	ds_write_b16 v128, v80 offset:128
	v_cvt_pk_bf16_f32 v80, v81, s0
	ds_write_b16 v128, v80 offset:656
	v_cvt_pk_bf16_f32 v80, v82, s0
	ds_write_b16 v128, v80 offset:1184
	v_cvt_pk_bf16_f32 v80, v83, s0
	ds_write_b16 v128, v80 offset:1712
	v_cvt_pk_bf16_f32 v80, v84, s0
	ds_write_b16 v128, v80 offset:4352
	v_cvt_pk_bf16_f32 v80, v85, s0
	ds_write_b16 v128, v80 offset:4880
	v_cvt_pk_bf16_f32 v80, v86, s0
	ds_write_b16 v128, v80 offset:5408
	v_cvt_pk_bf16_f32 v80, v87, s0
	ds_write_b16 v128, v80 offset:5936
	v_cvt_pk_bf16_f32 v80, v88, s0
	ds_write_b16 v128, v80 offset:8576
	v_cvt_pk_bf16_f32 v80, v89, s0
	ds_write_b16 v128, v80 offset:9104
	v_cvt_pk_bf16_f32 v80, v90, s0
	ds_write_b16 v128, v80 offset:9632
	v_cvt_pk_bf16_f32 v80, v91, s0
	ds_write_b16 v128, v80 offset:10160
	v_cvt_pk_bf16_f32 v80, v92, s0
	ds_write_b16 v128, v80 offset:12800
	v_cvt_pk_bf16_f32 v80, v93, s0
	ds_write_b16 v128, v80 offset:13328
	v_cvt_pk_bf16_f32 v80, v94, s0
	ds_write_b16 v128, v80 offset:13856
	v_cvt_pk_bf16_f32 v80, v95, s0
	ds_write_b16 v128, v80 offset:14384
	v_mov_b32_e32 v80, v129
	v_cvt_pk_bf16_f32 v64, v64, s0
	ds_write_b16 v128, v64 offset:192
	v_cvt_pk_bf16_f32 v64, v65, s0
	ds_write_b16 v128, v64 offset:720
	v_cvt_pk_bf16_f32 v64, v66, s0
	ds_write_b16 v128, v64 offset:1248
	v_cvt_pk_bf16_f32 v64, v67, s0
	ds_write_b16 v128, v64 offset:1776
	v_cvt_pk_bf16_f32 v64, v68, s0
	ds_write_b16 v128, v64 offset:4416
	v_cvt_pk_bf16_f32 v64, v69, s0
	ds_write_b16 v128, v64 offset:4944
	v_cvt_pk_bf16_f32 v64, v70, s0
	ds_write_b16 v128, v64 offset:5472
	v_cvt_pk_bf16_f32 v64, v71, s0
	ds_write_b16 v128, v64 offset:6000
	v_cvt_pk_bf16_f32 v64, v72, s0
	ds_write_b16 v128, v64 offset:8640
	v_cvt_pk_bf16_f32 v64, v73, s0
	ds_write_b16 v128, v64 offset:9168
	v_cvt_pk_bf16_f32 v64, v74, s0
	ds_write_b16 v128, v64 offset:9696
	v_cvt_pk_bf16_f32 v64, v75, s0
	ds_write_b16 v128, v64 offset:10224
	v_cvt_pk_bf16_f32 v64, v76, s0
	ds_write_b16 v128, v64 offset:12864
	v_cvt_pk_bf16_f32 v64, v77, s0
	ds_write_b16 v128, v64 offset:13392
	v_cvt_pk_bf16_f32 v64, v78, s0
	ds_write_b16 v128, v64 offset:13920
	v_cvt_pk_bf16_f32 v64, v79, s0
	ds_write_b16 v128, v64 offset:14448
	v_mov_b32_e32 v64, v129
	v_cvt_pk_bf16_f32 v48, v48, s0
	ds_write_b16 v128, v48 offset:16896
	v_cvt_pk_bf16_f32 v48, v49, s0
	ds_write_b16 v128, v48 offset:17424
	v_cvt_pk_bf16_f32 v48, v50, s0
	ds_write_b16 v128, v48 offset:17952
	v_cvt_pk_bf16_f32 v48, v51, s0
	ds_write_b16 v128, v48 offset:18480
	v_cvt_pk_bf16_f32 v48, v52, s0
	ds_write_b16 v128, v48 offset:21120
	v_cvt_pk_bf16_f32 v48, v53, s0
	ds_write_b16 v128, v48 offset:21648
	v_cvt_pk_bf16_f32 v48, v54, s0
	ds_write_b16 v128, v48 offset:22176
	v_cvt_pk_bf16_f32 v48, v55, s0
	ds_write_b16 v128, v48 offset:22704
; DI u16 f2bf(float a) { return (u16)(pk2(a, 0.f) & 0xffffu); }
; DI int crow(int i, int h) { return (i & 3) + 8 * (i >> 2) + 4 * h; }
; template <int EPI>
; __device__ __forceinline__ void gemm_tile(const Params& p, int layer, const u16* __restrict__ A, const u16* __restrict__ Bt, int mt, int nt, char* lds) {
;     ...
;       } else {
;         u16* Qs = (u16*)lds;
; #pragma unroll
;         for (int e = 0; e < 16; ++e) {
;           const int lr = wr * 64 + i * 32 + crow(e, h);
;           Qs[lr * QLD + wc * 128 + j * 32 + r] = f2bf(acc[i][j][e]);
;         }
;       }
;     }
;   }
;   if (EPI == 2) {
;     __syncthreads();
;     const u16* Qs = (const u16*)lds;
;     route_task(p, layer, Qs + (wid * 32 + r) * QLD + 8 * h, m0 + wid * 32, nt, r, h);
; __device__ __forceinline__ void route_task(const Params& p, int layer, const u16* qg, int rb, int hd, int r, int h) {
;   const u16* KY = (const u16*)(p.ws + OFF_KEYS);
;   int* EX = (int*)(p.ws + OFF_EXP);
;   float* GT = (float*)(p.ws + OFF_GATE);
;     unsigned top[2][16];
; #pragma unroll
;   for (int ph = 0; ph < 2; ++ph) {
;     bf16x8 qf[8];
; #pragma unroll
;     for (int s = 0; s < 8; ++s) qf[s] = *(const bf16x8*)(qg + ph * 128 + 16 * s);
;     const u16* kg = KY + ((size_t)((layer * 8 + hd) * 2 + ph) * 128 + r) * 128 + 8 * h;
;     unsigned tp[16];
; #pragma unroll
;     for (int jj = 0; jj < 16; ++jj) tp[jj] = 0u;
; #pragma unroll 1
;     for (int n = 0; n < 4; ++n) {
;       f32x16 acc;
; #pragma unroll
;       for (int e = 0; e < 16; ++e) acc[e] = 0.f;
; #pragma unroll
;       for (int s = 0; s < 8; ++s) {
;         bf16x8 kf = *(const bf16x8*)(kg + (size_t)n * 32 * 128 + 16 * s);
	v_cvt_pk_bf16_f32 v48, v56, s0
	ds_write_b16 v128, v48 offset:25344
	v_cvt_pk_bf16_f32 v48, v57, s0
	ds_write_b16 v128, v48 offset:25872
	v_cvt_pk_bf16_f32 v48, v58, s0
	ds_write_b16 v128, v48 offset:26400
	v_cvt_pk_bf16_f32 v48, v59, s0
	ds_write_b16 v128, v48 offset:26928
	v_cvt_pk_bf16_f32 v48, v60, s0
	ds_write_b16 v128, v48 offset:29568
	v_cvt_pk_bf16_f32 v48, v61, s0
	ds_write_b16 v128, v48 offset:30096
	v_cvt_pk_bf16_f32 v48, v62, s0
	ds_write_b16 v128, v48 offset:30624
	v_cvt_pk_bf16_f32 v48, v63, s0
	ds_write_b16 v128, v48 offset:31152
	v_mov_b32_e32 v48, v129
	v_cvt_pk_bf16_f32 v32, v32, s0
	ds_write_b16 v128, v32 offset:16960
	v_cvt_pk_bf16_f32 v32, v33, s0
	ds_write_b16 v128, v32 offset:17488
	v_cvt_pk_bf16_f32 v32, v34, s0
	ds_write_b16 v128, v32 offset:18016
	v_cvt_pk_bf16_f32 v32, v35, s0
	ds_write_b16 v128, v32 offset:18544
	v_cvt_pk_bf16_f32 v32, v36, s0
	ds_write_b16 v128, v32 offset:21184
	v_cvt_pk_bf16_f32 v32, v37, s0
	ds_write_b16 v128, v32 offset:21712
	v_cvt_pk_bf16_f32 v32, v38, s0
	ds_write_b16 v128, v32 offset:22240
	v_cvt_pk_bf16_f32 v32, v39, s0
	ds_write_b16 v128, v32 offset:22768
	v_cvt_pk_bf16_f32 v32, v40, s0
	ds_write_b16 v128, v32 offset:25408
	v_cvt_pk_bf16_f32 v32, v41, s0
	ds_write_b16 v128, v32 offset:25936
	v_cvt_pk_bf16_f32 v32, v42, s0
	ds_write_b16 v128, v32 offset:26464
	v_cvt_pk_bf16_f32 v32, v43, s0
	ds_write_b16 v128, v32 offset:26992
	v_cvt_pk_bf16_f32 v32, v44, s0
	ds_write_b16 v128, v32 offset:29632
	v_cvt_pk_bf16_f32 v32, v45, s0
	ds_write_b16 v128, v32 offset:30160
	v_cvt_pk_bf16_f32 v32, v46, s0
	ds_write_b16 v128, v32 offset:30688
	v_cvt_pk_bf16_f32 v32, v47, s0
	ds_write_b16 v128, v32 offset:31216
	v_mov_b32_e32 v32, v129
	v_cvt_pk_bf16_f32 v16, v16, s0
	ds_write_b16 v128, v16 offset:17024
	v_cvt_pk_bf16_f32 v16, v17, s0
	ds_write_b16 v128, v16 offset:17552
	v_cvt_pk_bf16_f32 v16, v18, s0
	ds_write_b16 v128, v16 offset:18080
	v_cvt_pk_bf16_f32 v16, v19, s0
	ds_write_b16 v128, v16 offset:18608
	v_cvt_pk_bf16_f32 v16, v20, s0
	ds_write_b16 v128, v16 offset:21248
	v_cvt_pk_bf16_f32 v16, v21, s0
	ds_write_b16 v128, v16 offset:21776
	v_cvt_pk_bf16_f32 v16, v22, s0
	ds_write_b16 v128, v16 offset:22304
	v_cvt_pk_bf16_f32 v16, v23, s0
	ds_write_b16 v128, v16 offset:22832
	v_cvt_pk_bf16_f32 v16, v24, s0
	ds_write_b16 v128, v16 offset:25472
	v_cvt_pk_bf16_f32 v16, v25, s0
	ds_write_b16 v128, v16 offset:26000
	v_cvt_pk_bf16_f32 v16, v26, s0
	ds_write_b16 v128, v16 offset:26528
	v_cvt_pk_bf16_f32 v16, v27, s0
	ds_write_b16 v128, v16 offset:27056
	v_cvt_pk_bf16_f32 v16, v28, s0
	ds_write_b16 v128, v16 offset:29696
	v_cvt_pk_bf16_f32 v16, v29, s0
	ds_write_b16 v128, v16 offset:30224
	v_cvt_pk_bf16_f32 v16, v30, s0
	ds_write_b16 v128, v16 offset:30752
	v_cvt_pk_bf16_f32 v16, v31, s0
	ds_write_b16 v128, v16 offset:31280
	v_mov_b32_e32 v16, v129
	v_cvt_pk_bf16_f32 v0, v0, s0
	ds_write_b16 v128, v0 offset:17088
	v_cvt_pk_bf16_f32 v0, v1, s0
	ds_write_b16 v128, v0 offset:17616
	v_cvt_pk_bf16_f32 v0, v2, s0
	ds_write_b16 v128, v0 offset:18144
	v_cvt_pk_bf16_f32 v0, v3, s0
	ds_write_b16 v128, v0 offset:18672
	v_cvt_pk_bf16_f32 v0, v4, s0
	ds_write_b16 v128, v0 offset:21312
	v_cvt_pk_bf16_f32 v0, v5, s0
	ds_write_b16 v128, v0 offset:21840
	v_cvt_pk_bf16_f32 v0, v6, s0
	ds_write_b16 v128, v0 offset:22368
	v_cvt_pk_bf16_f32 v0, v7, s0
	ds_write_b16 v128, v0 offset:22896
	v_cvt_pk_bf16_f32 v0, v8, s0
	ds_write_b16 v128, v0 offset:25536
	v_cvt_pk_bf16_f32 v0, v9, s0
	ds_write_b16 v128, v0 offset:26064
	v_cvt_pk_bf16_f32 v0, v10, s0
	ds_write_b16 v128, v0 offset:26592
	v_cvt_pk_bf16_f32 v0, v11, s0
	ds_write_b16 v128, v0 offset:27120
	v_cvt_pk_bf16_f32 v0, v12, s0
	ds_write_b16 v128, v0 offset:29760
	v_cvt_pk_bf16_f32 v0, v13, s0
	ds_write_b16 v128, v0 offset:30288
	v_cvt_pk_bf16_f32 v0, v14, s0
	ds_write_b16 v128, v0 offset:30816
	v_cvt_pk_bf16_f32 v0, v15, s0
	v_lshlrev_b32_e32 v52, 5, v141
	ds_write_b16 v128, v0 offset:31344
	v_or_b32_e32 v0, v52, v138
	v_mul_lo_u32 v0, v0, s60
	v_lshl_add_u32 v83, v142, 1, v0
	s_waitcnt lgkmcnt(0)
	s_barrier
	ds_read_b128 v[16:19], v83
	ds_read_b128 v[20:23], v83 offset:32
	ds_read_b128 v[24:27], v83 offset:64
	ds_read_b128 v[28:31], v83 offset:96
	ds_read_b128 v[32:35], v83 offset:128
	ds_read_b128 v[36:39], v83 offset:160
	ds_read_b128 v[40:43], v83 offset:192
	ds_read_b128 v[44:47], v83 offset:224
	s_lshl_b32 s46, s83, 1
	s_ashr_i32 s47, s46, 31
	v_lshrrev_b32_e32 v1, 1, v140
	s_lshl_b64 s[46:47], s[46:47], 15
	v_lshlrev_b32_e32 v0, 8, v138
	v_and_b32_e32 v1, 16, v1
	v_or3_b32 v48, s46, v0, v1
	v_mov_b32_e32 v49, s47
	s_mov_b32 s18, 0
	v_mul_i32_i24_e32 v53, -4, v139
	v_lshl_add_u64 v[50:51], s[12:13], 0, v[48:49]
	v_mov_b32_e32 v69, 0
	v_mov_b32_e32 v68, 0
	v_mov_b32_e32 v67, 0
	v_mov_b32_e32 v66, 0
	v_mov_b32_e32 v65, 0
	v_mov_b32_e32 v64, 0
	v_mov_b32_e32 v63, 0
	v_mov_b32_e32 v62, 0
	v_mov_b32_e32 v61, 0
	v_mov_b32_e32 v60, 0
	v_mov_b32_e32 v59, 0
	v_mov_b32_e32 v58, 0
	v_mov_b32_e32 v57, 0
	v_mov_b32_e32 v56, 0
	v_mov_b32_e32 v55, 0
	v_mov_b32_e32 v54, 0

; template <int EPI>
; __device__ __forceinline__ void gemm_tile(const Params& p, int layer, const u16* __restrict__ A, const u16* __restrict__ Bt, int mt, int nt, char* lds) {
;     ...
;   for (int kt = 0; kt < NK - 1; ++kt) {
;     G_SLAB(true, kt + 1)
;     __syncthreads();
;     G_WRITE();
;     __syncthreads();
;   }
.LBB0_1992:
	ds_read_b128 v[148:151], v130
	ds_read_b128 v[152:155], v130 offset:4608
	ds_read_b128 v[156:159], v131 offset:18432
	ds_read_b128 v[160:163], v131 offset:23040
	ds_read_b128 v[164:167], v131 offset:27648
	ds_read_b128 v[168:171], v131 offset:32256
	ds_read_b128 v[172:175], v130 offset:32
	ds_read_b128 v[176:179], v130 offset:4640
	ds_read_b128 v[180:183], v131 offset:18464
	ds_read_b128 v[184:187], v131 offset:23072
	ds_read_b128 v[188:191], v131 offset:27680
	ds_read_b128 v[192:195], v131 offset:32288
	s_waitcnt lgkmcnt(9)
	v_mfma_f32_32x32x16_bf16 v[112:127], v[148:151], v[156:159], v[112:127]
	s_waitcnt lgkmcnt(8)
	v_mfma_f32_32x32x16_bf16 v[96:111], v[148:151], v[160:163], v[96:111]
	s_waitcnt lgkmcnt(7)
	v_mfma_f32_32x32x16_bf16 v[80:95], v[148:151], v[164:167], v[80:95]
	s_waitcnt lgkmcnt(6)
	v_mfma_f32_32x32x16_bf16 v[64:79], v[148:151], v[168:171], v[64:79]
	v_lshl_add_u64 v[208:209], v[134:135], 0, s[0:1]
	s_mov_b32 s4, 0xa768000
	v_add_co_u32_e32 v148, vcc, s4, v208
	v_lshl_add_u64 v[212:213], v[136:137], 0, s[0:1]
	s_nop 0
	v_addc_co_u32_e32 v149, vcc, 0, v209, vcc
	s_mov_b32 s4, 0x7290000
	v_add_co_u32_e32 v196, vcc, s4, v212
	s_nop 1
	v_addc_co_u32_e32 v197, vcc, 0, v213, vcc
	global_load_dwordx4 v[148:151], v[148:149], off offset:384
	s_nop 0
	global_load_dwordx4 v[196:199], v[196:197], off offset:128
	v_mfma_f32_32x32x16_bf16 v[48:63], v[152:155], v[156:159], v[48:63]
	v_mfma_f32_32x32x16_bf16 v[32:47], v[152:155], v[160:163], v[32:47]
	v_mfma_f32_32x32x16_bf16 v[16:31], v[152:155], v[164:167], v[16:31]
	v_mfma_f32_32x32x16_bf16 v[0:15], v[152:155], v[168:171], v[0:15]
	v_add_co_u32_e32 v152, vcc, s66, v212
	s_nop 1
	v_addc_co_u32_e32 v153, vcc, 0, v213, vcc
	global_load_dwordx4 v[152:155], v[152:153], off offset:128
	ds_read_b128 v[156:159], v130 offset:64
	ds_read_b128 v[160:163], v130 offset:4672
	ds_read_b128 v[164:167], v131 offset:18496
	ds_read_b128 v[168:171], v131 offset:23104
	ds_read_b128 v[200:203], v131 offset:27712
	ds_read_b128 v[204:207], v131 offset:32320
	s_waitcnt lgkmcnt(9)
	v_mfma_f32_32x32x16_bf16 v[112:127], v[172:175], v[180:183], v[112:127]
	s_waitcnt lgkmcnt(8)
	v_mfma_f32_32x32x16_bf16 v[96:111], v[172:175], v[184:187], v[96:111]
	s_waitcnt lgkmcnt(7)
	v_mfma_f32_32x32x16_bf16 v[80:95], v[172:175], v[188:191], v[80:95]
	s_waitcnt lgkmcnt(6)
	v_mfma_f32_32x32x16_bf16 v[64:79], v[172:175], v[192:195], v[64:79]
	v_add_co_u32_e32 v172, vcc, s67, v208
	s_nop 1
	v_addc_co_u32_e32 v173, vcc, 0, v209, vcc
	v_add_co_u32_e32 v216, vcc, s68, v212
	s_nop 1
	v_addc_co_u32_e32 v217, vcc, 0, v213, vcc
	global_load_dwordx4 v[172:175], v[172:173], off offset:384
	s_nop 0
	global_load_dwordx4 v[216:219], v[216:217], off offset:128
	v_mfma_f32_32x32x16_bf16 v[48:63], v[176:179], v[180:183], v[48:63]
	v_mfma_f32_32x32x16_bf16 v[32:47], v[176:179], v[184:187], v[32:47]
	v_mfma_f32_32x32x16_bf16 v[16:31], v[176:179], v[188:191], v[16:31]
	v_mfma_f32_32x32x16_bf16 v[0:15], v[176:179], v[192:195], v[0:15]
	v_add_co_u32_e32 v176, vcc, s69, v212
	s_nop 1
	v_addc_co_u32_e32 v177, vcc, 0, v213, vcc
	global_load_dwordx4 v[176:179], v[176:177], off offset:128
	ds_read_b128 v[180:183], v130 offset:96
	ds_read_b128 v[184:187], v130 offset:4704
	ds_read_b128 v[188:191], v131 offset:18528
	ds_read_b128 v[192:195], v131 offset:23136
	ds_read_b128 v[220:223], v131 offset:27744
	ds_read_b128 v[224:227], v131 offset:32352
	s_waitcnt lgkmcnt(9)
	v_mfma_f32_32x32x16_bf16 v[112:127], v[156:159], v[164:167], v[112:127]
	s_waitcnt lgkmcnt(8)
	v_mfma_f32_32x32x16_bf16 v[96:111], v[156:159], v[168:171], v[96:111]
	s_waitcnt lgkmcnt(7)
	v_mfma_f32_32x32x16_bf16 v[80:95], v[156:159], v[200:203], v[80:95]
	s_waitcnt lgkmcnt(6)
	v_mfma_f32_32x32x16_bf16 v[64:79], v[156:159], v[204:207], v[64:79]
	v_add_co_u32_e32 v156, vcc, s70, v208
	s_nop 1
	v_addc_co_u32_e32 v157, vcc, 0, v209, vcc
	v_add_co_u32_e32 v228, vcc, s71, v212
	s_nop 1
	v_addc_co_u32_e32 v229, vcc, 0, v213, vcc
	global_load_dwordx4 v[156:159], v[156:157], off offset:384
	s_nop 0
	global_load_dwordx4 v[228:231], v[228:229], off offset:128
	v_mfma_f32_32x32x16_bf16 v[48:63], v[160:163], v[164:167], v[48:63]
	v_mfma_f32_32x32x16_bf16 v[32:47], v[160:163], v[168:171], v[32:47]
	v_mfma_f32_32x32x16_bf16 v[16:31], v[160:163], v[200:203], v[16:31]
	v_mfma_f32_32x32x16_bf16 v[0:15], v[160:163], v[204:207], v[0:15]
	v_add_co_u32_e32 v160, vcc, s72, v212
	s_nop 1
	v_addc_co_u32_e32 v161, vcc, 0, v213, vcc
	global_load_dwordx4 v[160:163], v[160:161], off offset:128
	s_waitcnt lgkmcnt(3)
	v_mfma_f32_32x32x16_bf16 v[112:127], v[180:183], v[188:191], v[112:127]
	s_waitcnt lgkmcnt(2)
	v_mfma_f32_32x32x16_bf16 v[96:111], v[180:183], v[192:195], v[96:111]
	s_waitcnt lgkmcnt(1)
	v_mfma_f32_32x32x16_bf16 v[80:95], v[180:183], v[220:223], v[80:95]
	s_waitcnt lgkmcnt(0)
	v_mfma_f32_32x32x16_bf16 v[64:79], v[180:183], v[224:227], v[64:79]
	v_add_co_u32_e32 v164, vcc, s73, v208
	s_nop 1
	v_addc_co_u32_e32 v165, vcc, 0, v209, vcc
	v_add_co_u32_e32 v168, vcc, s77, v212
	s_nop 1
	v_addc_co_u32_e32 v169, vcc, 0, v213, vcc
	global_load_dwordx4 v[164:167], v[164:165], off offset:384
	s_nop 0
	global_load_dwordx4 v[168:171], v[168:169], off offset:128
	v_mfma_f32_32x32x16_bf16 v[48:63], v[184:187], v[188:191], v[48:63]
	v_mfma_f32_32x32x16_bf16 v[32:47], v[184:187], v[192:195], v[32:47]
	v_mfma_f32_32x32x16_bf16 v[16:31], v[184:187], v[220:223], v[16:31]
	v_mfma_f32_32x32x16_bf16 v[0:15], v[184:187], v[224:227], v[0:15]
	v_add_co_u32_e32 v180, vcc, s78, v212
	s_nop 1
	v_addc_co_u32_e32 v181, vcc, 0, v213, vcc
	global_load_dwordx4 v[180:183], v[180:181], off offset:128
	s_add_u32 s0, s0, 0x80
	s_addc_u32 s1, s1, 0
	s_cmpk_eq_i32 s0, 0xf80
	s_barrier
; template <int EPI>
; __device__ __forceinline__ void gemm_tile(const Params& p, int layer, const u16* __restrict__ A, const u16* __restrict__ Bt, int mt, int nt, char* lds) {
;     ...
;   for (int kt = 0; kt < NK - 1; ++kt) {
;     G_SLAB(true, kt + 1)
;     __syncthreads();
;     G_WRITE();
;     __syncthreads();
;   }
;   G_SLAB(false, 0)
;   __syncthreads();
; #pragma unroll
;   for (int i = 0; i < 2; ++i) {
; #pragma unroll
;     for (int j = 0; j < 4; ++j) {
;       int zq = 0; asm volatile("" : "+v"(zq));
;       const int gc = n0 + wc * 128 + j * 32 + r + zq;
;       const int gcb = n0 + wc * 128 + j * 32;
;       const int grb = m0 + wr * 64 + i * 32;
;       if (EPI == 0) {
;         u16* P = (u16*)(p.ws + OFF_P);
;         if ((j & 1) == 0 && ((gcb >= 512 && gcb < 1024) || (gcb >= 2560 && gcb < 2816) || (gcb >= 3584 && gcb < 4096))) {
	s_setprio 0
	s_waitcnt vmcnt(11)
	ds_write_b128 v132, v[148:151]
	s_waitcnt vmcnt(8)
	ds_write_b128 v132, v[172:175] offset:4608
	s_waitcnt vmcnt(5)
	ds_write_b128 v132, v[156:159] offset:9216
	s_waitcnt vmcnt(2)
	ds_write_b128 v132, v[164:167] offset:13824
	ds_write_b128 v132, v[196:199] offset:18432
	ds_write_b128 v132, v[216:219] offset:23040
	ds_write_b128 v132, v[228:231] offset:27648
	s_waitcnt vmcnt(1)
	ds_write_b128 v132, v[168:171] offset:32256
	ds_write_b128 v132, v[152:155] offset:36864
	ds_write_b128 v132, v[176:179] offset:41472
	ds_write_b128 v132, v[160:163] offset:46080
	s_waitcnt vmcnt(0)
	ds_write_b128 v132, v[180:183] offset:50688
	s_waitcnt lgkmcnt(0)
	s_setprio 1
	s_barrier
	s_cbranch_scc0 .LBB0_1992
	ds_read_b128 v[132:135], v130
	ds_read_b128 v[148:151], v130 offset:4608
	ds_read_b128 v[152:155], v131 offset:18432
	ds_read_b128 v[156:159], v131 offset:23040
	ds_read_b128 v[160:163], v131 offset:27648
	ds_read_b128 v[164:167], v131 offset:32256
	ds_read_b128 v[168:171], v130 offset:32
	ds_read_b128 v[172:175], v130 offset:4640
	ds_read_b128 v[176:179], v131 offset:18464
	ds_read_b128 v[180:183], v131 offset:23072
	ds_read_b128 v[184:187], v131 offset:27680
	ds_read_b128 v[188:191], v131 offset:32288
	s_waitcnt lgkmcnt(9)
	v_mfma_f32_32x32x16_bf16 v[112:127], v[132:135], v[152:155], v[112:127]
	s_waitcnt lgkmcnt(8)
	v_mfma_f32_32x32x16_bf16 v[96:111], v[132:135], v[156:159], v[96:111]
	s_waitcnt lgkmcnt(7)
	v_mfma_f32_32x32x16_bf16 v[80:95], v[132:135], v[160:163], v[80:95]
	s_waitcnt lgkmcnt(6)
	v_mfma_f32_32x32x16_bf16 v[64:79], v[132:135], v[164:167], v[64:79]
	v_mfma_f32_32x32x16_bf16 v[48:63], v[148:151], v[152:155], v[48:63]
	v_mfma_f32_32x32x16_bf16 v[32:47], v[148:151], v[156:159], v[32:47]
	v_mfma_f32_32x32x16_bf16 v[16:31], v[148:151], v[160:163], v[16:31]
	v_mfma_f32_32x32x16_bf16 v[0:15], v[148:151], v[164:167], v[0:15]
	ds_read_b128 v[132:135], v130 offset:64
	ds_read_b128 v[148:151], v130 offset:4672
	ds_read_b128 v[152:155], v131 offset:18496
	ds_read_b128 v[156:159], v131 offset:23104
	ds_read_b128 v[160:163], v131 offset:27712
	ds_read_b128 v[164:167], v131 offset:32320
	s_waitcnt lgkmcnt(9)
	v_mfma_f32_32x32x16_bf16 v[112:127], v[168:171], v[176:179], v[112:127]
	s_waitcnt lgkmcnt(8)
	v_mfma_f32_32x32x16_bf16 v[96:111], v[168:171], v[180:183], v[96:111]
	s_waitcnt lgkmcnt(7)
	v_mfma_f32_32x32x16_bf16 v[80:95], v[168:171], v[184:187], v[80:95]
	s_waitcnt lgkmcnt(6)
	v_mfma_f32_32x32x16_bf16 v[64:79], v[168:171], v[188:191], v[64:79]
	v_mfma_f32_32x32x16_bf16 v[48:63], v[172:175], v[176:179], v[48:63]
	v_mfma_f32_32x32x16_bf16 v[32:47], v[172:175], v[180:183], v[32:47]
	v_mfma_f32_32x32x16_bf16 v[16:31], v[172:175], v[184:187], v[16:31]
	v_mfma_f32_32x32x16_bf16 v[0:15], v[172:175], v[188:191], v[0:15]
	ds_read_b128 v[168:171], v130 offset:96
	ds_read_b128 v[172:175], v130 offset:4704
	ds_read_b128 v[176:179], v131 offset:18528
	ds_read_b128 v[180:183], v131 offset:23136
	ds_read_b128 v[184:187], v131 offset:27744
	ds_read_b128 v[188:191], v131 offset:32352
	s_waitcnt lgkmcnt(9)
	v_mfma_f32_32x32x16_bf16 v[112:127], v[132:135], v[152:155], v[112:127]
	s_waitcnt lgkmcnt(8)
	v_mfma_f32_32x32x16_bf16 v[96:111], v[132:135], v[156:159], v[96:111]
	s_waitcnt lgkmcnt(7)
	v_mfma_f32_32x32x16_bf16 v[80:95], v[132:135], v[160:163], v[80:95]
	s_waitcnt lgkmcnt(6)
	v_mfma_f32_32x32x16_bf16 v[64:79], v[132:135], v[164:167], v[64:79]
	v_mfma_f32_32x32x16_bf16 v[48:63], v[148:151], v[152:155], v[48:63]
	v_mfma_f32_32x32x16_bf16 v[32:47], v[148:151], v[156:159], v[32:47]
	v_mfma_f32_32x32x16_bf16 v[16:31], v[148:151], v[160:163], v[16:31]
	v_mfma_f32_32x32x16_bf16 v[0:15], v[148:151], v[164:167], v[0:15]
	s_waitcnt lgkmcnt(3)
	v_mfma_f32_32x32x16_bf16 v[112:127], v[168:171], v[176:179], v[112:127]
	s_waitcnt lgkmcnt(2)
	v_mfma_f32_32x32x16_bf16 v[96:111], v[168:171], v[180:183], v[96:111]
	s_waitcnt lgkmcnt(1)
	v_mfma_f32_32x32x16_bf16 v[80:95], v[168:171], v[184:187], v[80:95]
	s_waitcnt lgkmcnt(0)
	v_mfma_f32_32x32x16_bf16 v[64:79], v[168:171], v[188:191], v[64:79]
	v_mfma_f32_32x32x16_bf16 v[48:63], v[172:175], v[176:179], v[48:63]
	v_mfma_f32_32x32x16_bf16 v[32:47], v[172:175], v[180:183], v[32:47]
	v_mfma_f32_32x32x16_bf16 v[16:31], v[172:175], v[184:187], v[16:31]
	v_mfma_f32_32x32x16_bf16 v[0:15], v[172:175], v[188:191], v[0:15]
	s_and_b32 s97, s96, 0xffff
	s_cmp_lg_u32 s97, 10
	v_or_b32_e32 v137, s95, v145
	s_cselect_b64 s[16:17], -1, 0
	s_and_b32 s88, s96, 0xfffffe
	v_cmp_eq_u32_e64 s[0:1], 0, v144
	v_mov_b32_e32 v128, 0
	v_cmp_gt_i32_e64 s[6:7], s79, v137
	v_cmp_lt_i32_e64 s[10:11], s80, v137
	s_mov_b64 s[4:5], -1
	s_and_b64 vcc, exec, s[16:17]
	s_barrier
	s_cbranch_vccz .LBB0_1998
	s_cmp_lt_i32 s88, 14
	s_cbranch_scc1 .LBB0_1996
	s_cmp_eq_u32 s88, 14
	s_cselect_b64 s[4:5], -1, 0
	s_cbranch_execz .LBB0_1997
	s_branch .LBB0_1998

; template <int EPI>
; __device__ __forceinline__ void gemm_tile(const Params& p, int layer, const u16* __restrict__ A, const u16* __restrict__ Bt, int mt, int nt, char* lds) {
;     ...
;   for (int kt = 0; kt < NK - 1; ++kt) {
;     G_SLAB(true, kt + 1)
;     __syncthreads();
;     G_WRITE();
;     __syncthreads();
;   }
.LBB0_2385:
	ds_read_b128 v[142:145], v130
	ds_read_b128 v[146:149], v130 offset:4608
	ds_read_b128 v[150:153], v131 offset:18432
	ds_read_b128 v[154:157], v131 offset:23040
	ds_read_b128 v[158:161], v131 offset:27648
	ds_read_b128 v[162:165], v131 offset:32256
	ds_read_b128 v[166:169], v130 offset:32
	ds_read_b128 v[170:173], v130 offset:4640
	ds_read_b128 v[174:177], v131 offset:18464
	ds_read_b128 v[178:181], v131 offset:23072
	ds_read_b128 v[182:185], v131 offset:27680
	ds_read_b128 v[186:189], v131 offset:32288
	s_waitcnt lgkmcnt(9)
	v_mfma_f32_32x32x16_bf16 v[112:127], v[142:145], v[150:153], v[112:127]
	s_waitcnt lgkmcnt(8)
	v_mfma_f32_32x32x16_bf16 v[96:111], v[142:145], v[154:157], v[96:111]
	s_waitcnt lgkmcnt(7)
	v_mfma_f32_32x32x16_bf16 v[80:95], v[142:145], v[158:161], v[80:95]
	s_waitcnt lgkmcnt(6)
	v_mfma_f32_32x32x16_bf16 v[64:79], v[142:145], v[162:165], v[64:79]
	v_lshl_add_u64 v[212:213], v[134:135], 0, s[10:11]
	v_add_co_u32_e32 v142, vcc, s23, v212
	v_lshl_add_u64 v[224:225], v[136:137], 0, s[10:11]
	s_nop 0
	v_addc_co_u32_e32 v143, vcc, 0, v213, vcc
	v_add_co_u32_e32 v190, vcc, s24, v224
	s_nop 1
	v_addc_co_u32_e32 v191, vcc, 0, v225, vcc
	global_load_dwordx4 v[142:145], v[142:143], off offset:384
	s_nop 0
	global_load_dwordx4 v[190:193], v[190:191], off offset:128
	v_mfma_f32_32x32x16_bf16 v[48:63], v[146:149], v[150:153], v[48:63]
	v_mfma_f32_32x32x16_bf16 v[32:47], v[146:149], v[154:157], v[32:47]
	v_mfma_f32_32x32x16_bf16 v[16:31], v[146:149], v[158:161], v[16:31]
	v_mfma_f32_32x32x16_bf16 v[0:15], v[146:149], v[162:165], v[0:15]
	v_add_co_u32_e32 v146, vcc, s25, v224
	s_nop 1
	v_addc_co_u32_e32 v147, vcc, 0, v225, vcc
	global_load_dwordx4 v[146:149], v[146:147], off offset:128
	ds_read_b128 v[150:153], v130 offset:64
	ds_read_b128 v[154:157], v130 offset:4672
	ds_read_b128 v[158:161], v131 offset:18496
	ds_read_b128 v[162:165], v131 offset:23104
	ds_read_b128 v[194:197], v131 offset:27712
	ds_read_b128 v[198:201], v131 offset:32320
	s_waitcnt lgkmcnt(9)
	v_mfma_f32_32x32x16_bf16 v[112:127], v[166:169], v[174:177], v[112:127]
	s_waitcnt lgkmcnt(8)
	v_mfma_f32_32x32x16_bf16 v[96:111], v[166:169], v[178:181], v[96:111]
	s_waitcnt lgkmcnt(7)
	v_mfma_f32_32x32x16_bf16 v[80:95], v[166:169], v[182:185], v[80:95]
	s_waitcnt lgkmcnt(6)
	v_mfma_f32_32x32x16_bf16 v[64:79], v[166:169], v[186:189], v[64:79]
	v_add_co_u32_e32 v166, vcc, s26, v212
	s_nop 1
	v_addc_co_u32_e32 v167, vcc, 0, v213, vcc
	v_add_co_u32_e32 v202, vcc, s27, v224
	s_nop 1
	v_addc_co_u32_e32 v203, vcc, 0, v225, vcc
	global_load_dwordx4 v[166:169], v[166:167], off offset:384
	s_nop 0
	global_load_dwordx4 v[202:205], v[202:203], off offset:128
	v_mfma_f32_32x32x16_bf16 v[48:63], v[170:173], v[174:177], v[48:63]
	v_mfma_f32_32x32x16_bf16 v[32:47], v[170:173], v[178:181], v[32:47]
	v_mfma_f32_32x32x16_bf16 v[16:31], v[170:173], v[182:185], v[16:31]
	v_mfma_f32_32x32x16_bf16 v[0:15], v[170:173], v[186:189], v[0:15]
	v_add_co_u32_e32 v170, vcc, s28, v224
	s_nop 1
	v_addc_co_u32_e32 v171, vcc, 0, v225, vcc
	global_load_dwordx4 v[170:173], v[170:171], off offset:128
	ds_read_b128 v[174:177], v130 offset:96
	ds_read_b128 v[178:181], v130 offset:4704
	ds_read_b128 v[182:185], v131 offset:18528
	ds_read_b128 v[186:189], v131 offset:23136
	ds_read_b128 v[206:209], v131 offset:27744
	ds_read_b128 v[216:219], v131 offset:32352
	s_waitcnt lgkmcnt(9)
	v_mfma_f32_32x32x16_bf16 v[112:127], v[150:153], v[158:161], v[112:127]
	s_waitcnt lgkmcnt(8)
	v_mfma_f32_32x32x16_bf16 v[96:111], v[150:153], v[162:165], v[96:111]
	s_waitcnt lgkmcnt(7)
	v_mfma_f32_32x32x16_bf16 v[80:95], v[150:153], v[194:197], v[80:95]
	s_waitcnt lgkmcnt(6)
	v_mfma_f32_32x32x16_bf16 v[64:79], v[150:153], v[198:201], v[64:79]
	v_add_co_u32_e32 v150, vcc, s29, v212
	s_nop 1
	v_addc_co_u32_e32 v151, vcc, 0, v213, vcc
	v_add_co_u32_e32 v220, vcc, s30, v224
	s_nop 1
	v_addc_co_u32_e32 v221, vcc, 0, v225, vcc
	global_load_dwordx4 v[150:153], v[150:151], off offset:384
	s_nop 0
	global_load_dwordx4 v[220:223], v[220:221], off offset:128
	v_mfma_f32_32x32x16_bf16 v[48:63], v[154:157], v[158:161], v[48:63]
	v_mfma_f32_32x32x16_bf16 v[32:47], v[154:157], v[162:165], v[32:47]
	v_mfma_f32_32x32x16_bf16 v[16:31], v[154:157], v[194:197], v[16:31]
	v_mfma_f32_32x32x16_bf16 v[0:15], v[154:157], v[198:201], v[0:15]
	v_add_co_u32_e32 v154, vcc, s31, v224
	s_nop 1
	v_addc_co_u32_e32 v155, vcc, 0, v225, vcc
	global_load_dwordx4 v[154:157], v[154:155], off offset:128
	s_waitcnt lgkmcnt(3)
	v_mfma_f32_32x32x16_bf16 v[112:127], v[174:177], v[182:185], v[112:127]
	s_waitcnt lgkmcnt(2)
	v_mfma_f32_32x32x16_bf16 v[96:111], v[174:177], v[186:189], v[96:111]
	s_waitcnt lgkmcnt(1)
	v_mfma_f32_32x32x16_bf16 v[80:95], v[174:177], v[206:209], v[80:95]
	s_waitcnt lgkmcnt(0)
	v_mfma_f32_32x32x16_bf16 v[64:79], v[174:177], v[216:219], v[64:79]
	v_add_co_u32_e32 v158, vcc, s34, v212
	s_nop 1
	v_addc_co_u32_e32 v159, vcc, 0, v213, vcc
	v_add_co_u32_e32 v162, vcc, s35, v224
	s_nop 1
	v_addc_co_u32_e32 v163, vcc, 0, v225, vcc
	global_load_dwordx4 v[158:161], v[158:159], off offset:384
	s_nop 0
	global_load_dwordx4 v[162:165], v[162:163], off offset:128
	v_mfma_f32_32x32x16_bf16 v[48:63], v[178:181], v[182:185], v[48:63]
	v_mfma_f32_32x32x16_bf16 v[32:47], v[178:181], v[186:189], v[32:47]
	v_mfma_f32_32x32x16_bf16 v[16:31], v[178:181], v[206:209], v[16:31]
	v_mfma_f32_32x32x16_bf16 v[0:15], v[178:181], v[216:219], v[0:15]
	v_add_co_u32_e32 v174, vcc, s36, v224
	s_nop 1
	v_addc_co_u32_e32 v175, vcc, 0, v225, vcc
	global_load_dwordx4 v[174:177], v[174:175], off offset:128
	s_add_u32 s10, s10, 0x80
	s_addc_u32 s11, s11, 0
	s_cmpk_eq_i32 s10, 0xf80
	s_barrier
; template <int EPI>
; __device__ __forceinline__ void gemm_tile(const Params& p, int layer, const u16* __restrict__ A, const u16* __restrict__ Bt, int mt, int nt, char* lds) {
;     ...
;   for (int kt = 0; kt < NK - 1; ++kt) {
;     G_SLAB(true, kt + 1)
;     __syncthreads();
;     G_WRITE();
;     __syncthreads();
;   }
;   G_SLAB(false, 0)
;   __syncthreads();
	s_setprio 0
	s_waitcnt vmcnt(11)
	ds_write_b128 v132, v[142:145]
	s_waitcnt vmcnt(8)
	ds_write_b128 v132, v[166:169] offset:4608
	s_waitcnt vmcnt(5)
	ds_write_b128 v132, v[150:153] offset:9216
	s_waitcnt vmcnt(2)
	ds_write_b128 v132, v[158:161] offset:13824
	ds_write_b128 v132, v[190:193] offset:18432
	ds_write_b128 v132, v[202:205] offset:23040
	ds_write_b128 v132, v[220:223] offset:27648
	s_waitcnt vmcnt(1)
	ds_write_b128 v132, v[162:165] offset:32256
	ds_write_b128 v132, v[146:149] offset:36864
	ds_write_b128 v132, v[170:173] offset:41472
	ds_write_b128 v132, v[154:157] offset:46080
	s_waitcnt vmcnt(0)
	ds_write_b128 v132, v[174:177] offset:50688
	s_waitcnt lgkmcnt(0)
	s_setprio 1
	s_barrier
	s_cbranch_scc0 .LBB0_2385
	ds_read_b128 v[132:135], v130
	ds_read_b128 v[142:145], v130 offset:4608
	ds_read_b128 v[146:149], v131 offset:18432
	ds_read_b128 v[150:153], v131 offset:23040
	ds_read_b128 v[154:157], v131 offset:27648
	ds_read_b128 v[158:161], v131 offset:32256
	ds_read_b128 v[162:165], v130 offset:32
	ds_read_b128 v[166:169], v130 offset:4640
	ds_read_b128 v[170:173], v131 offset:18464
	ds_read_b128 v[174:177], v131 offset:23072
	ds_read_b128 v[178:181], v131 offset:27680
	ds_read_b128 v[182:185], v131 offset:32288
	s_waitcnt lgkmcnt(9)
	v_mfma_f32_32x32x16_bf16 v[112:127], v[132:135], v[146:149], v[112:127]
	s_waitcnt lgkmcnt(8)
	v_mfma_f32_32x32x16_bf16 v[96:111], v[132:135], v[150:153], v[96:111]
	s_waitcnt lgkmcnt(7)
	v_mfma_f32_32x32x16_bf16 v[80:95], v[132:135], v[154:157], v[80:95]
	s_waitcnt lgkmcnt(6)
	v_mfma_f32_32x32x16_bf16 v[64:79], v[132:135], v[158:161], v[64:79]
	v_mfma_f32_32x32x16_bf16 v[48:63], v[142:145], v[146:149], v[48:63]
	v_mfma_f32_32x32x16_bf16 v[32:47], v[142:145], v[150:153], v[32:47]
	v_mfma_f32_32x32x16_bf16 v[16:31], v[142:145], v[154:157], v[16:31]
	v_mfma_f32_32x32x16_bf16 v[0:15], v[142:145], v[158:161], v[0:15]
	ds_read_b128 v[132:135], v130 offset:64
	ds_read_b128 v[142:145], v130 offset:4672
	ds_read_b128 v[146:149], v131 offset:18496
	ds_read_b128 v[150:153], v131 offset:23104
	ds_read_b128 v[154:157], v131 offset:27712
	ds_read_b128 v[158:161], v131 offset:32320
	s_waitcnt lgkmcnt(9)
	v_mfma_f32_32x32x16_bf16 v[112:127], v[162:165], v[170:173], v[112:127]
	s_waitcnt lgkmcnt(8)
	v_mfma_f32_32x32x16_bf16 v[96:111], v[162:165], v[174:177], v[96:111]
	s_waitcnt lgkmcnt(7)
	v_mfma_f32_32x32x16_bf16 v[80:95], v[162:165], v[178:181], v[80:95]
	s_waitcnt lgkmcnt(6)
	v_mfma_f32_32x32x16_bf16 v[64:79], v[162:165], v[182:185], v[64:79]
	v_mfma_f32_32x32x16_bf16 v[48:63], v[166:169], v[170:173], v[48:63]
	v_mfma_f32_32x32x16_bf16 v[32:47], v[166:169], v[174:177], v[32:47]
	v_mfma_f32_32x32x16_bf16 v[16:31], v[166:169], v[178:181], v[16:31]
	v_mfma_f32_32x32x16_bf16 v[0:15], v[166:169], v[182:185], v[0:15]
	ds_read_b128 v[162:165], v130 offset:96
	ds_read_b128 v[166:169], v130 offset:4704
	ds_read_b128 v[170:173], v131 offset:18528
	ds_read_b128 v[174:177], v131 offset:23136
	ds_read_b128 v[178:181], v131 offset:27744
	ds_read_b128 v[182:185], v131 offset:32352
	s_waitcnt lgkmcnt(9)
	v_mfma_f32_32x32x16_bf16 v[112:127], v[132:135], v[146:149], v[112:127]
	s_waitcnt lgkmcnt(8)
	v_mfma_f32_32x32x16_bf16 v[96:111], v[132:135], v[150:153], v[96:111]
	s_waitcnt lgkmcnt(7)
	v_mfma_f32_32x32x16_bf16 v[80:95], v[132:135], v[154:157], v[80:95]
	s_waitcnt lgkmcnt(6)
	v_mfma_f32_32x32x16_bf16 v[64:79], v[132:135], v[158:161], v[64:79]
	v_mfma_f32_32x32x16_bf16 v[48:63], v[142:145], v[146:149], v[48:63]
	v_mfma_f32_32x32x16_bf16 v[32:47], v[142:145], v[150:153], v[32:47]
	v_mfma_f32_32x32x16_bf16 v[16:31], v[142:145], v[154:157], v[16:31]
	v_mfma_f32_32x32x16_bf16 v[0:15], v[142:145], v[158:161], v[0:15]
	s_waitcnt lgkmcnt(3)
	v_mfma_f32_32x32x16_bf16 v[112:127], v[162:165], v[170:173], v[112:127]
	s_waitcnt lgkmcnt(2)
	v_mfma_f32_32x32x16_bf16 v[96:111], v[162:165], v[174:177], v[96:111]
	s_waitcnt lgkmcnt(1)
	v_mfma_f32_32x32x16_bf16 v[80:95], v[162:165], v[178:181], v[80:95]
	s_waitcnt lgkmcnt(0)
	v_mfma_f32_32x32x16_bf16 v[64:79], v[162:165], v[182:185], v[64:79]
	v_mfma_f32_32x32x16_bf16 v[48:63], v[166:169], v[170:173], v[48:63]
	v_mfma_f32_32x32x16_bf16 v[32:47], v[166:169], v[174:177], v[32:47]
	v_mfma_f32_32x32x16_bf16 v[16:31], v[166:169], v[178:181], v[16:31]
	v_mfma_f32_32x32x16_bf16 v[0:15], v[166:169], v[182:185], v[0:15]
	v_or_b32_e32 v130, s50, v140
	s_cmp_lt_i32 s48, 2
	v_mov_b32_e32 v131, v129
	s_barrier
; DI int crow(int i, int h) { return (i & 3) + 8 * (i >> 2) + 4 * h; }
; DI const float* modp(const Params& p, int layer, int v) { return (const float*)(p.ws + OFF_MOD) + (size_t)(layer * 2 + v) * 12288; }
; template <int EPI>
; __device__ __forceinline__ void gemm_tile(const Params& p, int layer, const u16* __restrict__ A, const u16* __restrict__ Bt, int mt, int nt, char* lds) {
;     ...
;       } else if (EPI == 1) {
;         float* PRE = (float*)(p.ws + OFF_P);
;         const int v = m0 < NCTX ? 1 : 0;
;         const float g = modp(p, layer, v)[4096 + gc];
; #pragma unroll
;         for (int e = 0; e < 16; ++e) {
;           const int gr = grb + crow(e, h);
;           float xin;
;           if (layer == 0) xin = (gr < NCTX) ? p.ctx[(size_t)gr * DM + gc] : p.x[(size_t)(gr - NCTX) * DM + gc];
;           else xin = ((const float*)(p.ws + OFF_XRES))[(size_t)gr * LDF + gc];
;           PRE[(size_t)gr * LDF + gc] = ALPHA * xin + (DBG_NOATTN ? 0.f : g * acc[i][j][e]);
;         }
	s_cselect_b32 s10, s37, 0x18000
	s_add_u32 s10, s0, s10
	v_add_u32_e32 v132, v131, v130
	v_ashrrev_i32_e32 v133, 31, v132
	s_addc_u32 s11, s1, 0
	v_lshlrev_b64 v[132:133], 2, v[132:133]
	v_add_u32_e32 v128, s49, v139
	v_lshl_add_u64 v[134:135], s[10:11], 0, v[132:133]
	v_lshl_or_b32 v128, v138, 2, v128
	v_add_co_u32_e32 v134, vcc, s46, v134
	v_lshl_add_u64 v[136:137], s[8:9], 0, v[132:133]
	s_nop 0
	v_addc_co_u32_e32 v135, vcc, 0, v135, vcc
	v_mad_i64_i32 v[138:139], s[48:49], v128, s47, v[136:137]
	v_or_b32_e32 v152, 1, v128
	global_load_dword v131, v[138:139], off
	s_nop 0
	global_load_dword v138, v[134:135], off
	v_mad_i64_i32 v[134:135], s[48:49], v152, s47, v[136:137]
	global_load_dword v139, v[134:135], off
	v_or_b32_e32 v156, 2, v128
	v_mad_i64_i32 v[134:135], s[48:49], v156, s47, v[136:137]
	v_or_b32_e32 v157, 3, v128
	global_load_dword v140, v[134:135], off
	v_mad_i64_i32 v[134:135], s[48:49], v157, s47, v[136:137]
	global_load_dword v141, v[134:135], off
	v_or_b32_e32 v158, 8, v128
	v_mad_i64_i32 v[134:135], s[48:49], v158, s47, v[136:137]
	global_load_dword v142, v[134:135], off
	v_or_b32_e32 v159, 9, v128
	v_mad_i64_i32 v[134:135], s[48:49], v159, s47, v[136:137]
	global_load_dword v143, v[134:135], off
	v_or_b32_e32 v162, 10, v128
	v_mad_i64_i32 v[134:135], s[48:49], v162, s47, v[136:137]
	global_load_dword v144, v[134:135], off
	v_or_b32_e32 v163, 11, v128
	v_mad_i64_i32 v[134:135], s[48:49], v163, s47, v[136:137]
	global_load_dword v145, v[134:135], off
	v_or_b32_e32 v164, 16, v128
	v_mad_i64_i32 v[134:135], s[48:49], v164, s47, v[136:137]
	global_load_dword v146, v[134:135], off
	v_or_b32_e32 v165, 17, v128
	v_mad_i64_i32 v[134:135], s[48:49], v165, s47, v[136:137]
	global_load_dword v147, v[134:135], off
	v_or_b32_e32 v166, 18, v128
	v_mad_i64_i32 v[134:135], s[48:49], v166, s47, v[136:137]
	global_load_dword v148, v[134:135], off
	v_or_b32_e32 v167, 19, v128
	v_mad_i64_i32 v[134:135], s[48:49], v167, s47, v[136:137]
	global_load_dword v149, v[134:135], off
	v_or_b32_e32 v169, 24, v128
	v_mad_i64_i32 v[134:135], s[48:49], v169, s47, v[136:137]
	global_load_dword v150, v[134:135], off
	v_or_b32_e32 v172, 25, v128
	v_mad_i64_i32 v[134:135], s[48:49], v172, s47, v[136:137]
	global_load_dword v151, v[134:135], off
	v_or_b32_e32 v173, 26, v128
	v_mad_i64_i32 v[134:135], s[48:49], v173, s47, v[136:137]
	global_load_dword v153, v[134:135], off
	v_or_b32_e32 v174, 27, v128
	v_mad_i64_i32 v[134:135], s[48:49], v174, s47, v[136:137]
	global_load_dword v136, v[134:135], off
	v_lshl_add_u64 v[132:133], s[6:7], 0, v[132:133]
	v_mad_i64_i32 v[134:135], s[48:49], v128, s47, v[132:133]
	v_or_b32_e32 v168, 32, v130
	s_waitcnt vmcnt(16)
	v_mul_f32_e32 v131, 0x3fb504f3, v131
	s_waitcnt vmcnt(15)
	v_fmac_f32_e32 v131, v112, v138
	global_store_dword v[134:135], v131, off
	s_waitcnt vmcnt(15)
	v_mul_f32_e32 v131, 0x3fb504f3, v139
	v_fmac_f32_e32 v131, v113, v138
	v_mad_i64_i32 v[112:113], s[48:49], v152, s47, v[132:133]
	global_store_dword v[112:113], v131, off
	s_waitcnt vmcnt(15)
	v_mul_f32_e32 v131, 0x3fb504f3, v140
	v_fmac_f32_e32 v131, v114, v138
	v_mad_i64_i32 v[112:113], s[48:49], v156, s47, v[132:133]
	s_waitcnt vmcnt(14)
	v_mul_f32_e32 v114, 0x3fb504f3, v141
	global_store_dword v[112:113], v131, off
	v_fmac_f32_e32 v114, v115, v138
	v_mad_i64_i32 v[112:113], s[48:49], v157, s47, v[132:133]
	global_store_dword v[112:113], v114, off
	s_waitcnt vmcnt(15)
	v_mul_f32_e32 v114, 0x3fb504f3, v142
	v_fmac_f32_e32 v114, v116, v138
	v_mad_i64_i32 v[112:113], s[48:49], v158, s47, v[132:133]
	global_store_dword v[112:113], v114, off
	s_waitcnt vmcnt(15)
	v_mul_f32_e32 v114, 0x3fb504f3, v143
	v_fmac_f32_e32 v114, v117, v138
	v_mad_i64_i32 v[112:113], s[48:49], v159, s47, v[132:133]
	global_store_dword v[112:113], v114, off
	s_waitcnt vmcnt(15)
	v_mul_f32_e32 v114, 0x3fb504f3, v144
	v_fmac_f32_e32 v114, v118, v138
	v_mad_i64_i32 v[112:113], s[48:49], v162, s47, v[132:133]
	global_store_dword v[112:113], v114, off
	s_waitcnt vmcnt(15)
	v_mul_f32_e32 v114, 0x3fb504f3, v145
	v_fmac_f32_e32 v114, v119, v138
	v_mad_i64_i32 v[112:113], s[48:49], v163, s47, v[132:133]
	global_store_dword v[112:113], v114, off
	s_waitcnt vmcnt(15)
	v_mul_f32_e32 v114, 0x3fb504f3, v146
	v_fmac_f32_e32 v114, v120, v138
	v_mad_i64_i32 v[112:113], s[48:49], v164, s47, v[132:133]
	global_store_dword v[112:113], v114, off
	s_waitcnt vmcnt(15)
	v_mul_f32_e32 v114, 0x3fb504f3, v147
	v_fmac_f32_e32 v114, v121, v138
	v_mad_i64_i32 v[112:113], s[48:49], v165, s47, v[132:133]
	global_store_dword v[112:113], v114, off
	s_waitcnt vmcnt(15)
	v_mul_f32_e32 v114, 0x3fb504f3, v148
	v_fmac_f32_e32 v114, v122, v138
	v_mad_i64_i32 v[112:113], s[48:49], v166, s47, v[132:133]
	global_store_dword v[112:113], v114, off
	s_waitcnt vmcnt(15)
	v_mul_f32_e32 v114, 0x3fb504f3, v149
	v_fmac_f32_e32 v114, v123, v138
	v_mad_i64_i32 v[112:113], s[48:49], v167, s47, v[132:133]
	global_store_dword v[112:113], v114, off
	s_waitcnt vmcnt(15)
	v_mul_f32_e32 v114, 0x3fb504f3, v150
	v_fmac_f32_e32 v114, v124, v138
	v_mad_i64_i32 v[112:113], s[48:49], v169, s47, v[132:133]
	global_store_dword v[112:113], v114, off
	s_waitcnt vmcnt(15)
	v_mul_f32_e32 v114, 0x3fb504f3, v151
	v_fmac_f32_e32 v114, v125, v138
	v_mad_i64_i32 v[112:113], s[48:49], v172, s47, v[132:133]
	global_store_dword v[112:113], v114, off
	s_waitcnt vmcnt(15)
	v_mul_f32_e32 v114, 0x3fb504f3, v153
	v_fmac_f32_e32 v114, v126, v138
	v_mad_i64_i32 v[112:113], s[48:49], v173, s47, v[132:133]
	global_store_dword v[112:113], v114, off
	s_waitcnt vmcnt(15)
; DI int crow(int i, int h) { return (i & 3) + 8 * (i >> 2) + 4 * h; }
; DI const float* modp(const Params& p, int layer, int v) { return (const float*)(p.ws + OFF_MOD) + (size_t)(layer * 2 + v) * 12288; }
; template <int EPI>
; __device__ __forceinline__ void gemm_tile(const Params& p, int layer, const u16* __restrict__ A, const u16* __restrict__ Bt, int mt, int nt, char* lds) {
;     ...
;       } else if (EPI == 1) {
;         float* PRE = (float*)(p.ws + OFF_P);
;         const int v = m0 < NCTX ? 1 : 0;
;         const float g = modp(p, layer, v)[4096 + gc];
; #pragma unroll
;         for (int e = 0; e < 16; ++e) {
;           const int gr = grb + crow(e, h);
;           float xin;
;           if (layer == 0) xin = (gr < NCTX) ? p.ctx[(size_t)gr * DM + gc] : p.x[(size_t)(gr - NCTX) * DM + gc];
;           else xin = ((const float*)(p.ws + OFF_XRES))[(size_t)gr * LDF + gc];
;           PRE[(size_t)gr * LDF + gc] = ALPHA * xin + (DBG_NOATTN ? 0.f : g * acc[i][j][e]);
;         }
	v_mul_f32_e32 v114, 0x3fb504f3, v136
	v_fmac_f32_e32 v114, v127, v138
	v_mad_i64_i32 v[112:113], s[48:49], v174, s47, v[132:133]
	global_store_dword v[112:113], v114, off
	v_mov_b32_e32 v112, v129
	v_ashrrev_i32_e32 v131, 31, v130
	v_ashrrev_i32_e32 v113, 31, v112
	v_add_u32_e32 v114, v112, v168
	v_lshl_add_u64 v[112:113], v[112:113], 0, v[130:131]
	v_lshl_add_u64 v[112:113], v[112:113], 2, s[10:11]
	v_add_co_u32_e32 v116, vcc, s46, v112
	v_ashrrev_i32_e32 v115, 31, v114
	s_nop 0
	v_addc_co_u32_e32 v117, vcc, 0, v113, vcc
	v_mov_b64_e32 v[112:113], s[8:9]
	v_mad_i64_i32 v[118:119], s[48:49], v128, s47, v[112:113]
	v_lshlrev_b64 v[170:171], 2, v[114:115]
	v_lshl_add_u64 v[114:115], v[118:119], 0, v[170:171]
	global_load_dword v142, v[114:115], off
	global_load_dword v175, v[116:117], off offset:128
	v_mad_i64_i32 v[120:121], s[48:49], v152, s47, v[112:113]
	v_lshl_add_u64 v[114:115], v[120:121], 0, v[170:171]
	global_load_dword v153, v[114:115], off
	v_mad_i64_i32 v[144:145], s[48:49], v167, s47, v[112:113]
	v_mad_i64_i32 v[122:123], s[48:49], v156, s47, v[112:113]
	v_lshl_add_u64 v[116:117], v[144:145], 0, v[170:171]
	v_mad_i64_i32 v[124:125], s[48:49], v157, s47, v[112:113]
	global_load_dword v185, v[116:117], off
	v_lshl_add_u64 v[114:115], v[122:123], 0, v[170:171]
	global_load_dword v176, v[114:115], off
	v_lshl_add_u64 v[114:115], v[124:125], 0, v[170:171]
	global_load_dword v177, v[114:115], off
	v_mad_i64_i32 v[126:127], s[48:49], v158, s47, v[112:113]
	v_lshl_add_u64 v[114:115], v[126:127], 0, v[170:171]
	v_mad_i64_i32 v[132:133], s[48:49], v159, s47, v[112:113]
	global_load_dword v178, v[114:115], off
	v_lshl_add_u64 v[114:115], v[132:133], 0, v[170:171]
	global_load_dword v179, v[114:115], off
	v_mad_i64_i32 v[134:135], s[48:49], v162, s47, v[112:113]
	v_lshl_add_u64 v[114:115], v[134:135], 0, v[170:171]
	v_mad_i64_i32 v[136:137], s[48:49], v163, s47, v[112:113]
	global_load_dword v180, v[114:115], off
	v_lshl_add_u64 v[114:115], v[136:137], 0, v[170:171]
	v_mad_i64_i32 v[138:139], s[48:49], v164, s47, v[112:113]
	global_load_dword v181, v[114:115], off
	v_lshl_add_u64 v[114:115], v[138:139], 0, v[170:171]
	v_mad_i64_i32 v[140:141], s[48:49], v165, s47, v[112:113]
	global_load_dword v182, v[114:115], off
	v_lshl_add_u64 v[114:115], v[140:141], 0, v[170:171]
	global_load_dword v183, v[114:115], off
	v_mad_i64_i32 v[146:147], s[48:49], v169, s47, v[112:113]
	v_lshl_add_u64 v[150:151], v[146:147], 0, v[170:171]
	global_load_dword v186, v[150:151], off
	v_mad_i64_i32 v[160:161], s[48:49], v174, s47, v[112:113]
	s_waitcnt vmcnt(12)
	v_mul_f32_e32 v154, 0x3fb504f3, v142
	v_mad_i64_i32 v[142:143], s[48:49], v166, s47, v[112:113]
	v_lshl_add_u64 v[114:115], v[142:143], 0, v[170:171]
	global_load_dword v184, v[114:115], off
	v_mov_b64_e32 v[114:115], s[6:7]
	v_mad_i64_i32 v[116:117], s[48:49], v128, s47, v[114:115]
	s_waitcnt vmcnt(12)
	v_fmac_f32_e32 v154, v96, v175
	v_lshl_add_u64 v[148:149], v[116:117], 0, v[170:171]
	global_store_dword v[148:149], v154, off
	s_waitcnt vmcnt(12)
	v_mul_f32_e32 v187, 0x3fb504f3, v153
	v_mad_i64_i32 v[154:155], s[48:49], v173, s47, v[112:113]
	v_mad_i64_i32 v[148:149], s[48:49], v172, s47, v[112:113]
	v_fmac_f32_e32 v187, v97, v175
	v_lshl_add_u64 v[96:97], v[154:155], 0, v[170:171]
	global_load_dword v189, v[96:97], off
	v_lshl_add_u64 v[150:151], v[148:149], 0, v[170:171]
	global_load_dword v188, v[150:151], off
	v_mad_i64_i32 v[96:97], s[48:49], v152, s47, v[114:115]
	v_lshl_add_u64 v[152:153], v[160:161], 0, v[170:171]
	global_load_dword v190, v[152:153], off
	v_lshl_add_u64 v[150:151], v[96:97], 0, v[170:171]
	global_store_dword v[150:151], v187, off
	s_waitcnt vmcnt(14)
	v_mul_f32_e32 v176, 0x3fb504f3, v176
	v_mad_i64_i32 v[150:151], s[48:49], v156, s47, v[114:115]
	s_waitcnt vmcnt(13)
	v_mul_f32_e32 v156, 0x3fb504f3, v177
	v_fmac_f32_e32 v176, v98, v175
	v_lshl_add_u64 v[152:153], v[150:151], 0, v[170:171]
	v_fmac_f32_e32 v156, v99, v175
	v_mad_i64_i32 v[98:99], s[48:49], v157, s47, v[114:115]
	global_store_dword v[152:153], v176, off
	v_lshl_add_u64 v[152:153], v[98:99], 0, v[170:171]
	global_store_dword v[152:153], v156, off
	s_waitcnt vmcnt(14)
	v_mul_f32_e32 v176, 0x3fb504f3, v178
	v_mad_i64_i32 v[152:153], s[48:49], v158, s47, v[114:115]
	s_waitcnt vmcnt(13)
	v_mul_f32_e32 v158, 0x3fb504f3, v179
	v_fmac_f32_e32 v176, v100, v175
	v_lshl_add_u64 v[156:157], v[152:153], 0, v[170:171]
	v_fmac_f32_e32 v158, v101, v175
	v_mad_i64_i32 v[100:101], s[48:49], v159, s47, v[114:115]
	global_store_dword v[156:157], v176, off
	v_lshl_add_u64 v[156:157], v[100:101], 0, v[170:171]
	global_store_dword v[156:157], v158, off
	s_waitcnt vmcnt(14)
	v_mul_f32_e32 v176, 0x3fb504f3, v180
	v_mad_i64_i32 v[156:157], s[48:49], v162, s47, v[114:115]
	s_waitcnt vmcnt(13)
	v_mul_f32_e32 v162, 0x3fb504f3, v181
	v_fmac_f32_e32 v176, v102, v175
	v_lshl_add_u64 v[158:159], v[156:157], 0, v[170:171]
	v_fmac_f32_e32 v162, v103, v175
	v_mad_i64_i32 v[102:103], s[48:49], v163, s47, v[114:115]
	global_store_dword v[158:159], v176, off
	v_lshl_add_u64 v[158:159], v[102:103], 0, v[170:171]
	global_store_dword v[158:159], v162, off
	s_waitcnt vmcnt(14)
	v_mul_f32_e32 v176, 0x3fb504f3, v182
	v_mad_i64_i32 v[158:159], s[48:49], v164, s47, v[114:115]
	s_waitcnt vmcnt(13)
	v_mul_f32_e32 v164, 0x3fb504f3, v183
	v_fmac_f32_e32 v176, v104, v175
	v_lshl_add_u64 v[162:163], v[158:159], 0, v[170:171]
	v_fmac_f32_e32 v164, v105, v175
	v_mad_i64_i32 v[104:105], s[48:49], v165, s47, v[114:115]
	global_store_dword v[162:163], v176, off
	v_lshl_add_u64 v[162:163], v[104:105], 0, v[170:171]
	global_store_dword v[162:163], v164, off
	v_mad_i64_i32 v[162:163], s[48:49], v166, s47, v[114:115]
	v_mul_f32_e32 v166, 0x3fb504f3, v185
	v_lshl_add_u64 v[164:165], v[162:163], 0, v[170:171]
	v_fmac_f32_e32 v166, v107, v175
	s_waitcnt vmcnt(13)
; DI int crow(int i, int h) { return (i & 3) + 8 * (i >> 2) + 4 * h; }
; DI const float* modp(const Params& p, int layer, int v) { return (const float*)(p.ws + OFF_MOD) + (size_t)(layer * 2 + v) * 12288; }
; template <int EPI>
; __device__ __forceinline__ void gemm_tile(const Params& p, int layer, const u16* __restrict__ A, const u16* __restrict__ Bt, int mt, int nt, char* lds) {
;     ...
;       } else if (EPI == 1) {
;         float* PRE = (float*)(p.ws + OFF_P);
;         const int v = m0 < NCTX ? 1 : 0;
;         const float g = modp(p, layer, v)[4096 + gc];
; #pragma unroll
;         for (int e = 0; e < 16; ++e) {
;           const int gr = grb + crow(e, h);
;           float xin;
;           if (layer == 0) xin = (gr < NCTX) ? p.ctx[(size_t)gr * DM + gc] : p.x[(size_t)(gr - NCTX) * DM + gc];
;           else xin = ((const float*)(p.ws + OFF_XRES))[(size_t)gr * LDF + gc];
;           PRE[(size_t)gr * LDF + gc] = ALPHA * xin + (DBG_NOATTN ? 0.f : g * acc[i][j][e]);
;         }
	v_mul_f32_e32 v176, 0x3fb504f3, v184
	v_fmac_f32_e32 v176, v106, v175
	v_mad_i64_i32 v[106:107], s[48:49], v167, s47, v[114:115]
	global_store_dword v[164:165], v176, off
	v_lshl_add_u64 v[164:165], v[106:107], 0, v[170:171]
	global_store_dword v[164:165], v166, off
	v_mul_f32_e32 v176, 0x3fb504f3, v186
	v_mad_i64_i32 v[164:165], s[48:49], v169, s47, v[114:115]
	v_fmac_f32_e32 v176, v108, v175
	v_lshl_add_u64 v[166:167], v[164:165], 0, v[170:171]
	global_store_dword v[166:167], v176, off
	s_waitcnt vmcnt(13)
	v_mul_f32_e32 v169, 0x3fb504f3, v188
	v_fmac_f32_e32 v169, v109, v175
	v_mad_i64_i32 v[108:109], s[48:49], v172, s47, v[114:115]
	v_lshl_add_u64 v[166:167], v[108:109], 0, v[170:171]
	global_store_dword v[166:167], v169, off
	v_mul_f32_e32 v169, 0x3fb504f3, v189
	v_mad_i64_i32 v[166:167], s[48:49], v173, s47, v[114:115]
	v_fmac_f32_e32 v169, v110, v175
	v_lshl_add_u64 v[172:173], v[166:167], 0, v[170:171]
	global_store_dword v[172:173], v169, off
	s_waitcnt vmcnt(14)
	v_mul_f32_e32 v169, 0x3fb504f3, v190
	v_fmac_f32_e32 v169, v111, v175
	v_mad_i64_i32 v[110:111], s[48:49], v174, s47, v[114:115]
	v_lshl_add_u64 v[170:171], v[110:111], 0, v[170:171]
	global_store_dword v[170:171], v169, off
	v_mov_b32_e32 v170, v129
	v_or_b32_e32 v169, 64, v130
	v_ashrrev_i32_e32 v171, 31, v170
	v_add_u32_e32 v172, v170, v169
	v_lshl_add_u64 v[170:171], v[170:171], 0, v[130:131]
	v_ashrrev_i32_e32 v173, 31, v172
	v_lshl_add_u64 v[170:171], v[170:171], 2, s[10:11]
	v_add_co_u32_e32 v170, vcc, s46, v170
	v_lshlrev_b64 v[172:173], 2, v[172:173]
	s_nop 0
	v_addc_co_u32_e32 v171, vcc, 0, v171, vcc
	v_lshl_add_u64 v[174:175], v[118:119], 0, v[172:173]
	global_load_dword v174, v[174:175], off
	s_nop 0
	global_load_dword v175, v[170:171], off offset:256
	v_lshl_add_u64 v[170:171], v[120:121], 0, v[172:173]
	global_load_dword v176, v[170:171], off
	v_lshl_add_u64 v[170:171], v[122:123], 0, v[172:173]
	global_load_dword v177, v[170:171], off
	v_lshl_add_u64 v[170:171], v[124:125], 0, v[172:173]
	global_load_dword v178, v[170:171], off
	v_lshl_add_u64 v[170:171], v[126:127], 0, v[172:173]
	global_load_dword v179, v[170:171], off
	v_lshl_add_u64 v[170:171], v[132:133], 0, v[172:173]
	global_load_dword v180, v[170:171], off
	v_lshl_add_u64 v[170:171], v[134:135], 0, v[172:173]
	global_load_dword v181, v[170:171], off
	v_lshl_add_u64 v[170:171], v[136:137], 0, v[172:173]
	global_load_dword v182, v[170:171], off
	v_lshl_add_u64 v[170:171], v[138:139], 0, v[172:173]
	global_load_dword v183, v[170:171], off
	v_lshl_add_u64 v[170:171], v[140:141], 0, v[172:173]
	global_load_dword v184, v[170:171], off
	v_lshl_add_u64 v[170:171], v[142:143], 0, v[172:173]
	global_load_dword v185, v[170:171], off
	v_lshl_add_u64 v[170:171], v[144:145], 0, v[172:173]
	global_load_dword v186, v[170:171], off
	v_lshl_add_u64 v[170:171], v[146:147], 0, v[172:173]
	global_load_dword v187, v[170:171], off
	v_lshl_add_u64 v[170:171], v[148:149], 0, v[172:173]
	global_load_dword v188, v[170:171], off
	v_lshl_add_u64 v[170:171], v[154:155], 0, v[172:173]
	global_load_dword v189, v[170:171], off
	v_lshl_add_u64 v[170:171], v[160:161], 0, v[172:173]
	global_load_dword v190, v[170:171], off
	v_lshl_add_u64 v[170:171], v[116:117], 0, v[172:173]
	s_waitcnt vmcnt(16)
	v_mul_f32_e32 v174, 0x3fb504f3, v174
	s_waitcnt vmcnt(15)
	v_fmac_f32_e32 v174, v80, v175
	global_store_dword v[170:171], v174, off
	s_waitcnt vmcnt(15)
	v_mul_f32_e32 v170, 0x3fb504f3, v176
	v_fmac_f32_e32 v170, v81, v175
	v_lshl_add_u64 v[80:81], v[96:97], 0, v[172:173]
	global_store_dword v[80:81], v170, off
	s_waitcnt vmcnt(15)
	v_mul_f32_e32 v170, 0x3fb504f3, v177
	v_fmac_f32_e32 v170, v82, v175
	v_lshl_add_u64 v[80:81], v[150:151], 0, v[172:173]
	s_waitcnt vmcnt(14)
	v_mul_f32_e32 v82, 0x3fb504f3, v178
	global_store_dword v[80:81], v170, off
	v_fmac_f32_e32 v82, v83, v175
	v_lshl_add_u64 v[80:81], v[98:99], 0, v[172:173]
	global_store_dword v[80:81], v82, off
	s_waitcnt vmcnt(15)
	v_mul_f32_e32 v82, 0x3fb504f3, v179
	v_fmac_f32_e32 v82, v84, v175
	v_lshl_add_u64 v[80:81], v[152:153], 0, v[172:173]
	global_store_dword v[80:81], v82, off
	s_waitcnt vmcnt(15)
	v_mul_f32_e32 v82, 0x3fb504f3, v180
	v_fmac_f32_e32 v82, v85, v175
	v_lshl_add_u64 v[80:81], v[100:101], 0, v[172:173]
	global_store_dword v[80:81], v82, off
	s_waitcnt vmcnt(15)
	v_mul_f32_e32 v82, 0x3fb504f3, v181
	v_fmac_f32_e32 v82, v86, v175
	v_lshl_add_u64 v[80:81], v[156:157], 0, v[172:173]
	global_store_dword v[80:81], v82, off
	s_waitcnt vmcnt(15)
	v_mul_f32_e32 v82, 0x3fb504f3, v182
	v_fmac_f32_e32 v82, v87, v175
	v_lshl_add_u64 v[80:81], v[102:103], 0, v[172:173]
	global_store_dword v[80:81], v82, off
	s_waitcnt vmcnt(15)
	v_mul_f32_e32 v82, 0x3fb504f3, v183
	v_fmac_f32_e32 v82, v88, v175
	v_lshl_add_u64 v[80:81], v[158:159], 0, v[172:173]
	global_store_dword v[80:81], v82, off
	s_waitcnt vmcnt(15)
	v_mul_f32_e32 v82, 0x3fb504f3, v184
	v_fmac_f32_e32 v82, v89, v175
	v_lshl_add_u64 v[80:81], v[104:105], 0, v[172:173]
	global_store_dword v[80:81], v82, off
	s_waitcnt vmcnt(15)
	v_mul_f32_e32 v82, 0x3fb504f3, v185
	v_fmac_f32_e32 v82, v90, v175
	v_lshl_add_u64 v[80:81], v[162:163], 0, v[172:173]
	global_store_dword v[80:81], v82, off
	s_waitcnt vmcnt(15)
	v_mul_f32_e32 v82, 0x3fb504f3, v186
	v_fmac_f32_e32 v82, v91, v175
	v_lshl_add_u64 v[80:81], v[106:107], 0, v[172:173]
	global_store_dword v[80:81], v82, off
	s_waitcnt vmcnt(15)
	v_mul_f32_e32 v82, 0x3fb504f3, v187
	v_fmac_f32_e32 v82, v92, v175
	v_lshl_add_u64 v[80:81], v[164:165], 0, v[172:173]
	global_store_dword v[80:81], v82, off
	s_waitcnt vmcnt(15)
; DI int crow(int i, int h) { return (i & 3) + 8 * (i >> 2) + 4 * h; }
; DI const float* modp(const Params& p, int layer, int v) { return (const float*)(p.ws + OFF_MOD) + (size_t)(layer * 2 + v) * 12288; }
; template <int EPI>
; __device__ __forceinline__ void gemm_tile(const Params& p, int layer, const u16* __restrict__ A, const u16* __restrict__ Bt, int mt, int nt, char* lds) {
;     ...
;       } else if (EPI == 1) {
;         float* PRE = (float*)(p.ws + OFF_P);
;         const int v = m0 < NCTX ? 1 : 0;
;         const float g = modp(p, layer, v)[4096 + gc];
; #pragma unroll
;         for (int e = 0; e < 16; ++e) {
;           const int gr = grb + crow(e, h);
;           float xin;
;           if (layer == 0) xin = (gr < NCTX) ? p.ctx[(size_t)gr * DM + gc] : p.x[(size_t)(gr - NCTX) * DM + gc];
;           else xin = ((const float*)(p.ws + OFF_XRES))[(size_t)gr * LDF + gc];
;           PRE[(size_t)gr * LDF + gc] = ALPHA * xin + (DBG_NOATTN ? 0.f : g * acc[i][j][e]);
;         }
	v_mul_f32_e32 v82, 0x3fb504f3, v188
	v_fmac_f32_e32 v82, v93, v175
	v_lshl_add_u64 v[80:81], v[108:109], 0, v[172:173]
	global_store_dword v[80:81], v82, off
	s_waitcnt vmcnt(15)
	v_mul_f32_e32 v82, 0x3fb504f3, v189
	v_fmac_f32_e32 v82, v94, v175
	v_lshl_add_u64 v[80:81], v[166:167], 0, v[172:173]
	global_store_dword v[80:81], v82, off
	s_waitcnt vmcnt(15)
	v_mul_f32_e32 v82, 0x3fb504f3, v190
	v_fmac_f32_e32 v82, v95, v175
	v_lshl_add_u64 v[80:81], v[110:111], 0, v[172:173]
	global_store_dword v[80:81], v82, off
	v_mov_b32_e32 v80, v129
	v_or_b32_e32 v170, 0x60, v130
	v_ashrrev_i32_e32 v81, 31, v80
	v_add_u32_e32 v82, v80, v170
	v_lshl_add_u64 v[80:81], v[80:81], 0, v[130:131]
	v_ashrrev_i32_e32 v83, 31, v82
	v_lshl_add_u64 v[80:81], v[80:81], 2, s[10:11]
	v_add_co_u32_e32 v80, vcc, s46, v80
	v_lshlrev_b64 v[82:83], 2, v[82:83]
	s_nop 0
	v_addc_co_u32_e32 v81, vcc, 0, v81, vcc
	v_lshl_add_u64 v[84:85], v[118:119], 0, v[82:83]
	global_load_dword v84, v[84:85], off
	s_nop 0
	global_load_dword v85, v[80:81], off offset:384
	v_lshl_add_u64 v[80:81], v[120:121], 0, v[82:83]
	global_load_dword v86, v[80:81], off
	v_lshl_add_u64 v[80:81], v[122:123], 0, v[82:83]
	global_load_dword v87, v[80:81], off
	v_lshl_add_u64 v[80:81], v[124:125], 0, v[82:83]
	global_load_dword v88, v[80:81], off
	v_lshl_add_u64 v[80:81], v[126:127], 0, v[82:83]
	global_load_dword v89, v[80:81], off
	v_lshl_add_u64 v[80:81], v[132:133], 0, v[82:83]
	global_load_dword v90, v[80:81], off
	v_lshl_add_u64 v[80:81], v[134:135], 0, v[82:83]
	global_load_dword v91, v[80:81], off
	v_lshl_add_u64 v[80:81], v[136:137], 0, v[82:83]
	global_load_dword v92, v[80:81], off
	v_lshl_add_u64 v[80:81], v[138:139], 0, v[82:83]
	global_load_dword v93, v[80:81], off
	v_lshl_add_u64 v[80:81], v[140:141], 0, v[82:83]
	global_load_dword v94, v[80:81], off
	v_lshl_add_u64 v[80:81], v[142:143], 0, v[82:83]
	global_load_dword v95, v[80:81], off
	v_lshl_add_u64 v[80:81], v[144:145], 0, v[82:83]
	global_load_dword v118, v[80:81], off
	v_lshl_add_u64 v[80:81], v[146:147], 0, v[82:83]
	global_load_dword v119, v[80:81], off
	v_lshl_add_u64 v[80:81], v[148:149], 0, v[82:83]
	global_load_dword v120, v[80:81], off
	v_lshl_add_u64 v[80:81], v[154:155], 0, v[82:83]
	global_load_dword v121, v[80:81], off
	v_lshl_add_u64 v[80:81], v[160:161], 0, v[82:83]
	global_load_dword v122, v[80:81], off
	v_lshl_add_u64 v[80:81], v[116:117], 0, v[82:83]
	s_waitcnt vmcnt(16)
	v_mul_f32_e32 v84, 0x3fb504f3, v84
	s_waitcnt vmcnt(15)
	v_fmac_f32_e32 v84, v64, v85
	global_store_dword v[80:81], v84, off
	s_waitcnt vmcnt(15)
	v_mul_f32_e32 v80, 0x3fb504f3, v86
	v_fmac_f32_e32 v80, v65, v85
	v_lshl_add_u64 v[64:65], v[96:97], 0, v[82:83]
	global_store_dword v[64:65], v80, off
	s_waitcnt vmcnt(15)
	v_mul_f32_e32 v80, 0x3fb504f3, v87
	v_fmac_f32_e32 v80, v66, v85
	v_lshl_add_u64 v[64:65], v[150:151], 0, v[82:83]
	s_waitcnt vmcnt(14)
	v_mul_f32_e32 v66, 0x3fb504f3, v88
	global_store_dword v[64:65], v80, off
	v_fmac_f32_e32 v66, v67, v85
	v_lshl_add_u64 v[64:65], v[98:99], 0, v[82:83]
	global_store_dword v[64:65], v66, off
	s_waitcnt vmcnt(15)
	v_mul_f32_e32 v66, 0x3fb504f3, v89
	v_fmac_f32_e32 v66, v68, v85
	v_lshl_add_u64 v[64:65], v[152:153], 0, v[82:83]
	global_store_dword v[64:65], v66, off
	s_waitcnt vmcnt(15)
	v_mul_f32_e32 v66, 0x3fb504f3, v90
	v_fmac_f32_e32 v66, v69, v85
	v_lshl_add_u64 v[64:65], v[100:101], 0, v[82:83]
	global_store_dword v[64:65], v66, off
	s_waitcnt vmcnt(15)
	v_mul_f32_e32 v66, 0x3fb504f3, v91
	v_fmac_f32_e32 v66, v70, v85
	v_lshl_add_u64 v[64:65], v[156:157], 0, v[82:83]
	global_store_dword v[64:65], v66, off
	s_waitcnt vmcnt(15)
	v_mul_f32_e32 v66, 0x3fb504f3, v92
	v_fmac_f32_e32 v66, v71, v85
	v_lshl_add_u64 v[64:65], v[102:103], 0, v[82:83]
	global_store_dword v[64:65], v66, off
	s_waitcnt vmcnt(15)
	v_mul_f32_e32 v66, 0x3fb504f3, v93
	v_fmac_f32_e32 v66, v72, v85
	v_lshl_add_u64 v[64:65], v[158:159], 0, v[82:83]
	global_store_dword v[64:65], v66, off
	s_waitcnt vmcnt(15)
	v_mul_f32_e32 v66, 0x3fb504f3, v94
	v_fmac_f32_e32 v66, v73, v85
	v_lshl_add_u64 v[64:65], v[104:105], 0, v[82:83]
	global_store_dword v[64:65], v66, off
	s_waitcnt vmcnt(15)
	v_mul_f32_e32 v66, 0x3fb504f3, v95
	v_fmac_f32_e32 v66, v74, v85
	v_lshl_add_u64 v[64:65], v[162:163], 0, v[82:83]
	global_store_dword v[64:65], v66, off
	s_waitcnt vmcnt(15)
	v_mul_f32_e32 v66, 0x3fb504f3, v118
	v_fmac_f32_e32 v66, v75, v85
	v_lshl_add_u64 v[64:65], v[106:107], 0, v[82:83]
	global_store_dword v[64:65], v66, off
	s_waitcnt vmcnt(15)
	v_mul_f32_e32 v66, 0x3fb504f3, v119
	v_fmac_f32_e32 v66, v76, v85
	v_lshl_add_u64 v[64:65], v[164:165], 0, v[82:83]
	global_store_dword v[64:65], v66, off
	s_waitcnt vmcnt(15)
	v_mul_f32_e32 v66, 0x3fb504f3, v120
	v_fmac_f32_e32 v66, v77, v85
	v_lshl_add_u64 v[64:65], v[108:109], 0, v[82:83]
	global_store_dword v[64:65], v66, off
	s_waitcnt vmcnt(15)
	v_mul_f32_e32 v66, 0x3fb504f3, v121
	v_fmac_f32_e32 v66, v78, v85
	v_lshl_add_u64 v[64:65], v[166:167], 0, v[82:83]
	global_store_dword v[64:65], v66, off
	s_waitcnt vmcnt(15)
; DI int crow(int i, int h) { return (i & 3) + 8 * (i >> 2) + 4 * h; }
; DI const float* modp(const Params& p, int layer, int v) { return (const float*)(p.ws + OFF_MOD) + (size_t)(layer * 2 + v) * 12288; }
; template <int EPI>
; __device__ __forceinline__ void gemm_tile(const Params& p, int layer, const u16* __restrict__ A, const u16* __restrict__ Bt, int mt, int nt, char* lds) {
;     ...
;       } else if (EPI == 1) {
;         float* PRE = (float*)(p.ws + OFF_P);
;         const int v = m0 < NCTX ? 1 : 0;
;         const float g = modp(p, layer, v)[4096 + gc];
; #pragma unroll
;         for (int e = 0; e < 16; ++e) {
;           const int gr = grb + crow(e, h);
;           float xin;
;           if (layer == 0) xin = (gr < NCTX) ? p.ctx[(size_t)gr * DM + gc] : p.x[(size_t)(gr - NCTX) * DM + gc];
;           else xin = ((const float*)(p.ws + OFF_XRES))[(size_t)gr * LDF + gc];
;           PRE[(size_t)gr * LDF + gc] = ALPHA * xin + (DBG_NOATTN ? 0.f : g * acc[i][j][e]);
;         }
	v_mul_f32_e32 v66, 0x3fb504f3, v122
	v_fmac_f32_e32 v66, v79, v85
	v_lshl_add_u64 v[64:65], v[110:111], 0, v[82:83]
	global_store_dword v[64:65], v66, off
	v_mov_b32_e32 v64, v129
	v_or_b32_e32 v74, 32, v128
	v_add_u32_e32 v64, v64, v130
	v_ashrrev_i32_e32 v65, 31, v64
	v_lshlrev_b64 v[64:65], 2, v[64:65]
	v_lshl_add_u64 v[66:67], s[10:11], 0, v[64:65]
	v_add_co_u32_e32 v66, vcc, s46, v66
	v_lshl_add_u64 v[68:69], s[8:9], 0, v[64:65]
	s_nop 0
	v_addc_co_u32_e32 v67, vcc, 0, v67, vcc
	v_mad_i64_i32 v[70:71], s[48:49], v74, s47, v[68:69]
	v_or_b32_e32 v80, 33, v128
	global_load_dword v70, v[70:71], off
	s_nop 0
	global_load_dword v71, v[66:67], off
	v_mad_i64_i32 v[66:67], s[48:49], v80, s47, v[68:69]
	global_load_dword v72, v[66:67], off
	v_or_b32_e32 v84, 34, v128
	v_mad_i64_i32 v[66:67], s[48:49], v84, s47, v[68:69]
	v_or_b32_e32 v85, 35, v128
	global_load_dword v73, v[66:67], off
	v_mad_i64_i32 v[66:67], s[48:49], v85, s47, v[68:69]
	global_load_dword v75, v[66:67], off
	v_or_b32_e32 v86, 40, v128
	v_mad_i64_i32 v[66:67], s[48:49], v86, s47, v[68:69]
	global_load_dword v76, v[66:67], off
	v_or_b32_e32 v87, 41, v128
	v_mad_i64_i32 v[66:67], s[48:49], v87, s47, v[68:69]
	global_load_dword v77, v[66:67], off
	v_or_b32_e32 v90, 42, v128
	v_mad_i64_i32 v[66:67], s[48:49], v90, s47, v[68:69]
	global_load_dword v78, v[66:67], off
	v_or_b32_e32 v91, 43, v128
	v_mad_i64_i32 v[66:67], s[48:49], v91, s47, v[68:69]
	global_load_dword v79, v[66:67], off
	v_or_b32_e32 v92, 48, v128
	v_mad_i64_i32 v[66:67], s[48:49], v92, s47, v[68:69]
	global_load_dword v81, v[66:67], off
	v_or_b32_e32 v93, 49, v128
	v_mad_i64_i32 v[66:67], s[48:49], v93, s47, v[68:69]
	global_load_dword v82, v[66:67], off
	v_or_b32_e32 v94, 50, v128
	v_mad_i64_i32 v[66:67], s[48:49], v94, s47, v[68:69]
	global_load_dword v83, v[66:67], off
	v_or_b32_e32 v95, 51, v128
	v_mad_i64_i32 v[66:67], s[48:49], v95, s47, v[68:69]
	global_load_dword v88, v[66:67], off
	v_or_b32_e32 v98, 56, v128
	v_mad_i64_i32 v[66:67], s[48:49], v98, s47, v[68:69]
	global_load_dword v89, v[66:67], off
	v_or_b32_e32 v99, 57, v128
	v_mad_i64_i32 v[66:67], s[48:49], v99, s47, v[68:69]
	global_load_dword v96, v[66:67], off
	v_or_b32_e32 v100, 58, v128
	v_mad_i64_i32 v[66:67], s[48:49], v100, s47, v[68:69]
	global_load_dword v97, v[66:67], off
	v_or_b32_e32 v101, 59, v128
	v_mad_i64_i32 v[66:67], s[48:49], v101, s47, v[68:69]
	global_load_dword v68, v[66:67], off
	v_lshl_add_u64 v[64:65], s[6:7], 0, v[64:65]
	v_mad_i64_i32 v[66:67], s[48:49], v74, s47, v[64:65]
	s_waitcnt vmcnt(16)
	v_mul_f32_e32 v69, 0x3fb504f3, v70
	s_waitcnt vmcnt(15)
	v_fmac_f32_e32 v69, v48, v71
	global_store_dword v[66:67], v69, off
	s_waitcnt vmcnt(15)
	v_mul_f32_e32 v66, 0x3fb504f3, v72
	v_fmac_f32_e32 v66, v49, v71
	v_mad_i64_i32 v[48:49], s[48:49], v80, s47, v[64:65]
	global_store_dword v[48:49], v66, off
	s_waitcnt vmcnt(15)
	v_mul_f32_e32 v66, 0x3fb504f3, v73
	v_fmac_f32_e32 v66, v50, v71
	v_mad_i64_i32 v[48:49], s[48:49], v84, s47, v[64:65]
	s_waitcnt vmcnt(14)
	v_mul_f32_e32 v50, 0x3fb504f3, v75
	global_store_dword v[48:49], v66, off
	v_fmac_f32_e32 v50, v51, v71
	v_mad_i64_i32 v[48:49], s[48:49], v85, s47, v[64:65]
	global_store_dword v[48:49], v50, off
	s_waitcnt vmcnt(15)
	v_mul_f32_e32 v50, 0x3fb504f3, v76
	v_fmac_f32_e32 v50, v52, v71
	v_mad_i64_i32 v[48:49], s[48:49], v86, s47, v[64:65]
	global_store_dword v[48:49], v50, off
	s_waitcnt vmcnt(15)
	v_mul_f32_e32 v50, 0x3fb504f3, v77
	v_fmac_f32_e32 v50, v53, v71
	v_mad_i64_i32 v[48:49], s[48:49], v87, s47, v[64:65]
	global_store_dword v[48:49], v50, off
	s_waitcnt vmcnt(15)
	v_mul_f32_e32 v50, 0x3fb504f3, v78
	v_fmac_f32_e32 v50, v54, v71
	v_mad_i64_i32 v[48:49], s[48:49], v90, s47, v[64:65]
	global_store_dword v[48:49], v50, off
	s_waitcnt vmcnt(15)
	v_mul_f32_e32 v50, 0x3fb504f3, v79
	v_fmac_f32_e32 v50, v55, v71
	v_mad_i64_i32 v[48:49], s[48:49], v91, s47, v[64:65]
	global_store_dword v[48:49], v50, off
	s_waitcnt vmcnt(15)
	v_mul_f32_e32 v50, 0x3fb504f3, v81
	v_fmac_f32_e32 v50, v56, v71
	v_mad_i64_i32 v[48:49], s[48:49], v92, s47, v[64:65]
	global_store_dword v[48:49], v50, off
	s_waitcnt vmcnt(15)
	v_mul_f32_e32 v50, 0x3fb504f3, v82
	v_fmac_f32_e32 v50, v57, v71
	v_mad_i64_i32 v[48:49], s[48:49], v93, s47, v[64:65]
	global_store_dword v[48:49], v50, off
	s_waitcnt vmcnt(15)
	v_mul_f32_e32 v50, 0x3fb504f3, v83
	v_fmac_f32_e32 v50, v58, v71
	v_mad_i64_i32 v[48:49], s[48:49], v94, s47, v[64:65]
	global_store_dword v[48:49], v50, off
	s_waitcnt vmcnt(15)
	v_mul_f32_e32 v50, 0x3fb504f3, v88
	v_fmac_f32_e32 v50, v59, v71
	v_mad_i64_i32 v[48:49], s[48:49], v95, s47, v[64:65]
	global_store_dword v[48:49], v50, off
	s_waitcnt vmcnt(15)
	v_mul_f32_e32 v50, 0x3fb504f3, v89
	v_fmac_f32_e32 v50, v60, v71
	v_mad_i64_i32 v[48:49], s[48:49], v98, s47, v[64:65]
	global_store_dword v[48:49], v50, off
	s_waitcnt vmcnt(15)
	v_mul_f32_e32 v50, 0x3fb504f3, v96
	v_fmac_f32_e32 v50, v61, v71
	v_mad_i64_i32 v[48:49], s[48:49], v99, s47, v[64:65]
	global_store_dword v[48:49], v50, off
	s_waitcnt vmcnt(15)
	v_mul_f32_e32 v50, 0x3fb504f3, v97
	v_fmac_f32_e32 v50, v62, v71
	v_mad_i64_i32 v[48:49], s[48:49], v100, s47, v[64:65]
	global_store_dword v[48:49], v50, off
	s_waitcnt vmcnt(15)
; DI int crow(int i, int h) { return (i & 3) + 8 * (i >> 2) + 4 * h; }
; DI const float* modp(const Params& p, int layer, int v) { return (const float*)(p.ws + OFF_MOD) + (size_t)(layer * 2 + v) * 12288; }
; template <int EPI>
; __device__ __forceinline__ void gemm_tile(const Params& p, int layer, const u16* __restrict__ A, const u16* __restrict__ Bt, int mt, int nt, char* lds) {
;     ...
;       } else if (EPI == 1) {
;         float* PRE = (float*)(p.ws + OFF_P);
;         const int v = m0 < NCTX ? 1 : 0;
;         const float g = modp(p, layer, v)[4096 + gc];
; #pragma unroll
;         for (int e = 0; e < 16; ++e) {
;           const int gr = grb + crow(e, h);
;           float xin;
;           if (layer == 0) xin = (gr < NCTX) ? p.ctx[(size_t)gr * DM + gc] : p.x[(size_t)(gr - NCTX) * DM + gc];
;           else xin = ((const float*)(p.ws + OFF_XRES))[(size_t)gr * LDF + gc];
;           PRE[(size_t)gr * LDF + gc] = ALPHA * xin + (DBG_NOATTN ? 0.f : g * acc[i][j][e]);
;         }
	v_mul_f32_e32 v50, 0x3fb504f3, v68
	v_fmac_f32_e32 v50, v63, v71
	v_mad_i64_i32 v[48:49], s[48:49], v101, s47, v[64:65]
	global_store_dword v[48:49], v50, off
	v_mov_b32_e32 v48, v129
	v_mad_i64_i32 v[50:51], s[48:49], v74, s47, v[112:113]
	v_add_u32_e32 v52, v48, v168
	v_ashrrev_i32_e32 v53, 31, v52
	v_ashrrev_i32_e32 v49, 31, v48
	v_lshlrev_b64 v[96:97], 2, v[52:53]
	v_lshl_add_u64 v[48:49], v[48:49], 0, v[130:131]
	v_lshl_add_u64 v[52:53], v[50:51], 0, v[96:97]
	v_lshl_add_u64 v[48:49], v[48:49], 2, s[10:11]
	global_load_dword v70, v[52:53], off
	v_add_co_u32_e32 v48, vcc, s46, v48
	v_mad_i64_i32 v[54:55], s[48:49], v84, s47, v[112:113]
	s_nop 0
	v_addc_co_u32_e32 v49, vcc, 0, v49, vcc
	global_load_dword v102, v[48:49], off offset:128
	v_mad_i64_i32 v[52:53], s[48:49], v80, s47, v[112:113]
	v_lshl_add_u64 v[48:49], v[52:53], 0, v[96:97]
	global_load_dword v81, v[48:49], off
	v_lshl_add_u64 v[48:49], v[54:55], 0, v[96:97]
	v_mad_i64_i32 v[56:57], s[48:49], v85, s47, v[112:113]
	global_load_dword v103, v[48:49], off
	v_lshl_add_u64 v[48:49], v[56:57], 0, v[96:97]
	global_load_dword v104, v[48:49], off
	v_mad_i64_i32 v[58:59], s[48:49], v86, s47, v[112:113]
	v_lshl_add_u64 v[48:49], v[58:59], 0, v[96:97]
	v_mad_i64_i32 v[60:61], s[48:49], v87, s47, v[112:113]
	global_load_dword v105, v[48:49], off
	v_lshl_add_u64 v[48:49], v[60:61], 0, v[96:97]
	global_load_dword v106, v[48:49], off
	v_mad_i64_i32 v[62:63], s[48:49], v90, s47, v[112:113]
	v_lshl_add_u64 v[48:49], v[62:63], 0, v[96:97]
	v_mad_i64_i32 v[64:65], s[48:49], v91, s47, v[112:113]
	global_load_dword v107, v[48:49], off
	v_lshl_add_u64 v[48:49], v[64:65], 0, v[96:97]
	v_mad_i64_i32 v[66:67], s[48:49], v92, s47, v[112:113]
	global_load_dword v108, v[48:49], off
	v_lshl_add_u64 v[48:49], v[66:67], 0, v[96:97]
	v_mad_i64_i32 v[68:69], s[48:49], v93, s47, v[112:113]
	global_load_dword v109, v[48:49], off
	v_lshl_add_u64 v[48:49], v[68:69], 0, v[96:97]
	global_load_dword v110, v[48:49], off
	v_mad_i64_i32 v[72:73], s[48:49], v95, s47, v[112:113]
	v_mad_i64_i32 v[88:89], s[48:49], v101, s47, v[112:113]
	s_waitcnt vmcnt(10)
	v_mul_f32_e32 v82, 0x3fb504f3, v70
	v_mad_i64_i32 v[70:71], s[48:49], v94, s47, v[112:113]
	v_lshl_add_u64 v[48:49], v[70:71], 0, v[96:97]
	global_load_dword v111, v[48:49], off
	v_lshl_add_u64 v[48:49], v[72:73], 0, v[96:97]
	global_load_dword v116, v[48:49], off
	v_mad_i64_i32 v[48:49], s[48:49], v74, s47, v[114:115]
	s_waitcnt vmcnt(11)
	v_fmac_f32_e32 v82, v32, v102
	v_lshl_add_u64 v[76:77], v[48:49], 0, v[96:97]
	v_mad_i64_i32 v[74:75], s[48:49], v98, s47, v[112:113]
	global_store_dword v[76:77], v82, off
	s_waitcnt vmcnt(11)
	v_mul_f32_e32 v118, 0x3fb504f3, v81
	v_mad_i64_i32 v[82:83], s[48:49], v100, s47, v[112:113]
	v_lshl_add_u64 v[78:79], v[74:75], 0, v[96:97]
	v_mad_i64_i32 v[76:77], s[48:49], v99, s47, v[112:113]
	v_fmac_f32_e32 v118, v33, v102
	v_lshl_add_u64 v[32:33], v[82:83], 0, v[96:97]
	global_load_dword v117, v[78:79], off
	global_load_dword v120, v[32:33], off
	v_lshl_add_u64 v[78:79], v[76:77], 0, v[96:97]
	global_load_dword v119, v[78:79], off
	v_mad_i64_i32 v[32:33], s[48:49], v80, s47, v[114:115]
	v_lshl_add_u64 v[80:81], v[88:89], 0, v[96:97]
	global_load_dword v112, v[80:81], off
	v_lshl_add_u64 v[78:79], v[32:33], 0, v[96:97]
	global_store_dword v[78:79], v118, off
	s_waitcnt vmcnt(15)
	v_mul_f32_e32 v103, 0x3fb504f3, v103
	v_mad_i64_i32 v[78:79], s[48:49], v84, s47, v[114:115]
	s_waitcnt vmcnt(14)
	v_mul_f32_e32 v84, 0x3fb504f3, v104
	v_fmac_f32_e32 v103, v34, v102
	v_lshl_add_u64 v[80:81], v[78:79], 0, v[96:97]
	v_fmac_f32_e32 v84, v35, v102
	v_mad_i64_i32 v[34:35], s[48:49], v85, s47, v[114:115]
	global_store_dword v[80:81], v103, off
	v_lshl_add_u64 v[80:81], v[34:35], 0, v[96:97]
	global_store_dword v[80:81], v84, off
	s_waitcnt vmcnt(15)
	v_mul_f32_e32 v103, 0x3fb504f3, v105
	v_mad_i64_i32 v[80:81], s[48:49], v86, s47, v[114:115]
	s_waitcnt vmcnt(14)
	v_mul_f32_e32 v86, 0x3fb504f3, v106
	v_fmac_f32_e32 v103, v36, v102
	v_lshl_add_u64 v[84:85], v[80:81], 0, v[96:97]
	v_fmac_f32_e32 v86, v37, v102
	v_mad_i64_i32 v[36:37], s[48:49], v87, s47, v[114:115]
	global_store_dword v[84:85], v103, off
	v_lshl_add_u64 v[84:85], v[36:37], 0, v[96:97]
	global_store_dword v[84:85], v86, off
	s_waitcnt vmcnt(15)
	v_mul_f32_e32 v103, 0x3fb504f3, v107
	v_mad_i64_i32 v[84:85], s[48:49], v90, s47, v[114:115]
	s_waitcnt vmcnt(14)
	v_mul_f32_e32 v90, 0x3fb504f3, v108
	v_fmac_f32_e32 v103, v38, v102
	v_lshl_add_u64 v[86:87], v[84:85], 0, v[96:97]
	v_fmac_f32_e32 v90, v39, v102
	v_mad_i64_i32 v[38:39], s[48:49], v91, s47, v[114:115]
	global_store_dword v[86:87], v103, off
	v_lshl_add_u64 v[86:87], v[38:39], 0, v[96:97]
	global_store_dword v[86:87], v90, off
	s_waitcnt vmcnt(15)
	v_mul_f32_e32 v103, 0x3fb504f3, v109
	v_mad_i64_i32 v[86:87], s[48:49], v92, s47, v[114:115]
	s_waitcnt vmcnt(14)
	v_mul_f32_e32 v92, 0x3fb504f3, v110
	v_fmac_f32_e32 v103, v40, v102
	v_lshl_add_u64 v[90:91], v[86:87], 0, v[96:97]
	v_fmac_f32_e32 v92, v41, v102
	v_mad_i64_i32 v[40:41], s[48:49], v93, s47, v[114:115]
	global_store_dword v[90:91], v103, off
	v_lshl_add_u64 v[90:91], v[40:41], 0, v[96:97]
	global_store_dword v[90:91], v92, off
	v_mad_i64_i32 v[90:91], s[48:49], v94, s47, v[114:115]
	v_lshl_add_u64 v[92:93], v[90:91], 0, v[96:97]
	s_waitcnt vmcnt(15)
	v_mul_f32_e32 v103, 0x3fb504f3, v111
	v_fmac_f32_e32 v103, v42, v102
	s_waitcnt vmcnt(14)
	v_mul_f32_e32 v94, 0x3fb504f3, v116
	v_fmac_f32_e32 v94, v43, v102
	v_mad_i64_i32 v[42:43], s[48:49], v95, s47, v[114:115]
	global_store_dword v[92:93], v103, off
	v_lshl_add_u64 v[92:93], v[42:43], 0, v[96:97]
	global_store_dword v[92:93], v94, off
	v_mad_i64_i32 v[92:93], s[48:49], v98, s47, v[114:115]
	v_lshl_add_u64 v[94:95], v[92:93], 0, v[96:97]
	s_waitcnt vmcnt(14)
; DI int crow(int i, int h) { return (i & 3) + 8 * (i >> 2) + 4 * h; }
; DI const float* modp(const Params& p, int layer, int v) { return (const float*)(p.ws + OFF_MOD) + (size_t)(layer * 2 + v) * 12288; }
; template <int EPI>
; __device__ __forceinline__ void gemm_tile(const Params& p, int layer, const u16* __restrict__ A, const u16* __restrict__ Bt, int mt, int nt, char* lds) {
;     ...
;       } else if (EPI == 1) {
;         float* PRE = (float*)(p.ws + OFF_P);
;         const int v = m0 < NCTX ? 1 : 0;
;         const float g = modp(p, layer, v)[4096 + gc];
; #pragma unroll
;         for (int e = 0; e < 16; ++e) {
;           const int gr = grb + crow(e, h);
;           float xin;
;           if (layer == 0) xin = (gr < NCTX) ? p.ctx[(size_t)gr * DM + gc] : p.x[(size_t)(gr - NCTX) * DM + gc];
;           else xin = ((const float*)(p.ws + OFF_XRES))[(size_t)gr * LDF + gc];
;           PRE[(size_t)gr * LDF + gc] = ALPHA * xin + (DBG_NOATTN ? 0.f : g * acc[i][j][e]);
;         }
	v_mul_f32_e32 v103, 0x3fb504f3, v117
	v_fmac_f32_e32 v103, v44, v102
	global_store_dword v[94:95], v103, off
	s_waitcnt vmcnt(13)
	v_mul_f32_e32 v98, 0x3fb504f3, v119
	v_fmac_f32_e32 v98, v45, v102
	v_mad_i64_i32 v[44:45], s[48:49], v99, s47, v[114:115]
	v_lshl_add_u64 v[94:95], v[44:45], 0, v[96:97]
	global_store_dword v[94:95], v98, off
	v_mul_f32_e32 v103, 0x3fb504f3, v120
	v_mad_i64_i32 v[94:95], s[48:49], v100, s47, v[114:115]
	v_fmac_f32_e32 v103, v46, v102
	v_lshl_add_u64 v[98:99], v[94:95], 0, v[96:97]
	global_store_dword v[98:99], v103, off
	s_waitcnt vmcnt(14)
	v_mul_f32_e32 v98, 0x3fb504f3, v112
	v_fmac_f32_e32 v98, v47, v102
	v_mad_i64_i32 v[46:47], s[48:49], v101, s47, v[114:115]
	v_lshl_add_u64 v[96:97], v[46:47], 0, v[96:97]
	global_store_dword v[96:97], v98, off
	v_mov_b32_e32 v96, v129
	s_nop 0
	v_ashrrev_i32_e32 v97, 31, v96
	v_add_u32_e32 v98, v96, v169
	v_lshl_add_u64 v[96:97], v[96:97], 0, v[130:131]
	v_ashrrev_i32_e32 v99, 31, v98
	v_lshl_add_u64 v[96:97], v[96:97], 2, s[10:11]
	v_add_co_u32_e32 v96, vcc, s46, v96
	v_lshlrev_b64 v[98:99], 2, v[98:99]
	s_nop 0
	v_addc_co_u32_e32 v97, vcc, 0, v97, vcc
	v_lshl_add_u64 v[100:101], v[50:51], 0, v[98:99]
	global_load_dword v100, v[100:101], off
	s_nop 0
	global_load_dword v101, v[96:97], off offset:256
	v_lshl_add_u64 v[96:97], v[52:53], 0, v[98:99]
	global_load_dword v102, v[96:97], off
	v_lshl_add_u64 v[96:97], v[54:55], 0, v[98:99]
	global_load_dword v103, v[96:97], off
	v_lshl_add_u64 v[96:97], v[56:57], 0, v[98:99]
	global_load_dword v104, v[96:97], off
	v_lshl_add_u64 v[96:97], v[58:59], 0, v[98:99]
	global_load_dword v105, v[96:97], off
	v_lshl_add_u64 v[96:97], v[60:61], 0, v[98:99]
	global_load_dword v106, v[96:97], off
	v_lshl_add_u64 v[96:97], v[62:63], 0, v[98:99]
	global_load_dword v107, v[96:97], off
	v_lshl_add_u64 v[96:97], v[64:65], 0, v[98:99]
	global_load_dword v108, v[96:97], off
	v_lshl_add_u64 v[96:97], v[66:67], 0, v[98:99]
	global_load_dword v109, v[96:97], off
	v_lshl_add_u64 v[96:97], v[68:69], 0, v[98:99]
	global_load_dword v110, v[96:97], off
	v_lshl_add_u64 v[96:97], v[70:71], 0, v[98:99]
	global_load_dword v111, v[96:97], off
	v_lshl_add_u64 v[96:97], v[72:73], 0, v[98:99]
	global_load_dword v112, v[96:97], off
	v_lshl_add_u64 v[96:97], v[74:75], 0, v[98:99]
	global_load_dword v113, v[96:97], off
	v_lshl_add_u64 v[96:97], v[76:77], 0, v[98:99]
	global_load_dword v114, v[96:97], off
	v_lshl_add_u64 v[96:97], v[82:83], 0, v[98:99]
	global_load_dword v115, v[96:97], off
	v_lshl_add_u64 v[96:97], v[88:89], 0, v[98:99]
	global_load_dword v116, v[96:97], off
	v_lshl_add_u64 v[96:97], v[48:49], 0, v[98:99]
	s_waitcnt vmcnt(16)
	v_mul_f32_e32 v100, 0x3fb504f3, v100
	s_waitcnt vmcnt(15)
	v_fmac_f32_e32 v100, v16, v101
	global_store_dword v[96:97], v100, off
	s_waitcnt vmcnt(15)
	v_mul_f32_e32 v96, 0x3fb504f3, v102
	v_fmac_f32_e32 v96, v17, v101
	v_lshl_add_u64 v[16:17], v[32:33], 0, v[98:99]
	global_store_dword v[16:17], v96, off
	s_waitcnt vmcnt(15)
	v_mul_f32_e32 v96, 0x3fb504f3, v103
	v_fmac_f32_e32 v96, v18, v101
	v_lshl_add_u64 v[16:17], v[78:79], 0, v[98:99]
	s_waitcnt vmcnt(14)
	v_mul_f32_e32 v18, 0x3fb504f3, v104
	global_store_dword v[16:17], v96, off
	v_fmac_f32_e32 v18, v19, v101
	v_lshl_add_u64 v[16:17], v[34:35], 0, v[98:99]
	global_store_dword v[16:17], v18, off
	s_waitcnt vmcnt(15)
	v_mul_f32_e32 v18, 0x3fb504f3, v105
	v_fmac_f32_e32 v18, v20, v101
	v_lshl_add_u64 v[16:17], v[80:81], 0, v[98:99]
	global_store_dword v[16:17], v18, off
	s_waitcnt vmcnt(15)
	v_mul_f32_e32 v18, 0x3fb504f3, v106
	v_fmac_f32_e32 v18, v21, v101
	v_lshl_add_u64 v[16:17], v[36:37], 0, v[98:99]
	global_store_dword v[16:17], v18, off
	s_waitcnt vmcnt(15)
	v_mul_f32_e32 v18, 0x3fb504f3, v107
	v_fmac_f32_e32 v18, v22, v101
	v_lshl_add_u64 v[16:17], v[84:85], 0, v[98:99]
	global_store_dword v[16:17], v18, off
	s_waitcnt vmcnt(15)
	v_mul_f32_e32 v18, 0x3fb504f3, v108
	v_fmac_f32_e32 v18, v23, v101
	v_lshl_add_u64 v[16:17], v[38:39], 0, v[98:99]
	global_store_dword v[16:17], v18, off
	s_waitcnt vmcnt(15)
	v_mul_f32_e32 v18, 0x3fb504f3, v109
	v_fmac_f32_e32 v18, v24, v101
	v_lshl_add_u64 v[16:17], v[86:87], 0, v[98:99]
	global_store_dword v[16:17], v18, off
	s_waitcnt vmcnt(15)
	v_mul_f32_e32 v18, 0x3fb504f3, v110
	v_fmac_f32_e32 v18, v25, v101
	v_lshl_add_u64 v[16:17], v[40:41], 0, v[98:99]
	global_store_dword v[16:17], v18, off
	s_waitcnt vmcnt(15)
	v_mul_f32_e32 v18, 0x3fb504f3, v111
	v_fmac_f32_e32 v18, v26, v101
	v_lshl_add_u64 v[16:17], v[90:91], 0, v[98:99]
	global_store_dword v[16:17], v18, off
	s_waitcnt vmcnt(15)
	v_mul_f32_e32 v18, 0x3fb504f3, v112
	v_fmac_f32_e32 v18, v27, v101
	v_lshl_add_u64 v[16:17], v[42:43], 0, v[98:99]
	global_store_dword v[16:17], v18, off
	s_waitcnt vmcnt(15)
	v_mul_f32_e32 v18, 0x3fb504f3, v113
	v_fmac_f32_e32 v18, v28, v101
	v_lshl_add_u64 v[16:17], v[92:93], 0, v[98:99]
	global_store_dword v[16:17], v18, off
	s_waitcnt vmcnt(15)
; DI int crow(int i, int h) { return (i & 3) + 8 * (i >> 2) + 4 * h; }
; DI const float* modp(const Params& p, int layer, int v) { return (const float*)(p.ws + OFF_MOD) + (size_t)(layer * 2 + v) * 12288; }
; template <int EPI>
; __device__ __forceinline__ void gemm_tile(const Params& p, int layer, const u16* __restrict__ A, const u16* __restrict__ Bt, int mt, int nt, char* lds) {
;     ...
;       } else if (EPI == 1) {
;         float* PRE = (float*)(p.ws + OFF_P);
;         const int v = m0 < NCTX ? 1 : 0;
;         const float g = modp(p, layer, v)[4096 + gc];
; #pragma unroll
;         for (int e = 0; e < 16; ++e) {
;           const int gr = grb + crow(e, h);
;           float xin;
;           if (layer == 0) xin = (gr < NCTX) ? p.ctx[(size_t)gr * DM + gc] : p.x[(size_t)(gr - NCTX) * DM + gc];
;           else xin = ((const float*)(p.ws + OFF_XRES))[(size_t)gr * LDF + gc];
;           PRE[(size_t)gr * LDF + gc] = ALPHA * xin + (DBG_NOATTN ? 0.f : g * acc[i][j][e]);
;         }
	v_mul_f32_e32 v18, 0x3fb504f3, v114
	v_fmac_f32_e32 v18, v29, v101
	v_lshl_add_u64 v[16:17], v[44:45], 0, v[98:99]
	global_store_dword v[16:17], v18, off
	s_waitcnt vmcnt(15)
	v_mul_f32_e32 v18, 0x3fb504f3, v115
	v_fmac_f32_e32 v18, v30, v101
	v_lshl_add_u64 v[16:17], v[94:95], 0, v[98:99]
	global_store_dword v[16:17], v18, off
	s_waitcnt vmcnt(15)
	v_mul_f32_e32 v18, 0x3fb504f3, v116
	v_fmac_f32_e32 v18, v31, v101
	v_lshl_add_u64 v[16:17], v[46:47], 0, v[98:99]
	global_store_dword v[16:17], v18, off
	v_mov_b32_e32 v16, v129
	s_nop 0
	v_ashrrev_i32_e32 v17, 31, v16
	v_add_u32_e32 v18, v16, v170
	v_lshl_add_u64 v[16:17], v[16:17], 0, v[130:131]
	v_ashrrev_i32_e32 v19, 31, v18
	v_lshl_add_u64 v[16:17], v[16:17], 2, s[10:11]
	v_add_co_u32_e32 v16, vcc, s46, v16
	v_lshlrev_b64 v[18:19], 2, v[18:19]
	s_nop 0
	v_addc_co_u32_e32 v17, vcc, 0, v17, vcc
	v_lshl_add_u64 v[20:21], v[50:51], 0, v[18:19]
	global_load_dword v20, v[20:21], off
	s_nop 0
	global_load_dword v21, v[16:17], off offset:384
	v_lshl_add_u64 v[16:17], v[52:53], 0, v[18:19]
	global_load_dword v22, v[16:17], off
	v_lshl_add_u64 v[16:17], v[54:55], 0, v[18:19]
	global_load_dword v23, v[16:17], off
	v_lshl_add_u64 v[16:17], v[56:57], 0, v[18:19]
	global_load_dword v24, v[16:17], off
	v_lshl_add_u64 v[16:17], v[58:59], 0, v[18:19]
	global_load_dword v25, v[16:17], off
	v_lshl_add_u64 v[16:17], v[60:61], 0, v[18:19]
	global_load_dword v26, v[16:17], off
	v_lshl_add_u64 v[16:17], v[62:63], 0, v[18:19]
	global_load_dword v27, v[16:17], off
	v_lshl_add_u64 v[16:17], v[64:65], 0, v[18:19]
	global_load_dword v28, v[16:17], off
	v_lshl_add_u64 v[16:17], v[66:67], 0, v[18:19]
	global_load_dword v29, v[16:17], off
	v_lshl_add_u64 v[16:17], v[68:69], 0, v[18:19]
	global_load_dword v30, v[16:17], off
	v_lshl_add_u64 v[16:17], v[70:71], 0, v[18:19]
	global_load_dword v31, v[16:17], off
	v_lshl_add_u64 v[16:17], v[72:73], 0, v[18:19]
	global_load_dword v50, v[16:17], off
	v_lshl_add_u64 v[16:17], v[74:75], 0, v[18:19]
	global_load_dword v51, v[16:17], off
	v_lshl_add_u64 v[16:17], v[76:77], 0, v[18:19]
	global_load_dword v52, v[16:17], off
	v_lshl_add_u64 v[16:17], v[82:83], 0, v[18:19]
	global_load_dword v53, v[16:17], off
	v_lshl_add_u64 v[16:17], v[88:89], 0, v[18:19]
	global_load_dword v54, v[16:17], off
	v_lshl_add_u64 v[16:17], v[48:49], 0, v[18:19]
	s_waitcnt vmcnt(16)
	v_mul_f32_e32 v20, 0x3fb504f3, v20
	s_waitcnt vmcnt(15)
	v_fmac_f32_e32 v20, v0, v21
	global_store_dword v[16:17], v20, off
	s_waitcnt vmcnt(15)
	v_mul_f32_e32 v16, 0x3fb504f3, v22
	v_fmac_f32_e32 v16, v1, v21
	v_lshl_add_u64 v[0:1], v[32:33], 0, v[18:19]
	global_store_dword v[0:1], v16, off
	s_waitcnt vmcnt(15)
	v_mul_f32_e32 v16, 0x3fb504f3, v23
	v_fmac_f32_e32 v16, v2, v21
	v_lshl_add_u64 v[0:1], v[78:79], 0, v[18:19]
	s_waitcnt vmcnt(14)
	v_mul_f32_e32 v2, 0x3fb504f3, v24
	global_store_dword v[0:1], v16, off
	v_fmac_f32_e32 v2, v3, v21
	v_lshl_add_u64 v[0:1], v[34:35], 0, v[18:19]
	global_store_dword v[0:1], v2, off
	s_waitcnt vmcnt(15)
	v_mul_f32_e32 v2, 0x3fb504f3, v25
	v_fmac_f32_e32 v2, v4, v21
	v_lshl_add_u64 v[0:1], v[80:81], 0, v[18:19]
	global_store_dword v[0:1], v2, off
	s_waitcnt vmcnt(15)
	v_mul_f32_e32 v2, 0x3fb504f3, v26
	v_fmac_f32_e32 v2, v5, v21
	v_lshl_add_u64 v[0:1], v[36:37], 0, v[18:19]
	global_store_dword v[0:1], v2, off
	s_waitcnt vmcnt(15)
	v_mul_f32_e32 v2, 0x3fb504f3, v27
	v_fmac_f32_e32 v2, v6, v21
	v_lshl_add_u64 v[0:1], v[84:85], 0, v[18:19]
	global_store_dword v[0:1], v2, off
	s_waitcnt vmcnt(15)
	v_mul_f32_e32 v2, 0x3fb504f3, v28
	v_fmac_f32_e32 v2, v7, v21
	v_lshl_add_u64 v[0:1], v[38:39], 0, v[18:19]
	global_store_dword v[0:1], v2, off
	s_waitcnt vmcnt(15)
	v_mul_f32_e32 v2, 0x3fb504f3, v29
	v_fmac_f32_e32 v2, v8, v21
	v_lshl_add_u64 v[0:1], v[86:87], 0, v[18:19]
	global_store_dword v[0:1], v2, off
	s_waitcnt vmcnt(15)
	v_mul_f32_e32 v2, 0x3fb504f3, v30
	v_fmac_f32_e32 v2, v9, v21
	v_lshl_add_u64 v[0:1], v[40:41], 0, v[18:19]
	global_store_dword v[0:1], v2, off
	s_waitcnt vmcnt(15)
	v_mul_f32_e32 v2, 0x3fb504f3, v31
	v_fmac_f32_e32 v2, v10, v21
	v_lshl_add_u64 v[0:1], v[90:91], 0, v[18:19]
	global_store_dword v[0:1], v2, off
	s_waitcnt vmcnt(15)
	v_mul_f32_e32 v2, 0x3fb504f3, v50
	v_fmac_f32_e32 v2, v11, v21
	v_lshl_add_u64 v[0:1], v[42:43], 0, v[18:19]
	global_store_dword v[0:1], v2, off
	s_waitcnt vmcnt(15)
	v_mul_f32_e32 v2, 0x3fb504f3, v51
	v_fmac_f32_e32 v2, v12, v21
	v_lshl_add_u64 v[0:1], v[92:93], 0, v[18:19]
	global_store_dword v[0:1], v2, off
	s_waitcnt vmcnt(15)
	v_mul_f32_e32 v2, 0x3fb504f3, v52
	v_fmac_f32_e32 v2, v13, v21
	v_lshl_add_u64 v[0:1], v[44:45], 0, v[18:19]
	global_store_dword v[0:1], v2, off
	s_waitcnt vmcnt(15)
	v_mul_f32_e32 v2, 0x3fb504f3, v53
	v_fmac_f32_e32 v2, v14, v21
	v_lshl_add_u64 v[0:1], v[94:95], 0, v[18:19]
	global_store_dword v[0:1], v2, off
	s_waitcnt vmcnt(15)
	v_mul_f32_e32 v2, 0x3fb504f3, v54
	v_fmac_f32_e32 v2, v15, v21
	v_lshl_add_u64 v[0:1], v[46:47], 0, v[18:19]
	global_store_dword v[0:1], v2, off
	s_branch .LBB0_2382

; template <int EPI>
; __device__ __forceinline__ void gemm_tile(const Params& p, int layer, const u16* __restrict__ A, const u16* __restrict__ Bt, int mt, int nt, char* lds) {
;     ...
;   for (int kt = 0; kt < NK - 1; ++kt) {
;     G_SLAB(true, kt + 1)
;     __syncthreads();
;     G_WRITE();
;     __syncthreads();
;   }
.LBB0_2499:
	ds_read_b128 v[146:149], v130
	ds_read_b128 v[150:153], v130 offset:4608
	ds_read_b128 v[154:157], v131 offset:18432
	ds_read_b128 v[158:161], v131 offset:23040
	ds_read_b128 v[162:165], v131 offset:27648
	ds_read_b128 v[166:169], v131 offset:32256
	ds_read_b128 v[170:173], v130 offset:32
	ds_read_b128 v[174:177], v130 offset:4640
	ds_read_b128 v[178:181], v131 offset:18464
	ds_read_b128 v[182:185], v131 offset:23072
	ds_read_b128 v[186:189], v131 offset:27680
	ds_read_b128 v[190:193], v131 offset:32288
	s_waitcnt lgkmcnt(9)
	v_mfma_f32_32x32x16_bf16 v[112:127], v[146:149], v[154:157], v[112:127]
	s_waitcnt lgkmcnt(8)
	v_mfma_f32_32x32x16_bf16 v[96:111], v[146:149], v[158:161], v[96:111]
	s_waitcnt lgkmcnt(7)
	v_mfma_f32_32x32x16_bf16 v[80:95], v[146:149], v[162:165], v[80:95]
	s_waitcnt lgkmcnt(6)
	v_mfma_f32_32x32x16_bf16 v[64:79], v[146:149], v[166:169], v[64:79]
	v_lshl_add_u64 v[212:213], v[134:135], 0, s[18:19]
	v_add_co_u32_e32 v146, vcc, s29, v212
	v_lshl_add_u64 v[228:229], v[136:137], 0, s[18:19]
	s_nop 0
	v_addc_co_u32_e32 v147, vcc, 0, v213, vcc
	v_add_co_u32_e32 v194, vcc, s30, v228
	s_nop 1
	v_addc_co_u32_e32 v195, vcc, 0, v229, vcc
	global_load_dwordx4 v[146:149], v[146:147], off offset:384
	s_nop 0
	global_load_dwordx4 v[194:197], v[194:195], off offset:128
	v_mfma_f32_32x32x16_bf16 v[48:63], v[150:153], v[154:157], v[48:63]
	v_mfma_f32_32x32x16_bf16 v[32:47], v[150:153], v[158:161], v[32:47]
	v_mfma_f32_32x32x16_bf16 v[16:31], v[150:153], v[162:165], v[16:31]
	v_mfma_f32_32x32x16_bf16 v[0:15], v[150:153], v[166:169], v[0:15]
	v_add_co_u32_e32 v150, vcc, s31, v228
	s_nop 1
	v_addc_co_u32_e32 v151, vcc, 0, v229, vcc
	global_load_dwordx4 v[150:153], v[150:151], off offset:128
	ds_read_b128 v[154:157], v130 offset:64
	ds_read_b128 v[158:161], v130 offset:4672
	ds_read_b128 v[162:165], v131 offset:18496
	ds_read_b128 v[166:169], v131 offset:23104
	ds_read_b128 v[198:201], v131 offset:27712
	ds_read_b128 v[202:205], v131 offset:32320
	s_waitcnt lgkmcnt(9)
	v_mfma_f32_32x32x16_bf16 v[112:127], v[170:173], v[178:181], v[112:127]
	s_waitcnt lgkmcnt(8)
	v_mfma_f32_32x32x16_bf16 v[96:111], v[170:173], v[182:185], v[96:111]
	s_waitcnt lgkmcnt(7)
	v_mfma_f32_32x32x16_bf16 v[80:95], v[170:173], v[186:189], v[80:95]
	s_waitcnt lgkmcnt(6)
	v_mfma_f32_32x32x16_bf16 v[64:79], v[170:173], v[190:193], v[64:79]
	v_add_co_u32_e32 v170, vcc, s36, v212
	s_nop 1
	v_addc_co_u32_e32 v171, vcc, 0, v213, vcc
	v_add_co_u32_e32 v206, vcc, s37, v228
	s_nop 1
	v_addc_co_u32_e32 v207, vcc, 0, v229, vcc
	global_load_dwordx4 v[170:173], v[170:171], off offset:384
	s_nop 0
	global_load_dwordx4 v[206:209], v[206:207], off offset:128
	v_mfma_f32_32x32x16_bf16 v[48:63], v[174:177], v[178:181], v[48:63]
	v_mfma_f32_32x32x16_bf16 v[32:47], v[174:177], v[182:185], v[32:47]
	v_mfma_f32_32x32x16_bf16 v[16:31], v[174:177], v[186:189], v[16:31]
	v_mfma_f32_32x32x16_bf16 v[0:15], v[174:177], v[190:193], v[0:15]
	v_add_co_u32_e32 v174, vcc, s38, v228
	s_nop 1
	v_addc_co_u32_e32 v175, vcc, 0, v229, vcc
	global_load_dwordx4 v[174:177], v[174:175], off offset:128
	ds_read_b128 v[178:181], v130 offset:96
	ds_read_b128 v[182:185], v130 offset:4704
	ds_read_b128 v[186:189], v131 offset:18528
	ds_read_b128 v[190:193], v131 offset:23136
	ds_read_b128 v[216:219], v131 offset:27744
	ds_read_b128 v[220:223], v131 offset:32352
	s_waitcnt lgkmcnt(9)
	v_mfma_f32_32x32x16_bf16 v[112:127], v[154:157], v[162:165], v[112:127]
	s_waitcnt lgkmcnt(8)
	v_mfma_f32_32x32x16_bf16 v[96:111], v[154:157], v[166:169], v[96:111]
	s_waitcnt lgkmcnt(7)
	v_mfma_f32_32x32x16_bf16 v[80:95], v[154:157], v[198:201], v[80:95]
	s_waitcnt lgkmcnt(6)
	v_mfma_f32_32x32x16_bf16 v[64:79], v[154:157], v[202:205], v[64:79]
	v_add_co_u32_e32 v154, vcc, s39, v212
	s_nop 1
	v_addc_co_u32_e32 v155, vcc, 0, v213, vcc
	v_add_co_u32_e32 v224, vcc, s40, v228
	s_nop 1
	v_addc_co_u32_e32 v225, vcc, 0, v229, vcc
	global_load_dwordx4 v[154:157], v[154:155], off offset:384
	s_nop 0
	global_load_dwordx4 v[224:227], v[224:225], off offset:128
	v_mfma_f32_32x32x16_bf16 v[48:63], v[158:161], v[162:165], v[48:63]
	v_mfma_f32_32x32x16_bf16 v[32:47], v[158:161], v[166:169], v[32:47]
	v_mfma_f32_32x32x16_bf16 v[16:31], v[158:161], v[198:201], v[16:31]
	v_mfma_f32_32x32x16_bf16 v[0:15], v[158:161], v[202:205], v[0:15]
	v_add_co_u32_e32 v158, vcc, s41, v228
	s_nop 1
	v_addc_co_u32_e32 v159, vcc, 0, v229, vcc
	global_load_dwordx4 v[158:161], v[158:159], off offset:128
	s_waitcnt lgkmcnt(3)
	v_mfma_f32_32x32x16_bf16 v[112:127], v[178:181], v[186:189], v[112:127]
	s_waitcnt lgkmcnt(2)
	v_mfma_f32_32x32x16_bf16 v[96:111], v[178:181], v[190:193], v[96:111]
	s_waitcnt lgkmcnt(1)
	v_mfma_f32_32x32x16_bf16 v[80:95], v[178:181], v[216:219], v[80:95]
	s_waitcnt lgkmcnt(0)
	v_mfma_f32_32x32x16_bf16 v[64:79], v[178:181], v[220:223], v[64:79]
	v_add_co_u32_e32 v162, vcc, s48, v212
	s_nop 1
	v_addc_co_u32_e32 v163, vcc, 0, v213, vcc
	v_add_co_u32_e32 v166, vcc, s49, v228
	s_nop 1
	v_addc_co_u32_e32 v167, vcc, 0, v229, vcc
	global_load_dwordx4 v[162:165], v[162:163], off offset:384
	s_nop 0
	global_load_dwordx4 v[166:169], v[166:167], off offset:128
	v_mfma_f32_32x32x16_bf16 v[48:63], v[182:185], v[186:189], v[48:63]
	v_mfma_f32_32x32x16_bf16 v[32:47], v[182:185], v[190:193], v[32:47]
	v_mfma_f32_32x32x16_bf16 v[16:31], v[182:185], v[216:219], v[16:31]
	v_mfma_f32_32x32x16_bf16 v[0:15], v[182:185], v[220:223], v[0:15]
	v_add_co_u32_e32 v178, vcc, s50, v228
	s_nop 1
	v_addc_co_u32_e32 v179, vcc, 0, v229, vcc
	global_load_dwordx4 v[178:181], v[178:179], off offset:128
	s_add_u32 s18, s18, 0x80
	s_addc_u32 s19, s19, 0
	s_cmpk_eq_i32 s18, 0xf80
	s_barrier
; template <int EPI>
; __device__ __forceinline__ void gemm_tile(const Params& p, int layer, const u16* __restrict__ A, const u16* __restrict__ Bt, int mt, int nt, char* lds) {
;     ...
;   for (int kt = 0; kt < NK - 1; ++kt) {
;     G_SLAB(true, kt + 1)
;     __syncthreads();
;     G_WRITE();
;     __syncthreads();
;   }
;   G_SLAB(false, 0)
;   __syncthreads();
	s_setprio 0
	s_waitcnt vmcnt(11)
	ds_write_b128 v132, v[146:149]
	s_waitcnt vmcnt(8)
	ds_write_b128 v132, v[170:173] offset:4608
	s_waitcnt vmcnt(5)
	ds_write_b128 v132, v[154:157] offset:9216
	s_waitcnt vmcnt(2)
	ds_write_b128 v132, v[162:165] offset:13824
	ds_write_b128 v132, v[194:197] offset:18432
	ds_write_b128 v132, v[206:209] offset:23040
	ds_write_b128 v132, v[224:227] offset:27648
	s_waitcnt vmcnt(1)
	ds_write_b128 v132, v[166:169] offset:32256
	ds_write_b128 v132, v[150:153] offset:36864
	ds_write_b128 v132, v[174:177] offset:41472
	ds_write_b128 v132, v[158:161] offset:46080
	s_waitcnt vmcnt(0)
	ds_write_b128 v132, v[178:181] offset:50688
	s_waitcnt lgkmcnt(0)
	s_setprio 1
	s_barrier
	s_cbranch_scc0 .LBB0_2499
	ds_read_b128 v[132:135], v130
	ds_read_b128 v[146:149], v130 offset:4608
	ds_read_b128 v[150:153], v131 offset:18432
	ds_read_b128 v[154:157], v131 offset:23040
	ds_read_b128 v[158:161], v131 offset:27648
	ds_read_b128 v[162:165], v131 offset:32256
	ds_read_b128 v[166:169], v130 offset:32
	ds_read_b128 v[170:173], v130 offset:4640
	ds_read_b128 v[174:177], v131 offset:18464
	ds_read_b128 v[178:181], v131 offset:23072
	ds_read_b128 v[182:185], v131 offset:27680
	ds_read_b128 v[186:189], v131 offset:32288
	s_waitcnt lgkmcnt(7)
	v_mfma_f32_32x32x16_bf16 v[80:95], v[132:135], v[158:161], v[80:95]
	s_waitcnt lgkmcnt(6)
	v_mfma_f32_32x32x16_bf16 v[64:79], v[132:135], v[162:165], v[64:79]
	v_mfma_f32_32x32x16_bf16 v[112:127], v[132:135], v[150:153], v[112:127]
	v_mfma_f32_32x32x16_bf16 v[96:111], v[132:135], v[154:157], v[96:111]
	v_mfma_f32_32x32x16_bf16 v[48:63], v[146:149], v[150:153], v[48:63]
	v_mfma_f32_32x32x16_bf16 v[32:47], v[146:149], v[154:157], v[32:47]
	v_mfma_f32_32x32x16_bf16 v[16:31], v[146:149], v[158:161], v[16:31]
	v_mfma_f32_32x32x16_bf16 v[0:15], v[146:149], v[162:165], v[0:15]
	ds_read_b128 v[132:135], v130 offset:64
	ds_read_b128 v[146:149], v130 offset:4672
	ds_read_b128 v[150:153], v131 offset:18496
	ds_read_b128 v[154:157], v131 offset:23104
	ds_read_b128 v[158:161], v131 offset:27712
	ds_read_b128 v[162:165], v131 offset:32320
	s_waitcnt lgkmcnt(7)
	v_mfma_f32_32x32x16_bf16 v[80:95], v[166:169], v[182:185], v[80:95]
	s_waitcnt lgkmcnt(6)
	v_mfma_f32_32x32x16_bf16 v[64:79], v[166:169], v[186:189], v[64:79]
	v_mfma_f32_32x32x16_bf16 v[112:127], v[166:169], v[174:177], v[112:127]
	v_mfma_f32_32x32x16_bf16 v[96:111], v[166:169], v[178:181], v[96:111]
	v_mfma_f32_32x32x16_bf16 v[48:63], v[170:173], v[174:177], v[48:63]
	v_mfma_f32_32x32x16_bf16 v[32:47], v[170:173], v[178:181], v[32:47]
	v_mfma_f32_32x32x16_bf16 v[16:31], v[170:173], v[182:185], v[16:31]
	v_mfma_f32_32x32x16_bf16 v[0:15], v[170:173], v[186:189], v[0:15]
	ds_read_b128 v[166:169], v130 offset:96
	ds_read_b128 v[170:173], v130 offset:4704
	ds_read_b128 v[174:177], v131 offset:18528
	ds_read_b128 v[178:181], v131 offset:23136
	ds_read_b128 v[182:185], v131 offset:27744
	ds_read_b128 v[186:189], v131 offset:32352
	s_waitcnt lgkmcnt(7)
	v_mfma_f32_32x32x16_bf16 v[80:95], v[132:135], v[158:161], v[80:95]
	s_waitcnt lgkmcnt(6)
	v_mfma_f32_32x32x16_bf16 v[64:79], v[132:135], v[162:165], v[64:79]
	v_mfma_f32_32x32x16_bf16 v[112:127], v[132:135], v[150:153], v[112:127]
	v_mfma_f32_32x32x16_bf16 v[96:111], v[132:135], v[154:157], v[96:111]
	v_mfma_f32_32x32x16_bf16 v[48:63], v[146:149], v[150:153], v[48:63]
	v_mfma_f32_32x32x16_bf16 v[32:47], v[146:149], v[154:157], v[32:47]
	v_mfma_f32_32x32x16_bf16 v[16:31], v[146:149], v[158:161], v[16:31]
	v_mfma_f32_32x32x16_bf16 v[0:15], v[146:149], v[162:165], v[0:15]
	s_waitcnt lgkmcnt(1)
	v_mfma_f32_32x32x16_bf16 v[80:95], v[166:169], v[182:185], v[80:95]
	s_waitcnt lgkmcnt(0)
	v_mfma_f32_32x32x16_bf16 v[64:79], v[166:169], v[186:189], v[64:79]
	v_mfma_f32_32x32x16_bf16 v[112:127], v[166:169], v[174:177], v[112:127]
	v_mfma_f32_32x32x16_bf16 v[96:111], v[166:169], v[178:181], v[96:111]
	v_mfma_f32_32x32x16_bf16 v[48:63], v[170:173], v[174:177], v[48:63]
	v_mfma_f32_32x32x16_bf16 v[32:47], v[170:173], v[178:181], v[32:47]
	v_mfma_f32_32x32x16_bf16 v[16:31], v[170:173], v[182:185], v[16:31]
	v_mfma_f32_32x32x16_bf16 v[0:15], v[170:173], v[186:189], v[0:15]
	v_lshl_or_b32 v128, v139, 2, v143
	v_lshlrev_b32_e32 v130, 1, v144
	v_lshlrev_b32_e32 v131, 1, v138
	v_mul_lo_u32 v128, v128, s51
	v_mov_b32_e32 v132, v129
	s_nop 1
	v_cvt_pk_bf16_f32 v112, v112, s0
	v_add3_u32 v128, v130, v131, v128
	s_barrier
; DI u16 f2bf(float a) { return (u16)(pk2(a, 0.f) & 0xffffu); }
; DI int crow(int i, int h) { return (i & 3) + 8 * (i >> 2) + 4 * h; }
; template <int EPI>
; __device__ __forceinline__ void gemm_tile(const Params& p, int layer, const u16* __restrict__ A, const u16* __restrict__ Bt, int mt, int nt, char* lds) {
;     ...
;         u16* Qs = (u16*)lds;
; #pragma unroll
;         for (int e = 0; e < 16; ++e) {
;           const int lr = wr * 64 + i * 32 + crow(e, h);
;           Qs[lr * QLD + wc * 128 + j * 32 + r] = f2bf(acc[i][j][e]);
;         }
	ds_write_b16 v128, v112
	v_cvt_pk_bf16_f32 v112, v113, s0
	ds_write_b16 v128, v112 offset:528
	v_cvt_pk_bf16_f32 v112, v114, s0
	ds_write_b16 v128, v112 offset:1056
	v_cvt_pk_bf16_f32 v112, v115, s0
	ds_write_b16 v128, v112 offset:1584
	v_cvt_pk_bf16_f32 v112, v116, s0
	ds_write_b16 v128, v112 offset:4224
	v_cvt_pk_bf16_f32 v112, v117, s0
	ds_write_b16 v128, v112 offset:4752
	v_cvt_pk_bf16_f32 v112, v118, s0
	ds_write_b16 v128, v112 offset:5280
	v_cvt_pk_bf16_f32 v112, v119, s0
	ds_write_b16 v128, v112 offset:5808
	v_cvt_pk_bf16_f32 v112, v120, s0
	ds_write_b16 v128, v112 offset:8448
	v_cvt_pk_bf16_f32 v112, v121, s0
	ds_write_b16 v128, v112 offset:8976
	v_cvt_pk_bf16_f32 v112, v122, s0
	ds_write_b16 v128, v112 offset:9504
	v_cvt_pk_bf16_f32 v112, v123, s0
	ds_write_b16 v128, v112 offset:10032
	v_cvt_pk_bf16_f32 v112, v124, s0
	ds_write_b16 v128, v112 offset:12672
	v_cvt_pk_bf16_f32 v112, v125, s0
	ds_write_b16 v128, v112 offset:13200
	v_cvt_pk_bf16_f32 v112, v126, s0
	ds_write_b16 v128, v112 offset:13728
	v_cvt_pk_bf16_f32 v112, v127, s0
	ds_write_b16 v128, v112 offset:14256
	v_mov_b32_e32 v112, v129
	v_cvt_pk_bf16_f32 v96, v96, s0
	ds_write_b16 v128, v96 offset:64
	v_cvt_pk_bf16_f32 v96, v97, s0
	ds_write_b16 v128, v96 offset:592
	v_cvt_pk_bf16_f32 v96, v98, s0
	ds_write_b16 v128, v96 offset:1120
	v_cvt_pk_bf16_f32 v96, v99, s0
	ds_write_b16 v128, v96 offset:1648
	v_cvt_pk_bf16_f32 v96, v100, s0
	ds_write_b16 v128, v96 offset:4288
	v_cvt_pk_bf16_f32 v96, v101, s0
	ds_write_b16 v128, v96 offset:4816
	v_cvt_pk_bf16_f32 v96, v102, s0
	ds_write_b16 v128, v96 offset:5344
	v_cvt_pk_bf16_f32 v96, v103, s0
	ds_write_b16 v128, v96 offset:5872
	v_cvt_pk_bf16_f32 v96, v104, s0
	ds_write_b16 v128, v96 offset:8512
	v_cvt_pk_bf16_f32 v96, v105, s0
	ds_write_b16 v128, v96 offset:9040
	v_cvt_pk_bf16_f32 v96, v106, s0
	ds_write_b16 v128, v96 offset:9568
	v_cvt_pk_bf16_f32 v96, v107, s0
	ds_write_b16 v128, v96 offset:10096
	v_cvt_pk_bf16_f32 v96, v108, s0
	ds_write_b16 v128, v96 offset:12736
	v_cvt_pk_bf16_f32 v96, v109, s0
	ds_write_b16 v128, v96 offset:13264
	v_cvt_pk_bf16_f32 v96, v110, s0
	ds_write_b16 v128, v96 offset:13792
	v_cvt_pk_bf16_f32 v96, v111, s0
	ds_write_b16 v128, v96 offset:14320
	v_mov_b32_e32 v96, v129
	v_cvt_pk_bf16_f32 v80, v80, s0
	ds_write_b16 v128, v80 offset:128
	v_cvt_pk_bf16_f32 v80, v81, s0
	ds_write_b16 v128, v80 offset:656
	v_cvt_pk_bf16_f32 v80, v82, s0
	ds_write_b16 v128, v80 offset:1184
	v_cvt_pk_bf16_f32 v80, v83, s0
	ds_write_b16 v128, v80 offset:1712
	v_cvt_pk_bf16_f32 v80, v84, s0
	ds_write_b16 v128, v80 offset:4352
	v_cvt_pk_bf16_f32 v80, v85, s0
	ds_write_b16 v128, v80 offset:4880
	v_cvt_pk_bf16_f32 v80, v86, s0
	ds_write_b16 v128, v80 offset:5408
	v_cvt_pk_bf16_f32 v80, v87, s0
	ds_write_b16 v128, v80 offset:5936
	v_cvt_pk_bf16_f32 v80, v88, s0
	ds_write_b16 v128, v80 offset:8576
	v_cvt_pk_bf16_f32 v80, v89, s0
	ds_write_b16 v128, v80 offset:9104
	v_cvt_pk_bf16_f32 v80, v90, s0
	ds_write_b16 v128, v80 offset:9632
	v_cvt_pk_bf16_f32 v80, v91, s0
	ds_write_b16 v128, v80 offset:10160
	v_cvt_pk_bf16_f32 v80, v92, s0
	ds_write_b16 v128, v80 offset:12800
	v_cvt_pk_bf16_f32 v80, v93, s0
	ds_write_b16 v128, v80 offset:13328
	v_cvt_pk_bf16_f32 v80, v94, s0
	ds_write_b16 v128, v80 offset:13856
	v_cvt_pk_bf16_f32 v80, v95, s0
	ds_write_b16 v128, v80 offset:14384
	v_mov_b32_e32 v80, v129
	v_cvt_pk_bf16_f32 v64, v64, s0
	ds_write_b16 v128, v64 offset:192
	v_cvt_pk_bf16_f32 v64, v65, s0
	ds_write_b16 v128, v64 offset:720
	v_cvt_pk_bf16_f32 v64, v66, s0
	ds_write_b16 v128, v64 offset:1248
	v_cvt_pk_bf16_f32 v64, v67, s0
	ds_write_b16 v128, v64 offset:1776
	v_cvt_pk_bf16_f32 v64, v68, s0
	ds_write_b16 v128, v64 offset:4416
	v_cvt_pk_bf16_f32 v64, v69, s0
	ds_write_b16 v128, v64 offset:4944
	v_cvt_pk_bf16_f32 v64, v70, s0
	ds_write_b16 v128, v64 offset:5472
	v_cvt_pk_bf16_f32 v64, v71, s0
	ds_write_b16 v128, v64 offset:6000
	v_cvt_pk_bf16_f32 v64, v72, s0
	ds_write_b16 v128, v64 offset:8640
	v_cvt_pk_bf16_f32 v64, v73, s0
	ds_write_b16 v128, v64 offset:9168
	v_cvt_pk_bf16_f32 v64, v74, s0
	ds_write_b16 v128, v64 offset:9696
	v_cvt_pk_bf16_f32 v64, v75, s0
	ds_write_b16 v128, v64 offset:10224
	v_cvt_pk_bf16_f32 v64, v76, s0
	ds_write_b16 v128, v64 offset:12864
	v_cvt_pk_bf16_f32 v64, v77, s0
	ds_write_b16 v128, v64 offset:13392
	v_cvt_pk_bf16_f32 v64, v78, s0
	ds_write_b16 v128, v64 offset:13920
	v_cvt_pk_bf16_f32 v64, v79, s0
	ds_write_b16 v128, v64 offset:14448
	v_mov_b32_e32 v64, v129
	v_cvt_pk_bf16_f32 v48, v48, s0
	ds_write_b16 v128, v48 offset:16896
	v_cvt_pk_bf16_f32 v48, v49, s0
	ds_write_b16 v128, v48 offset:17424
	v_cvt_pk_bf16_f32 v48, v50, s0
	ds_write_b16 v128, v48 offset:17952
	v_cvt_pk_bf16_f32 v48, v51, s0
	ds_write_b16 v128, v48 offset:18480
	v_cvt_pk_bf16_f32 v48, v52, s0
	ds_write_b16 v128, v48 offset:21120
	v_cvt_pk_bf16_f32 v48, v53, s0
	ds_write_b16 v128, v48 offset:21648
	v_cvt_pk_bf16_f32 v48, v54, s0
	ds_write_b16 v128, v48 offset:22176
	v_cvt_pk_bf16_f32 v48, v55, s0
	ds_write_b16 v128, v48 offset:22704
; DI u16 f2bf(float a) { return (u16)(pk2(a, 0.f) & 0xffffu); }
; DI int crow(int i, int h) { return (i & 3) + 8 * (i >> 2) + 4 * h; }
; template <int EPI>
; __device__ __forceinline__ void gemm_tile(const Params& p, int layer, const u16* __restrict__ A, const u16* __restrict__ Bt, int mt, int nt, char* lds) {
;     ...
;         u16* Qs = (u16*)lds;
; #pragma unroll
;         for (int e = 0; e < 16; ++e) {
;           const int lr = wr * 64 + i * 32 + crow(e, h);
;           Qs[lr * QLD + wc * 128 + j * 32 + r] = f2bf(acc[i][j][e]);
;         }
;       }
;     }
;   }
;   if (EPI == 2) {
;     __syncthreads();
;     const u16* Qs = (const u16*)lds;
;     route_task(p, layer, Qs + (wid * 32 + r) * QLD + 8 * h, m0 + wid * 32, nt, r, h);
; __device__ __forceinline__ void route_task(const Params& p, int layer, const u16* qg, int rb, int hd, int r, int h) {
;   const u16* KY = (const u16*)(p.ws + OFF_KEYS);
;   int* EX = (int*)(p.ws + OFF_EXP);
;   float* GT = (float*)(p.ws + OFF_GATE);
;     unsigned top[2][16];
; #pragma unroll
;   for (int ph = 0; ph < 2; ++ph) {
;     bf16x8 qf[8];
; #pragma unroll
;     for (int s = 0; s < 8; ++s) qf[s] = *(const bf16x8*)(qg + ph * 128 + 16 * s);
;     const u16* kg = KY + ((size_t)((layer * 8 + hd) * 2 + ph) * 128 + r) * 128 + 8 * h;
;     unsigned tp[16];
; #pragma unroll
;     for (int jj = 0; jj < 16; ++jj) tp[jj] = 0u;
; #pragma unroll 1
;     for (int n = 0; n < 4; ++n) {
;       f32x16 acc;
; #pragma unroll
;       for (int e = 0; e < 16; ++e) acc[e] = 0.f;
	v_cvt_pk_bf16_f32 v48, v56, s0
	ds_write_b16 v128, v48 offset:25344
	v_cvt_pk_bf16_f32 v48, v57, s0
	ds_write_b16 v128, v48 offset:25872
	v_cvt_pk_bf16_f32 v48, v58, s0
	ds_write_b16 v128, v48 offset:26400
	v_cvt_pk_bf16_f32 v48, v59, s0
	ds_write_b16 v128, v48 offset:26928
	v_cvt_pk_bf16_f32 v48, v60, s0
	ds_write_b16 v128, v48 offset:29568
	v_cvt_pk_bf16_f32 v48, v61, s0
	ds_write_b16 v128, v48 offset:30096
	v_cvt_pk_bf16_f32 v48, v62, s0
	ds_write_b16 v128, v48 offset:30624
	v_cvt_pk_bf16_f32 v48, v63, s0
	ds_write_b16 v128, v48 offset:31152
	v_mov_b32_e32 v48, v129
	v_cvt_pk_bf16_f32 v32, v32, s0
	ds_write_b16 v128, v32 offset:16960
	v_cvt_pk_bf16_f32 v32, v33, s0
	ds_write_b16 v128, v32 offset:17488
	v_cvt_pk_bf16_f32 v32, v34, s0
	ds_write_b16 v128, v32 offset:18016
	v_cvt_pk_bf16_f32 v32, v35, s0
	ds_write_b16 v128, v32 offset:18544
	v_cvt_pk_bf16_f32 v32, v36, s0
	ds_write_b16 v128, v32 offset:21184
	v_cvt_pk_bf16_f32 v32, v37, s0
	ds_write_b16 v128, v32 offset:21712
	v_cvt_pk_bf16_f32 v32, v38, s0
	ds_write_b16 v128, v32 offset:22240
	v_cvt_pk_bf16_f32 v32, v39, s0
	ds_write_b16 v128, v32 offset:22768
	v_cvt_pk_bf16_f32 v32, v40, s0
	ds_write_b16 v128, v32 offset:25408
	v_cvt_pk_bf16_f32 v32, v41, s0
	ds_write_b16 v128, v32 offset:25936
	v_cvt_pk_bf16_f32 v32, v42, s0
	ds_write_b16 v128, v32 offset:26464
	v_cvt_pk_bf16_f32 v32, v43, s0
	ds_write_b16 v128, v32 offset:26992
	v_cvt_pk_bf16_f32 v32, v44, s0
	ds_write_b16 v128, v32 offset:29632
	v_cvt_pk_bf16_f32 v32, v45, s0
	ds_write_b16 v128, v32 offset:30160
	v_cvt_pk_bf16_f32 v32, v46, s0
	ds_write_b16 v128, v32 offset:30688
	v_cvt_pk_bf16_f32 v32, v47, s0
	ds_write_b16 v128, v32 offset:31216
	v_mov_b32_e32 v32, v129
	v_cvt_pk_bf16_f32 v16, v16, s0
	ds_write_b16 v128, v16 offset:17024
	v_cvt_pk_bf16_f32 v16, v17, s0
	ds_write_b16 v128, v16 offset:17552
	v_cvt_pk_bf16_f32 v16, v18, s0
	ds_write_b16 v128, v16 offset:18080
	v_cvt_pk_bf16_f32 v16, v19, s0
	ds_write_b16 v128, v16 offset:18608
	v_cvt_pk_bf16_f32 v16, v20, s0
	ds_write_b16 v128, v16 offset:21248
	v_cvt_pk_bf16_f32 v16, v21, s0
	ds_write_b16 v128, v16 offset:21776
	v_cvt_pk_bf16_f32 v16, v22, s0
	ds_write_b16 v128, v16 offset:22304
	v_cvt_pk_bf16_f32 v16, v23, s0
	ds_write_b16 v128, v16 offset:22832
	v_cvt_pk_bf16_f32 v16, v24, s0
	ds_write_b16 v128, v16 offset:25472
	v_cvt_pk_bf16_f32 v16, v25, s0
	ds_write_b16 v128, v16 offset:26000
	v_cvt_pk_bf16_f32 v16, v26, s0
	ds_write_b16 v128, v16 offset:26528
	v_cvt_pk_bf16_f32 v16, v27, s0
	ds_write_b16 v128, v16 offset:27056
	v_cvt_pk_bf16_f32 v16, v28, s0
	ds_write_b16 v128, v16 offset:29696
	v_cvt_pk_bf16_f32 v16, v29, s0
	ds_write_b16 v128, v16 offset:30224
	v_cvt_pk_bf16_f32 v16, v30, s0
	ds_write_b16 v128, v16 offset:30752
	v_cvt_pk_bf16_f32 v16, v31, s0
	ds_write_b16 v128, v16 offset:31280
	v_mov_b32_e32 v16, v129
	v_cvt_pk_bf16_f32 v0, v0, s0
	ds_write_b16 v128, v0 offset:17088
	v_cvt_pk_bf16_f32 v0, v1, s0
	ds_write_b16 v128, v0 offset:17616
	v_cvt_pk_bf16_f32 v0, v2, s0
	ds_write_b16 v128, v0 offset:18144
	v_cvt_pk_bf16_f32 v0, v3, s0
	ds_write_b16 v128, v0 offset:18672
	v_cvt_pk_bf16_f32 v0, v4, s0
	ds_write_b16 v128, v0 offset:21312
	v_cvt_pk_bf16_f32 v0, v5, s0
	ds_write_b16 v128, v0 offset:21840
	v_cvt_pk_bf16_f32 v0, v6, s0
	ds_write_b16 v128, v0 offset:22368
	v_cvt_pk_bf16_f32 v0, v7, s0
	ds_write_b16 v128, v0 offset:22896
	v_cvt_pk_bf16_f32 v0, v8, s0
	ds_write_b16 v128, v0 offset:25536
	v_cvt_pk_bf16_f32 v0, v9, s0
	ds_write_b16 v128, v0 offset:26064
	v_cvt_pk_bf16_f32 v0, v10, s0
	ds_write_b16 v128, v0 offset:26592
	v_cvt_pk_bf16_f32 v0, v11, s0
	ds_write_b16 v128, v0 offset:27120
	v_cvt_pk_bf16_f32 v0, v12, s0
	ds_write_b16 v128, v0 offset:29760
	v_cvt_pk_bf16_f32 v0, v13, s0
	ds_write_b16 v128, v0 offset:30288
	v_cvt_pk_bf16_f32 v0, v14, s0
	ds_write_b16 v128, v0 offset:30816
	v_cvt_pk_bf16_f32 v0, v15, s0
	v_lshlrev_b32_e32 v52, 5, v141
	ds_write_b16 v128, v0 offset:31344
	v_or_b32_e32 v0, v52, v138
	v_mul_lo_u32 v0, v0, s51
	v_lshl_add_u32 v83, v142, 1, v0
	s_waitcnt lgkmcnt(0)
	s_barrier
	ds_read_b128 v[16:19], v83
	ds_read_b128 v[20:23], v83 offset:32
	ds_read_b128 v[24:27], v83 offset:64
	ds_read_b128 v[28:31], v83 offset:96
	ds_read_b128 v[32:35], v83 offset:128
	ds_read_b128 v[36:39], v83 offset:160
	ds_read_b128 v[40:43], v83 offset:192
	ds_read_b128 v[44:47], v83 offset:224
	s_lshl_b32 s14, s72, 1
	s_add_i32 s14, s14, 16
	v_lshrrev_b32_e32 v1, 1, v140
	s_lshl_b64 s[46:47], s[14:15], 15
	v_lshlrev_b32_e32 v0, 8, v138
	v_and_b32_e32 v1, 16, v1
	v_or3_b32 v48, s46, v0, v1
	v_mov_b32_e32 v49, s47
	s_mov_b32 s18, 0
	v_mul_i32_i24_e32 v53, -4, v139
	v_lshl_add_u64 v[50:51], s[10:11], 0, v[48:49]
	v_mov_b32_e32 v69, 0
	v_mov_b32_e32 v68, 0
	v_mov_b32_e32 v67, 0
	v_mov_b32_e32 v66, 0
	v_mov_b32_e32 v65, 0
	v_mov_b32_e32 v64, 0
	v_mov_b32_e32 v63, 0
	v_mov_b32_e32 v62, 0
	v_mov_b32_e32 v61, 0
	v_mov_b32_e32 v60, 0
	v_mov_b32_e32 v59, 0
	v_mov_b32_e32 v58, 0
	v_mov_b32_e32 v57, 0
	v_mov_b32_e32 v56, 0
	v_mov_b32_e32 v55, 0
	v_mov_b32_e32 v54, 0
